# s_setprio 1 issued before the barrier that opens each GEMM compute segment (one fewer slot between release and first MFMA)
# baseline (speedup 1.0000x reference)
; #define PG8_STAGE(bufoff, gbase, voff) do { _Pragma("unroll") for (int _i = 0; _i < 2; ++_i) \
;     __builtin_amdgcn_global_load_lds((const unsigned*)((const char*)(gbase) + (voff)[_i]), (PG8_LAS unsigned*)(lds + (bufoff) + ldsw + _i * 8192), 16, 0, 0); } while (0)
; #define PG8_LDA(dst, b, h) do { _Pragma("unroll") for (int m = 0; m < 4; ++m) _Pragma("unroll") for (int k = 0; k < 2; ++k) dst[m][k] = *(const PG8_LAS bf16x8*)(lds + PG8_SA(b, h) + aoff + m * 2048 + k * 1024); } while (0)
; #define PG8_LDB(dst, b, h) do { _Pragma("unroll") for (int n = 0; n < 2; ++n) _Pragma("unroll") for (int k = 0; k < 2; ++k) dst[n][k] = *(const PG8_LAS bf16x8*)(lds + PG8_SB(b, h) + boff + n * 2048 + k * 1024); } while (0)
; #define PG8_MMA(ai, bj, At, Bt) do { __builtin_amdgcn_s_setprio(1); _Pragma("unroll") for (int m = 0; m < 4; ++m) _Pragma("unroll") for (int n = 0; n < 2; ++n) _Pragma("unroll") for (int k = 0; k < 2; ++k) \
;     acc[ai][bj][m][n] = __builtin_amdgcn_mfma_f32_16x16x32_bf16(Bt[n][k], At[m][k], acc[ai][bj][m][n], 0, 0, 0); __builtin_amdgcn_s_setprio(0); } while (0)
; #define PG8_WAIT_L(n) asm volatile("s_waitcnt lgkmcnt(" #n ")" ::: "memory")
; #define PG8_BAR __builtin_amdgcn_s_barrier()
; #define PG8_SCHED __builtin_amdgcn_sched_barrier(0)
; template <class Epi, class Sched>
; __device__ __forceinline__ void gemm_phase(PG8_LAS unsigned char* lds, const int lda, const int ldb, const Sched& S, const Epi& E) {
;     ...
;     for (int t = 0; t < nt; t += 2) {
;       const bool last = (t == nt - 2);
;       const char* a1 = cA + (size_t)(t + 1) * kstep;
;       const char* a2 = last ? nA : cA + (size_t)(t + 2) * kstep; const char* b2 = last ? nB : cB + (size_t)(t + 2) * kstep;
;       const char* a3 = a2 + kstep; const char* b3 = b2 + kstep;
;       PG8_LDB(B0, 0, 0); PG8_SCHED; PG8_LDA(At, 0, 0); PG8_STAGE(PG8_SA(1, 1), a1 + hstepA, voffA);
;       PG8_WAIT_L(8); PG8_BAR; PG8_WAIT_L(0); PG8_MMA(0, 0, At, B0); PG8_BAR; PG8_SCHED;
;       PG8_LDB(B1, 0, 1); PG8_STAGE(PG8_SB(0, 0), b2, voffB);
;       PG8_BAR; PG8_WAIT_L(0); PG8_MMA(0, 1, At, B1); PG8_BAR;
;       PG8_LDA(At, 0, 1); PG8_STAGE(PG8_SA(0, 0), a2, voffA);
;       PG8_BAR; PG8_WAIT_L(0); PG8_MMA(1, 0, At, B0); PG8_BAR; PG8_SCHED;
.LBB0_335:
	s_add_u32 s10, s8, 0xfffc0080
	s_addc_u32 s11, s9, -1
	s_add_i32 s31, 0, 0x10000
	v_add_u32_e32 v156, s31, v131
	ds_read_b128 v[144:147], v156
	ds_read_b128 v[148:151], v156 offset:1024
	ds_read_b128 v[152:155], v156 offset:2048
	ds_read_b128 v[200:203], v156 offset:3072
	s_cmp_eq_u32 s30, 12
	s_cselect_b32 s25, s17, s11
	s_cselect_b32 s24, s26, s10
	s_cselect_b32 s11, s15, s29
	s_cselect_b32 s10, s27, s28
	v_lshl_add_u64 v[156:157], s[8:9], 0, v[140:141]
	s_add_i32 m0, s40, 0xc000
	ds_read_b128 v[204:207], v172
	ds_read_b128 v[208:211], v172 offset:1024
	ds_read_b128 v[212:215], v172 offset:2048
	ds_read_b128 v[216:219], v172 offset:3072
	ds_read_b128 v[220:223], v172 offset:4096
	ds_read_b128 v[224:227], v172 offset:5120
	ds_read_b128 v[228:231], v172 offset:6144
	ds_read_b128 v[232:235], v172 offset:7168
	global_load_lds_dwordx4 v[156:157], off
	v_lshl_add_u64 v[156:157], s[8:9], 0, v[142:143]
	s_add_i32 m0, s40, 0xe000
	s_nop 0
	global_load_lds_dwordx4 v[156:157], off
	s_waitcnt lgkmcnt(8)
	s_setprio 1
	s_barrier
	s_waitcnt lgkmcnt(0)
	v_mfma_f32_16x16x32_bf16 v[126:129], v[144:147], v[204:207], v[126:129]
	v_mfma_f32_16x16x32_bf16 v[122:125], v[152:155], v[204:207], v[122:125]
	v_mfma_f32_16x16x32_bf16 v[110:113], v[144:147], v[212:215], v[110:113]
	v_mfma_f32_16x16x32_bf16 v[106:109], v[152:155], v[212:215], v[106:109]
	v_mfma_f32_16x16x32_bf16 v[94:97], v[144:147], v[220:223], v[94:97]
	v_mfma_f32_16x16x32_bf16 v[90:93], v[152:155], v[220:223], v[90:93]
	v_mfma_f32_16x16x32_bf16 v[78:81], v[144:147], v[228:231], v[78:81]
	v_mfma_f32_16x16x32_bf16 v[74:77], v[152:155], v[228:231], v[74:77]
	v_mfma_f32_16x16x32_bf16 v[126:129], v[148:151], v[208:211], v[126:129]
	v_mfma_f32_16x16x32_bf16 v[122:125], v[200:203], v[208:211], v[122:125]
	v_mfma_f32_16x16x32_bf16 v[110:113], v[148:151], v[216:219], v[110:113]
	v_mfma_f32_16x16x32_bf16 v[106:109], v[200:203], v[216:219], v[106:109]
	v_mfma_f32_16x16x32_bf16 v[94:97], v[148:151], v[224:227], v[94:97]
	v_mfma_f32_16x16x32_bf16 v[90:93], v[200:203], v[224:227], v[90:93]
	v_mfma_f32_16x16x32_bf16 v[78:81], v[148:151], v[232:235], v[78:81]
	v_mfma_f32_16x16x32_bf16 v[74:77], v[200:203], v[232:235], v[74:77]
	s_setprio 0
	s_barrier
	s_add_i32 s33, 0, 0x14000
	v_add_u32_e32 v156, s33, v131
	s_add_i32 s31, s31, s39
	ds_read_b128 v[236:239], v156
	ds_read_b128 v[240:243], v156 offset:1024
	ds_read_b128 v[244:247], v156 offset:2048
	ds_read_b128 v[248:251], v156 offset:3072
	v_lshl_add_u64 v[156:157], s[10:11], 0, v[134:135]
	s_mov_b32 m0, s31
	v_lshl_add_u64 v[174:175], s[10:11], 0, v[132:133]
	global_load_lds_dwordx4 v[156:157], off
	s_add_i32 m0, s31, 0x2000
	s_nop 0
	global_load_lds_dwordx4 v[174:175], off
	s_setprio 1
	s_barrier
	s_waitcnt lgkmcnt(0)
	v_mfma_f32_16x16x32_bf16 v[118:121], v[236:239], v[204:207], v[118:121]
	v_mfma_f32_16x16x32_bf16 v[114:117], v[244:247], v[204:207], v[114:117]
	v_mfma_f32_16x16x32_bf16 v[102:105], v[236:239], v[212:215], v[102:105]
	v_mfma_f32_16x16x32_bf16 v[98:101], v[244:247], v[212:215], v[98:101]
	v_mfma_f32_16x16x32_bf16 v[86:89], v[236:239], v[220:223], v[86:89]
	v_mfma_f32_16x16x32_bf16 v[82:85], v[244:247], v[220:223], v[82:85]
	v_mfma_f32_16x16x32_bf16 v[70:73], v[236:239], v[228:231], v[70:73]
	v_mfma_f32_16x16x32_bf16 v[66:69], v[244:247], v[228:231], v[66:69]
	v_mfma_f32_16x16x32_bf16 v[118:121], v[240:243], v[208:211], v[118:121]
	v_mfma_f32_16x16x32_bf16 v[114:117], v[248:251], v[208:211], v[114:117]
	v_mfma_f32_16x16x32_bf16 v[102:105], v[240:243], v[216:219], v[102:105]
	v_mfma_f32_16x16x32_bf16 v[98:101], v[248:251], v[216:219], v[98:101]
	v_mfma_f32_16x16x32_bf16 v[86:89], v[240:243], v[224:227], v[86:89]
	v_mfma_f32_16x16x32_bf16 v[82:85], v[248:251], v[224:227], v[82:85]
	v_mfma_f32_16x16x32_bf16 v[70:73], v[240:243], v[232:235], v[70:73]
	v_mfma_f32_16x16x32_bf16 v[66:69], v[248:251], v[232:235], v[66:69]
	s_setprio 0
	s_mov_b32 m0, s40
	v_lshl_add_u64 v[182:183], s[24:25], 0, v[134:135]
	s_barrier
	ds_read_b128 v[204:207], v172 offset:16384
	ds_read_b128 v[208:211], v172 offset:17408
	ds_read_b128 v[212:215], v172 offset:18432
	ds_read_b128 v[216:219], v172 offset:19456
	ds_read_b128 v[220:223], v172 offset:20480
	ds_read_b128 v[224:227], v172 offset:21504
	ds_read_b128 v[228:231], v172 offset:22528
	ds_read_b128 v[232:235], v172 offset:23552
	global_load_lds_dwordx4 v[182:183], off
	v_lshl_add_u64 v[184:185], s[24:25], 0, v[132:133]
	s_mov_b32 m0, s41
	s_nop 0
	global_load_lds_dwordx4 v[184:185], off
	s_setprio 1
	s_barrier
	s_waitcnt lgkmcnt(0)
	v_mfma_f32_16x16x32_bf16 v[62:65], v[144:147], v[204:207], v[62:65]
	v_mfma_f32_16x16x32_bf16 v[58:61], v[152:155], v[204:207], v[58:61]
	v_mfma_f32_16x16x32_bf16 v[46:49], v[144:147], v[212:215], v[46:49]
	v_mfma_f32_16x16x32_bf16 v[42:45], v[152:155], v[212:215], v[42:45]
	v_mfma_f32_16x16x32_bf16 v[30:33], v[144:147], v[220:223], v[30:33]
	v_mfma_f32_16x16x32_bf16 v[26:29], v[152:155], v[220:223], v[26:29]
	v_mfma_f32_16x16x32_bf16 v[14:17], v[144:147], v[228:231], v[14:17]
	v_mfma_f32_16x16x32_bf16 v[10:13], v[152:155], v[228:231], v[10:13]
	v_mfma_f32_16x16x32_bf16 v[62:65], v[148:151], v[208:211], v[62:65]
	v_mfma_f32_16x16x32_bf16 v[58:61], v[200:203], v[208:211], v[58:61]
	v_mfma_f32_16x16x32_bf16 v[46:49], v[148:151], v[216:219], v[46:49]
	v_mfma_f32_16x16x32_bf16 v[42:45], v[200:203], v[216:219], v[42:45]
	v_mfma_f32_16x16x32_bf16 v[30:33], v[148:151], v[224:227], v[30:33]
	v_mfma_f32_16x16x32_bf16 v[26:29], v[200:203], v[224:227], v[26:29]
	v_mfma_f32_16x16x32_bf16 v[14:17], v[148:151], v[232:235], v[14:17]
	v_mfma_f32_16x16x32_bf16 v[10:13], v[200:203], v[232:235], v[10:13]
	s_setprio 0
	s_barrier
; #define PG8_STAGE(bufoff, gbase, voff) do { _Pragma("unroll") for (int _i = 0; _i < 2; ++_i) \
;     __builtin_amdgcn_global_load_lds((const unsigned*)((const char*)(gbase) + (voff)[_i]), (PG8_LAS unsigned*)(lds + (bufoff) + ldsw + _i * 8192), 16, 0, 0); } while (0)
; #define PG8_LDA(dst, b, h) do { _Pragma("unroll") for (int m = 0; m < 4; ++m) _Pragma("unroll") for (int k = 0; k < 2; ++k) dst[m][k] = *(const PG8_LAS bf16x8*)(lds + PG8_SA(b, h) + aoff + m * 2048 + k * 1024); } while (0)
; #define PG8_LDB(dst, b, h) do { _Pragma("unroll") for (int n = 0; n < 2; ++n) _Pragma("unroll") for (int k = 0; k < 2; ++k) dst[n][k] = *(const PG8_LAS bf16x8*)(lds + PG8_SB(b, h) + boff + n * 2048 + k * 1024); } while (0)
; #define PG8_MMA(ai, bj, At, Bt) do { __builtin_amdgcn_s_setprio(1); _Pragma("unroll") for (int m = 0; m < 4; ++m) _Pragma("unroll") for (int n = 0; n < 2; ++n) _Pragma("unroll") for (int k = 0; k < 2; ++k) \
;     acc[ai][bj][m][n] = __builtin_amdgcn_mfma_f32_16x16x32_bf16(Bt[n][k], At[m][k], acc[ai][bj][m][n], 0, 0, 0); __builtin_amdgcn_s_setprio(0); } while (0)
; #define PG8_WAIT_V(n) asm volatile("s_waitcnt vmcnt(" #n ")" ::: "memory")
; #define PG8_WAIT_L(n) asm volatile("s_waitcnt lgkmcnt(" #n ")" ::: "memory")
; #define PG8_BAR __builtin_amdgcn_s_barrier()
; #define PG8_SCHED __builtin_amdgcn_sched_barrier(0)
; template <class Epi, class Sched>
; __device__ __forceinline__ void gemm_phase(PG8_LAS unsigned char* lds, const int lda, const int ldb, const Sched& S, const Epi& E) {
;     ...
;       PG8_STAGE(PG8_SB(0, 1), b2 + hstepB, voffB);
;       PG8_WAIT_V(6); PG8_BAR; PG8_MMA(1, 1, At, B1); PG8_BAR;
;       PG8_LDB(B0, 1, 0); PG8_SCHED; PG8_LDA(At, 1, 0); PG8_STAGE(PG8_SA(0, 1), a2 + hstepA, voffA);
;       PG8_WAIT_L(8); PG8_BAR; PG8_WAIT_L(0); PG8_MMA(0, 0, At, B0); PG8_BAR; PG8_SCHED;
;       PG8_LDB(B1, 1, 1); PG8_STAGE(PG8_SB(1, 0), b3, voffB);
;       PG8_BAR; PG8_WAIT_L(0); PG8_MMA(0, 1, At, B1); PG8_BAR;
;       PG8_LDA(At, 1, 1); PG8_STAGE(PG8_SA(1, 0), a3, voffA);
;       PG8_BAR; PG8_WAIT_L(0); PG8_MMA(1, 0, At, B0); PG8_BAR; PG8_SCHED;
	s_add_u32 s34, s10, 0x40000
	s_addc_u32 s35, s11, 0
	s_add_i32 s31, s33, s39
	v_lshl_add_u64 v[144:145], s[34:35], 0, v[134:135]
	s_mov_b32 m0, s31
	s_nop 0
	global_load_lds_dwordx4 v[144:145], off
	v_lshl_add_u64 v[144:145], s[34:35], 0, v[132:133]
	s_add_i32 m0, s31, 0x2000
	s_nop 0
	global_load_lds_dwordx4 v[144:145], off
	s_waitcnt vmcnt(6)
	s_setprio 1
	s_barrier
	v_mfma_f32_16x16x32_bf16 v[54:57], v[236:239], v[204:207], v[54:57]
	v_mfma_f32_16x16x32_bf16 v[50:53], v[244:247], v[204:207], v[50:53]
	v_mfma_f32_16x16x32_bf16 v[38:41], v[236:239], v[212:215], v[38:41]
	v_mfma_f32_16x16x32_bf16 v[34:37], v[244:247], v[212:215], v[34:37]
	v_mfma_f32_16x16x32_bf16 v[22:25], v[236:239], v[220:223], v[22:25]
	v_mfma_f32_16x16x32_bf16 v[18:21], v[244:247], v[220:223], v[18:21]
	v_mfma_f32_16x16x32_bf16 v[6:9], v[236:239], v[228:231], v[6:9]
	v_mfma_f32_16x16x32_bf16 v[2:5], v[244:247], v[228:231], v[2:5]
	v_mfma_f32_16x16x32_bf16 v[54:57], v[240:243], v[208:211], v[54:57]
	v_mfma_f32_16x16x32_bf16 v[50:53], v[248:251], v[208:211], v[50:53]
	v_mfma_f32_16x16x32_bf16 v[38:41], v[240:243], v[216:219], v[38:41]
	v_mfma_f32_16x16x32_bf16 v[34:37], v[248:251], v[216:219], v[34:37]
	v_mfma_f32_16x16x32_bf16 v[22:25], v[240:243], v[224:227], v[22:25]
	v_mfma_f32_16x16x32_bf16 v[18:21], v[248:251], v[224:227], v[18:21]
	v_mfma_f32_16x16x32_bf16 v[6:9], v[240:243], v[232:235], v[6:9]
	v_mfma_f32_16x16x32_bf16 v[2:5], v[248:251], v[232:235], v[2:5]
	s_setprio 0
	s_add_i32 s31, 0, 0x18000
	v_add_u32_e32 v173, s31, v131
	s_barrier
	ds_read_b128 v[144:147], v173
	ds_read_b128 v[148:151], v173 offset:1024
	ds_read_b128 v[152:155], v173 offset:2048
	ds_read_b128 v[200:203], v173 offset:3072
	s_add_u32 s24, s24, 0x40000
	s_addc_u32 s25, s25, 0
	s_mov_b32 m0, s42
	v_lshl_add_u64 v[236:237], s[24:25], 0, v[134:135]
	ds_read_b128 v[204:207], v172 offset:32768
	ds_read_b128 v[208:211], v172 offset:33792
	ds_read_b128 v[212:215], v172 offset:34816
	ds_read_b128 v[216:219], v172 offset:35840
	ds_read_b128 v[220:223], v172 offset:36864
	ds_read_b128 v[224:227], v172 offset:37888
	ds_read_b128 v[228:231], v172 offset:38912
	ds_read_b128 v[232:235], v172 offset:39936
	global_load_lds_dwordx4 v[236:237], off
	v_lshl_add_u64 v[236:237], s[24:25], 0, v[132:133]
	s_mov_b32 m0, s43
	s_nop 0
	global_load_lds_dwordx4 v[236:237], off
	s_waitcnt lgkmcnt(8)
	s_setprio 1
	s_barrier
	s_waitcnt lgkmcnt(0)
	v_mfma_f32_16x16x32_bf16 v[126:129], v[144:147], v[204:207], v[126:129]
	v_mfma_f32_16x16x32_bf16 v[122:125], v[152:155], v[204:207], v[122:125]
	v_mfma_f32_16x16x32_bf16 v[110:113], v[144:147], v[212:215], v[110:113]
	v_mfma_f32_16x16x32_bf16 v[106:109], v[152:155], v[212:215], v[106:109]
	v_mfma_f32_16x16x32_bf16 v[94:97], v[144:147], v[220:223], v[94:97]
	v_mfma_f32_16x16x32_bf16 v[90:93], v[152:155], v[220:223], v[90:93]
	v_mfma_f32_16x16x32_bf16 v[78:81], v[144:147], v[228:231], v[78:81]
	v_mfma_f32_16x16x32_bf16 v[74:77], v[152:155], v[228:231], v[74:77]
	v_mfma_f32_16x16x32_bf16 v[126:129], v[148:151], v[208:211], v[126:129]
	v_mfma_f32_16x16x32_bf16 v[122:125], v[200:203], v[208:211], v[122:125]
	v_mfma_f32_16x16x32_bf16 v[110:113], v[148:151], v[216:219], v[110:113]
	v_mfma_f32_16x16x32_bf16 v[106:109], v[200:203], v[216:219], v[106:109]
	v_mfma_f32_16x16x32_bf16 v[94:97], v[148:151], v[224:227], v[94:97]
	v_mfma_f32_16x16x32_bf16 v[90:93], v[200:203], v[224:227], v[90:93]
	v_mfma_f32_16x16x32_bf16 v[78:81], v[148:151], v[232:235], v[78:81]
	v_mfma_f32_16x16x32_bf16 v[74:77], v[200:203], v[232:235], v[74:77]
	s_setprio 0
	s_barrier
	s_add_i32 s24, 0, 0x1c000
	s_add_i32 s25, s31, s39
	v_add_u32_e32 v173, s24, v131
	v_lshl_add_u64 v[156:157], v[156:157], 0, s[86:87]
	s_mov_b32 m0, s25
	ds_read_b128 v[236:239], v173
	ds_read_b128 v[240:243], v173 offset:1024
	ds_read_b128 v[244:247], v173 offset:2048
	ds_read_b128 v[248:251], v173 offset:3072
	global_load_lds_dwordx4 v[156:157], off
	v_lshl_add_u64 v[156:157], v[174:175], 0, s[86:87]
	s_add_i32 m0, s25, 0x2000
	s_nop 0
	global_load_lds_dwordx4 v[156:157], off
	s_setprio 1
	s_barrier
	s_waitcnt lgkmcnt(0)
	v_mfma_f32_16x16x32_bf16 v[118:121], v[236:239], v[204:207], v[118:121]
	v_mfma_f32_16x16x32_bf16 v[114:117], v[244:247], v[204:207], v[114:117]
	v_mfma_f32_16x16x32_bf16 v[102:105], v[236:239], v[212:215], v[102:105]
	v_mfma_f32_16x16x32_bf16 v[98:101], v[244:247], v[212:215], v[98:101]
	v_mfma_f32_16x16x32_bf16 v[86:89], v[236:239], v[220:223], v[86:89]
	v_mfma_f32_16x16x32_bf16 v[82:85], v[244:247], v[220:223], v[82:85]
	v_mfma_f32_16x16x32_bf16 v[70:73], v[236:239], v[228:231], v[70:73]
	v_mfma_f32_16x16x32_bf16 v[66:69], v[244:247], v[228:231], v[66:69]
	v_mfma_f32_16x16x32_bf16 v[118:121], v[240:243], v[208:211], v[118:121]
	v_mfma_f32_16x16x32_bf16 v[114:117], v[248:251], v[208:211], v[114:117]
	v_mfma_f32_16x16x32_bf16 v[102:105], v[240:243], v[216:219], v[102:105]
	v_mfma_f32_16x16x32_bf16 v[98:101], v[248:251], v[216:219], v[98:101]
	v_mfma_f32_16x16x32_bf16 v[86:89], v[240:243], v[224:227], v[86:89]
	v_mfma_f32_16x16x32_bf16 v[82:85], v[248:251], v[224:227], v[82:85]
	v_mfma_f32_16x16x32_bf16 v[70:73], v[240:243], v[232:235], v[70:73]
	v_mfma_f32_16x16x32_bf16 v[66:69], v[248:251], v[232:235], v[66:69]
	s_setprio 0
	s_mov_b32 m0, s45
	v_lshl_add_u64 v[156:157], v[182:183], 0, s[86:87]
	s_barrier
	ds_read_b128 v[204:207], v172 offset:49152
	ds_read_b128 v[208:211], v172 offset:50176
	ds_read_b128 v[212:215], v172 offset:51200
	ds_read_b128 v[216:219], v172 offset:52224
	ds_read_b128 v[220:223], v172 offset:53248
	ds_read_b128 v[224:227], v172 offset:54272
	ds_read_b128 v[228:231], v172 offset:55296
	ds_read_b128 v[232:235], v172 offset:56320
	global_load_lds_dwordx4 v[156:157], off
	v_lshl_add_u64 v[156:157], v[184:185], 0, s[86:87]
	s_mov_b32 m0, s46
	s_nop 0
	global_load_lds_dwordx4 v[156:157], off
	s_setprio 1
	s_barrier
; #define PG8_STAGE(bufoff, gbase, voff) do { _Pragma("unroll") for (int _i = 0; _i < 2; ++_i) \
;     __builtin_amdgcn_global_load_lds((const unsigned*)((const char*)(gbase) + (voff)[_i]), (PG8_LAS unsigned*)(lds + (bufoff) + ldsw + _i * 8192), 16, 0, 0); } while (0)
; template <class Epi, class Sched>
; __device__ __forceinline__ void gemm_phase(PG8_LAS unsigned char* lds, const int lda, const int ldb, const Sched& S, const Epi& E) {
;     ...
;       PG8_BAR; PG8_WAIT_L(0); PG8_MMA(1, 0, At, B0); PG8_BAR; PG8_SCHED;
;       PG8_STAGE(PG8_SB(1, 1), b3 + hstepB, voffB);
;       PG8_WAIT_V(6); PG8_BAR; PG8_MMA(1, 1, At, B1); PG8_BAR;
;     }
;   __device__ __forceinline__ void operator()(const f32x4 (&acc)[2][2][4][2], const Unit& u, int wr, int wc, int fr, int fq) const {
; #pragma unroll
;     for (int ai = 0; ai < 2; ++ai)
; #pragma unroll
;       for (int m = 0; m < 4; ++m) {
;         const int r = u.pm * 256 + ai * 128 + wr * 64 + m * 16 + fr;
; #pragma unroll
;         for (int bj = 0; bj < 2; ++bj)
; #pragma unroll
;           for (int n = 0; n < 2; ++n) {
;             const f32x4 v = acc[ai][bj][m][n];
;             const int c = u.pn * 256 + bj * 128 + wc * 32 + n * 16 + 4 * fq;
;             if (u.pn < 7) {
;               uint2 w; w.x = pack2(v[0], v[1]); w.y = pack2(v[2], v[3]);
;               *reinterpret_cast<uint2*>(PB + (size_t)r * PBW + c) = w;
;             } else {
;               const int nn = c - 1792, part = nn >> 8, ch = nn & 255;
;               if (u.pn == 7 && bj == 0 && wc == 1 && n == 1) {
;                 *reinterpret_cast<float4*>(AB + (size_t)r * 16 + 4 * fq) = make_float4(v[0], v[1], v[2], v[3]);
;               } else {
;                 u16* d; int cstride;
;                 if (r < ML) { const int b = r >> 11, tt = r & 2047; d = FT + ((size_t)(b * 256)) * 4096 + part * 2048 + tt; cstride = 4096; }
;                 else { const int rc = r - ML, b = rc >> 8, tt = rc & 255; d = FTC + ((size_t)(b * 256)) * 512 + part * 256 + tt; cstride = 512; }
; #pragma unroll
;                 for (int e = 0; e < 4; ++e) d[(size_t)(ch + e) * cstride] = f2bf(v[e]);
;                 if (u.pn == 7 && bj == 0 && wc == 0) {
; #pragma unroll
;                   for (int e = 0; e < 4; ++e) {
;                     const int kc = n * 16 + 4 * fq + e;
;                     if (kc >= 1 && kc <= 16) d[(size_t)(64 - kc) * cstride] = f2bf(v[e]);
	s_waitcnt lgkmcnt(0)
	v_mfma_f32_16x16x32_bf16 v[62:65], v[144:147], v[204:207], v[62:65]
	v_mfma_f32_16x16x32_bf16 v[58:61], v[152:155], v[204:207], v[58:61]
	v_mfma_f32_16x16x32_bf16 v[46:49], v[144:147], v[212:215], v[46:49]
	v_mfma_f32_16x16x32_bf16 v[42:45], v[152:155], v[212:215], v[42:45]
	v_mfma_f32_16x16x32_bf16 v[30:33], v[144:147], v[220:223], v[30:33]
	v_mfma_f32_16x16x32_bf16 v[26:29], v[152:155], v[220:223], v[26:29]
	v_mfma_f32_16x16x32_bf16 v[14:17], v[144:147], v[228:231], v[14:17]
	v_mfma_f32_16x16x32_bf16 v[10:13], v[152:155], v[228:231], v[10:13]
	v_mfma_f32_16x16x32_bf16 v[62:65], v[148:151], v[208:211], v[62:65]
	v_mfma_f32_16x16x32_bf16 v[58:61], v[200:203], v[208:211], v[58:61]
	v_mfma_f32_16x16x32_bf16 v[46:49], v[148:151], v[216:219], v[46:49]
	v_mfma_f32_16x16x32_bf16 v[42:45], v[200:203], v[216:219], v[42:45]
	v_mfma_f32_16x16x32_bf16 v[30:33], v[148:151], v[224:227], v[30:33]
	v_mfma_f32_16x16x32_bf16 v[26:29], v[200:203], v[224:227], v[26:29]
	v_mfma_f32_16x16x32_bf16 v[14:17], v[148:151], v[232:235], v[14:17]
	v_mfma_f32_16x16x32_bf16 v[10:13], v[200:203], v[232:235], v[10:13]
	s_setprio 0
	s_barrier
	s_add_u32 s10, s10, 0x40080
	s_addc_u32 s11, s11, 0
	s_add_i32 s24, s24, s39
	v_lshl_add_u64 v[144:145], s[10:11], 0, v[134:135]
	s_mov_b32 m0, s24
	s_nop 0
	global_load_lds_dwordx4 v[144:145], off
	v_lshl_add_u64 v[144:145], s[10:11], 0, v[132:133]
	s_add_i32 m0, s24, 0x2000
	s_nop 0
	global_load_lds_dwordx4 v[144:145], off
	s_waitcnt vmcnt(6)
	s_setprio 1
	s_barrier
	v_mfma_f32_16x16x32_bf16 v[54:57], v[236:239], v[204:207], v[54:57]
	v_mfma_f32_16x16x32_bf16 v[50:53], v[244:247], v[204:207], v[50:53]
	v_mfma_f32_16x16x32_bf16 v[38:41], v[236:239], v[212:215], v[38:41]
	v_mfma_f32_16x16x32_bf16 v[34:37], v[244:247], v[212:215], v[34:37]
	v_mfma_f32_16x16x32_bf16 v[22:25], v[236:239], v[220:223], v[22:25]
	v_mfma_f32_16x16x32_bf16 v[18:21], v[244:247], v[220:223], v[18:21]
	v_mfma_f32_16x16x32_bf16 v[6:9], v[236:239], v[228:231], v[6:9]
	v_mfma_f32_16x16x32_bf16 v[2:5], v[244:247], v[228:231], v[2:5]
	v_mfma_f32_16x16x32_bf16 v[54:57], v[240:243], v[208:211], v[54:57]
	v_mfma_f32_16x16x32_bf16 v[50:53], v[248:251], v[208:211], v[50:53]
	v_mfma_f32_16x16x32_bf16 v[38:41], v[240:243], v[216:219], v[38:41]
	v_mfma_f32_16x16x32_bf16 v[34:37], v[248:251], v[216:219], v[34:37]
	v_mfma_f32_16x16x32_bf16 v[22:25], v[240:243], v[224:227], v[22:25]
	v_mfma_f32_16x16x32_bf16 v[18:21], v[248:251], v[224:227], v[18:21]
	v_mfma_f32_16x16x32_bf16 v[6:9], v[240:243], v[232:235], v[6:9]
	v_mfma_f32_16x16x32_bf16 v[2:5], v[248:251], v[232:235], v[2:5]
	s_setprio 0
	s_add_i32 s30, s30, 2
	s_add_u32 s8, s8, 0x100
	s_addc_u32 s9, s9, 0
	s_add_u32 s28, s28, 0x100
	s_addc_u32 s29, s29, 0
	s_cmp_gt_u32 s30, 13
	s_barrier
	s_cbranch_scc0 .LBB0_335
	s_lshl_b32 s15, s2, 8
	s_add_i32 s15, s15, s44
	v_or_b32_e32 v152, s15, v1
	s_mov_b32 s2, 0xffff
	v_cmp_lt_i32_e64 s[10:11], s2, v152
	s_and_b32 s2, s15, 0xffffff00
	s_add_i32 s2, s2, 0xffff0000
	s_lshl_b64 s[28:29], s[2:3], 10
	s_ashr_i32 s2, s15, 3
	s_and_b32 s8, s2, 0xffffff00
	s_ashr_i32 s9, s8, 31
	s_lshl_b64 s[26:27], s[8:9], 13
	s_lshl_b32 s24, s48, 8
	s_cmp_gt_i32 s48, 6
	s_cselect_b64 s[30:31], -1, 0
	v_bitop3_b32 v146, s15, v186, v1 bitop3:0xc8
	v_bitop3_b32 v148, s15, v187, v1 bitop3:0xc8
	s_mov_b64 s[8:9], -1
	s_and_b64 vcc, exec, s[30:31]
	s_cbranch_vccz .LBB0_346
	s_and_saveexec_b64 s[8:9], s[10:11]
	s_xor_b64 s[8:9], exec, s[8:9]
	s_add_u32 s34, s54, s28
	s_addc_u32 s35, s55, s29
	s_or_saveexec_b64 s[8:9], s[8:9]
	s_add_i32 s2, s24, 0xfffff900
	v_mov_b64_e32 v[144:145], 0x200
	v_mov_b32_e32 v150, s2
	v_mov_b64_e32 v[154:155], s[34:35]
	v_mov_b64_e32 v[156:157], v[146:147]
	s_xor_b64 exec, exec, s[8:9]
	s_add_u32 s34, s69, s26
	s_addc_u32 s35, s52, s27
	s_lshl_b32 s2, s2, 3
	v_mov_b64_e32 v[144:145], 0x1000
	v_mov_b32_e32 v150, s2
	v_mov_b64_e32 v[154:155], s[34:35]
	v_mov_b64_e32 v[156:157], v[148:149]
	s_or_b64 exec, exec, s[8:9]
	v_ashrrev_i32_e32 v151, 31, v150
	v_lshl_add_u64 v[150:151], v[150:151], 1, v[154:155]
	v_lshlrev_b32_e32 v154, 1, v156
	v_mov_b32_e32 v155, v0
	v_mul_u32_u24_e32 v145, v144, v136
	v_lshl_add_u64 v[150:151], v[150:151], 0, v[154:155]
	v_lshlrev_b32_e32 v154, 1, v145
	v_cvt_pk_bf16_f32 v149, v126, s0
	v_lshl_add_u64 v[154:155], v[150:151], 0, v[154:155]
	v_mul_u32_u24_e32 v147, v144, v166
	global_store_short v[154:155], v149, off
	v_lshlrev_b32_e32 v154, 1, v147
	v_mov_b32_e32 v155, v0
	v_cvt_pk_bf16_f32 v145, v127, s0
	v_lshl_add_u64 v[154:155], v[150:151], 0, v[154:155]
	v_mul_u32_u24_e32 v153, v144, v167
	global_store_short v[154:155], v145, off
	v_lshlrev_b32_e32 v154, 1, v153
	v_mov_b32_e32 v155, v0
	s_cmp_lg_u32 s48, 7
	v_cvt_pk_bf16_f32 v147, v128, s0
	v_lshl_add_u64 v[154:155], v[150:151], 0, v[154:155]
	s_cselect_b64 s[8:9], -1, 0
	global_store_short v[154:155], v147, off
	v_mul_u32_u24_e32 v154, v144, v168
	s_xor_b64 s[34:35], s[12:13], -1
	v_lshlrev_b32_e32 v154, 1, v154
	v_mov_b32_e32 v155, v0
	s_or_b64 s[8:9], s[34:35], s[8:9]
	v_cvt_pk_bf16_f32 v153, v129, s0
	v_lshl_add_u64 v[154:155], v[150:151], 0, v[154:155]
	s_and_b64 vcc, exec, s[8:9]
	global_store_short v[154:155], v153, off
	s_cbranch_vccnz .LBB0_345
	s_and_saveexec_b64 s[8:9], s[4:5]
	s_cbranch_execz .LBB0_344
	v_mul_u32_u24_e32 v154, v144, v158
	v_lshlrev_b32_e32 v154, 1, v154
	v_mov_b32_e32 v155, v0
	v_lshl_add_u64 v[154:155], v[150:151], 0, v[154:155]
	global_store_short v[154:155], v149, off

; #define PG8_STAGE(bufoff, gbase, voff) do { _Pragma("unroll") for (int _i = 0; _i < 2; ++_i) \
;     __builtin_amdgcn_global_load_lds((const unsigned*)((const char*)(gbase) + (voff)[_i]), (PG8_LAS unsigned*)(lds + (bufoff) + ldsw + _i * 8192), 16, 0, 0); } while (0)
; #define PG8_LDA(dst, b, h) do { _Pragma("unroll") for (int m = 0; m < 4; ++m) _Pragma("unroll") for (int k = 0; k < 2; ++k) dst[m][k] = *(const PG8_LAS bf16x8*)(lds + PG8_SA(b, h) + aoff + m * 2048 + k * 1024); } while (0)
; #define PG8_LDB(dst, b, h) do { _Pragma("unroll") for (int n = 0; n < 2; ++n) _Pragma("unroll") for (int k = 0; k < 2; ++k) dst[n][k] = *(const PG8_LAS bf16x8*)(lds + PG8_SB(b, h) + boff + n * 2048 + k * 1024); } while (0)
; #define PG8_MMA(ai, bj, At, Bt) do { __builtin_amdgcn_s_setprio(1); _Pragma("unroll") for (int m = 0; m < 4; ++m) _Pragma("unroll") for (int n = 0; n < 2; ++n) _Pragma("unroll") for (int k = 0; k < 2; ++k) \
;     acc[ai][bj][m][n] = __builtin_amdgcn_mfma_f32_16x16x32_bf16(Bt[n][k], At[m][k], acc[ai][bj][m][n], 0, 0, 0); __builtin_amdgcn_s_setprio(0); } while (0)
; #define PG8_WAIT_L(n) asm volatile("s_waitcnt lgkmcnt(" #n ")" ::: "memory")
; #define PG8_BAR __builtin_amdgcn_s_barrier()
; #define PG8_SCHED __builtin_amdgcn_sched_barrier(0)
; template <class Epi, class Sched>
; __device__ __forceinline__ void gemm_phase(PG8_LAS unsigned char* lds, const int lda, const int ldb, const Sched& S, const Epi& E) {
;     ...
;     for (int t = 0; t < nt; t += 2) {
;       const bool last = (t == nt - 2);
;       const char* a1 = cA + (size_t)(t + 1) * kstep;
;       const char* a2 = last ? nA : cA + (size_t)(t + 2) * kstep; const char* b2 = last ? nB : cB + (size_t)(t + 2) * kstep;
;       const char* a3 = a2 + kstep; const char* b3 = b2 + kstep;
;       PG8_LDB(B0, 0, 0); PG8_SCHED; PG8_LDA(At, 0, 0); PG8_STAGE(PG8_SA(1, 1), a1 + hstepA, voffA);
;       PG8_WAIT_L(8); PG8_BAR; PG8_WAIT_L(0); PG8_MMA(0, 0, At, B0); PG8_BAR; PG8_SCHED;
;       PG8_LDB(B1, 0, 1); PG8_STAGE(PG8_SB(0, 0), b2, voffB);
;       PG8_BAR; PG8_WAIT_L(0); PG8_MMA(0, 1, At, B1); PG8_BAR;
;       PG8_LDA(At, 0, 1); PG8_STAGE(PG8_SA(0, 0), a2, voffA);
;       PG8_BAR; PG8_WAIT_L(0); PG8_MMA(1, 0, At, B0); PG8_BAR; PG8_SCHED;
.LBB0_685:
	s_add_u32 s12, s10, 0xfffc0080
	s_addc_u32 s13, s11, -1
	s_add_i32 s31, 0, 0x10000
	v_add_u32_e32 v156, s31, v131
	ds_read_b128 v[144:147], v156
	ds_read_b128 v[148:151], v156 offset:1024
	ds_read_b128 v[152:155], v156 offset:2048
	ds_read_b128 v[200:203], v156 offset:3072
	s_cmp_eq_u32 s30, 12
	s_cselect_b32 s25, s19, s13
	s_cselect_b32 s24, s26, s12
	s_cselect_b32 s13, s17, s29
	s_cselect_b32 s12, s27, s28
	v_lshl_add_u64 v[156:157], s[10:11], 0, v[140:141]
	s_add_i32 m0, s40, 0xc000
	ds_read_b128 v[204:207], v172
	ds_read_b128 v[208:211], v172 offset:1024
	ds_read_b128 v[212:215], v172 offset:2048
	ds_read_b128 v[216:219], v172 offset:3072
	ds_read_b128 v[220:223], v172 offset:4096
	ds_read_b128 v[224:227], v172 offset:5120
	ds_read_b128 v[228:231], v172 offset:6144
	ds_read_b128 v[232:235], v172 offset:7168
	global_load_lds_dwordx4 v[156:157], off
	v_lshl_add_u64 v[156:157], s[10:11], 0, v[142:143]
	s_add_i32 m0, s40, 0xe000
	s_nop 0
	global_load_lds_dwordx4 v[156:157], off
	s_waitcnt lgkmcnt(8)
	s_setprio 1
	s_barrier
	s_waitcnt lgkmcnt(0)
	v_mfma_f32_16x16x32_bf16 v[126:129], v[144:147], v[204:207], v[126:129]
	v_mfma_f32_16x16x32_bf16 v[122:125], v[152:155], v[204:207], v[122:125]
	v_mfma_f32_16x16x32_bf16 v[110:113], v[144:147], v[212:215], v[110:113]
	v_mfma_f32_16x16x32_bf16 v[106:109], v[152:155], v[212:215], v[106:109]
	v_mfma_f32_16x16x32_bf16 v[94:97], v[144:147], v[220:223], v[94:97]
	v_mfma_f32_16x16x32_bf16 v[90:93], v[152:155], v[220:223], v[90:93]
	v_mfma_f32_16x16x32_bf16 v[78:81], v[144:147], v[228:231], v[78:81]
	v_mfma_f32_16x16x32_bf16 v[74:77], v[152:155], v[228:231], v[74:77]
	v_mfma_f32_16x16x32_bf16 v[126:129], v[148:151], v[208:211], v[126:129]
	v_mfma_f32_16x16x32_bf16 v[122:125], v[200:203], v[208:211], v[122:125]
	v_mfma_f32_16x16x32_bf16 v[110:113], v[148:151], v[216:219], v[110:113]
	v_mfma_f32_16x16x32_bf16 v[106:109], v[200:203], v[216:219], v[106:109]
	v_mfma_f32_16x16x32_bf16 v[94:97], v[148:151], v[224:227], v[94:97]
	v_mfma_f32_16x16x32_bf16 v[90:93], v[200:203], v[224:227], v[90:93]
	v_mfma_f32_16x16x32_bf16 v[78:81], v[148:151], v[232:235], v[78:81]
	v_mfma_f32_16x16x32_bf16 v[74:77], v[200:203], v[232:235], v[74:77]
	s_setprio 0
	s_barrier
	s_add_i32 s33, 0, 0x14000
	v_add_u32_e32 v156, s33, v131
	s_add_i32 s31, s31, s39
	ds_read_b128 v[236:239], v156
	ds_read_b128 v[240:243], v156 offset:1024
	ds_read_b128 v[244:247], v156 offset:2048
	ds_read_b128 v[248:251], v156 offset:3072
	v_lshl_add_u64 v[156:157], s[12:13], 0, v[134:135]
	s_mov_b32 m0, s31
	v_lshl_add_u64 v[174:175], s[12:13], 0, v[132:133]
	global_load_lds_dwordx4 v[156:157], off
	s_add_i32 m0, s31, 0x2000
	s_nop 0
	global_load_lds_dwordx4 v[174:175], off
	s_setprio 1
	s_barrier
	s_waitcnt lgkmcnt(0)
	v_mfma_f32_16x16x32_bf16 v[118:121], v[236:239], v[204:207], v[118:121]
	v_mfma_f32_16x16x32_bf16 v[114:117], v[244:247], v[204:207], v[114:117]
	v_mfma_f32_16x16x32_bf16 v[102:105], v[236:239], v[212:215], v[102:105]
	v_mfma_f32_16x16x32_bf16 v[98:101], v[244:247], v[212:215], v[98:101]
	v_mfma_f32_16x16x32_bf16 v[86:89], v[236:239], v[220:223], v[86:89]
	v_mfma_f32_16x16x32_bf16 v[82:85], v[244:247], v[220:223], v[82:85]
	v_mfma_f32_16x16x32_bf16 v[70:73], v[236:239], v[228:231], v[70:73]
	v_mfma_f32_16x16x32_bf16 v[66:69], v[244:247], v[228:231], v[66:69]
	v_mfma_f32_16x16x32_bf16 v[118:121], v[240:243], v[208:211], v[118:121]
	v_mfma_f32_16x16x32_bf16 v[114:117], v[248:251], v[208:211], v[114:117]
	v_mfma_f32_16x16x32_bf16 v[102:105], v[240:243], v[216:219], v[102:105]
	v_mfma_f32_16x16x32_bf16 v[98:101], v[248:251], v[216:219], v[98:101]
	v_mfma_f32_16x16x32_bf16 v[86:89], v[240:243], v[224:227], v[86:89]
	v_mfma_f32_16x16x32_bf16 v[82:85], v[248:251], v[224:227], v[82:85]
	v_mfma_f32_16x16x32_bf16 v[70:73], v[240:243], v[232:235], v[70:73]
	v_mfma_f32_16x16x32_bf16 v[66:69], v[248:251], v[232:235], v[66:69]
	s_setprio 0
	s_mov_b32 m0, s40
	v_lshl_add_u64 v[182:183], s[24:25], 0, v[134:135]
	s_barrier
	ds_read_b128 v[204:207], v172 offset:16384
	ds_read_b128 v[208:211], v172 offset:17408
	ds_read_b128 v[212:215], v172 offset:18432
	ds_read_b128 v[216:219], v172 offset:19456
	ds_read_b128 v[220:223], v172 offset:20480
	ds_read_b128 v[224:227], v172 offset:21504
	ds_read_b128 v[228:231], v172 offset:22528
	ds_read_b128 v[232:235], v172 offset:23552
	global_load_lds_dwordx4 v[182:183], off
	v_lshl_add_u64 v[184:185], s[24:25], 0, v[132:133]
	s_mov_b32 m0, s41
	s_nop 0
	global_load_lds_dwordx4 v[184:185], off
	s_setprio 1
	s_barrier
	s_waitcnt lgkmcnt(0)
	v_mfma_f32_16x16x32_bf16 v[62:65], v[144:147], v[204:207], v[62:65]
	v_mfma_f32_16x16x32_bf16 v[58:61], v[152:155], v[204:207], v[58:61]
	v_mfma_f32_16x16x32_bf16 v[46:49], v[144:147], v[212:215], v[46:49]
	v_mfma_f32_16x16x32_bf16 v[42:45], v[152:155], v[212:215], v[42:45]
	v_mfma_f32_16x16x32_bf16 v[30:33], v[144:147], v[220:223], v[30:33]
	v_mfma_f32_16x16x32_bf16 v[26:29], v[152:155], v[220:223], v[26:29]
	v_mfma_f32_16x16x32_bf16 v[14:17], v[144:147], v[228:231], v[14:17]
	v_mfma_f32_16x16x32_bf16 v[10:13], v[152:155], v[228:231], v[10:13]
	v_mfma_f32_16x16x32_bf16 v[62:65], v[148:151], v[208:211], v[62:65]
	v_mfma_f32_16x16x32_bf16 v[58:61], v[200:203], v[208:211], v[58:61]
	v_mfma_f32_16x16x32_bf16 v[46:49], v[148:151], v[216:219], v[46:49]
	v_mfma_f32_16x16x32_bf16 v[42:45], v[200:203], v[216:219], v[42:45]
	v_mfma_f32_16x16x32_bf16 v[30:33], v[148:151], v[224:227], v[30:33]
	v_mfma_f32_16x16x32_bf16 v[26:29], v[200:203], v[224:227], v[26:29]
	v_mfma_f32_16x16x32_bf16 v[14:17], v[148:151], v[232:235], v[14:17]
	v_mfma_f32_16x16x32_bf16 v[10:13], v[200:203], v[232:235], v[10:13]
	s_setprio 0
	s_barrier
; #define PG8_STAGE(bufoff, gbase, voff) do { _Pragma("unroll") for (int _i = 0; _i < 2; ++_i) \
;     __builtin_amdgcn_global_load_lds((const unsigned*)((const char*)(gbase) + (voff)[_i]), (PG8_LAS unsigned*)(lds + (bufoff) + ldsw + _i * 8192), 16, 0, 0); } while (0)
; #define PG8_LDA(dst, b, h) do { _Pragma("unroll") for (int m = 0; m < 4; ++m) _Pragma("unroll") for (int k = 0; k < 2; ++k) dst[m][k] = *(const PG8_LAS bf16x8*)(lds + PG8_SA(b, h) + aoff + m * 2048 + k * 1024); } while (0)
; #define PG8_LDB(dst, b, h) do { _Pragma("unroll") for (int n = 0; n < 2; ++n) _Pragma("unroll") for (int k = 0; k < 2; ++k) dst[n][k] = *(const PG8_LAS bf16x8*)(lds + PG8_SB(b, h) + boff + n * 2048 + k * 1024); } while (0)
; #define PG8_MMA(ai, bj, At, Bt) do { __builtin_amdgcn_s_setprio(1); _Pragma("unroll") for (int m = 0; m < 4; ++m) _Pragma("unroll") for (int n = 0; n < 2; ++n) _Pragma("unroll") for (int k = 0; k < 2; ++k) \
;     acc[ai][bj][m][n] = __builtin_amdgcn_mfma_f32_16x16x32_bf16(Bt[n][k], At[m][k], acc[ai][bj][m][n], 0, 0, 0); __builtin_amdgcn_s_setprio(0); } while (0)
; #define PG8_WAIT_V(n) asm volatile("s_waitcnt vmcnt(" #n ")" ::: "memory")
; #define PG8_WAIT_L(n) asm volatile("s_waitcnt lgkmcnt(" #n ")" ::: "memory")
; #define PG8_BAR __builtin_amdgcn_s_barrier()
; #define PG8_SCHED __builtin_amdgcn_sched_barrier(0)
; template <class Epi, class Sched>
; __device__ __forceinline__ void gemm_phase(PG8_LAS unsigned char* lds, const int lda, const int ldb, const Sched& S, const Epi& E) {
;     ...
;       PG8_STAGE(PG8_SB(0, 1), b2 + hstepB, voffB);
;       PG8_WAIT_V(6); PG8_BAR; PG8_MMA(1, 1, At, B1); PG8_BAR;
;       PG8_LDB(B0, 1, 0); PG8_SCHED; PG8_LDA(At, 1, 0); PG8_STAGE(PG8_SA(0, 1), a2 + hstepA, voffA);
;       PG8_WAIT_L(8); PG8_BAR; PG8_WAIT_L(0); PG8_MMA(0, 0, At, B0); PG8_BAR; PG8_SCHED;
;       PG8_LDB(B1, 1, 1); PG8_STAGE(PG8_SB(1, 0), b3, voffB);
;       PG8_BAR; PG8_WAIT_L(0); PG8_MMA(0, 1, At, B1); PG8_BAR;
;       PG8_LDA(At, 1, 1); PG8_STAGE(PG8_SA(1, 0), a3, voffA);
;       PG8_BAR; PG8_WAIT_L(0); PG8_MMA(1, 0, At, B0); PG8_BAR; PG8_SCHED;
	s_add_u32 s34, s12, 0x40000
	s_addc_u32 s35, s13, 0
	s_add_i32 s31, s33, s39
	v_lshl_add_u64 v[144:145], s[34:35], 0, v[134:135]
	s_mov_b32 m0, s31
	s_nop 0
	global_load_lds_dwordx4 v[144:145], off
	v_lshl_add_u64 v[144:145], s[34:35], 0, v[132:133]
	s_add_i32 m0, s31, 0x2000
	s_nop 0
	global_load_lds_dwordx4 v[144:145], off
	s_waitcnt vmcnt(6)
	s_setprio 1
	s_barrier
	v_mfma_f32_16x16x32_bf16 v[54:57], v[236:239], v[204:207], v[54:57]
	v_mfma_f32_16x16x32_bf16 v[50:53], v[244:247], v[204:207], v[50:53]
	v_mfma_f32_16x16x32_bf16 v[38:41], v[236:239], v[212:215], v[38:41]
	v_mfma_f32_16x16x32_bf16 v[34:37], v[244:247], v[212:215], v[34:37]
	v_mfma_f32_16x16x32_bf16 v[22:25], v[236:239], v[220:223], v[22:25]
	v_mfma_f32_16x16x32_bf16 v[18:21], v[244:247], v[220:223], v[18:21]
	v_mfma_f32_16x16x32_bf16 v[6:9], v[236:239], v[228:231], v[6:9]
	v_mfma_f32_16x16x32_bf16 v[2:5], v[244:247], v[228:231], v[2:5]
	v_mfma_f32_16x16x32_bf16 v[54:57], v[240:243], v[208:211], v[54:57]
	v_mfma_f32_16x16x32_bf16 v[50:53], v[248:251], v[208:211], v[50:53]
	v_mfma_f32_16x16x32_bf16 v[38:41], v[240:243], v[216:219], v[38:41]
	v_mfma_f32_16x16x32_bf16 v[34:37], v[248:251], v[216:219], v[34:37]
	v_mfma_f32_16x16x32_bf16 v[22:25], v[240:243], v[224:227], v[22:25]
	v_mfma_f32_16x16x32_bf16 v[18:21], v[248:251], v[224:227], v[18:21]
	v_mfma_f32_16x16x32_bf16 v[6:9], v[240:243], v[232:235], v[6:9]
	v_mfma_f32_16x16x32_bf16 v[2:5], v[248:251], v[232:235], v[2:5]
	s_setprio 0
	s_add_i32 s31, 0, 0x18000
	v_add_u32_e32 v173, s31, v131
	s_barrier
	ds_read_b128 v[144:147], v173
	ds_read_b128 v[148:151], v173 offset:1024
	ds_read_b128 v[152:155], v173 offset:2048
	ds_read_b128 v[200:203], v173 offset:3072
	s_add_u32 s24, s24, 0x40000
	s_addc_u32 s25, s25, 0
	s_mov_b32 m0, s42
	v_lshl_add_u64 v[236:237], s[24:25], 0, v[134:135]
	ds_read_b128 v[204:207], v172 offset:32768
	ds_read_b128 v[208:211], v172 offset:33792
	ds_read_b128 v[212:215], v172 offset:34816
	ds_read_b128 v[216:219], v172 offset:35840
	ds_read_b128 v[220:223], v172 offset:36864
	ds_read_b128 v[224:227], v172 offset:37888
	ds_read_b128 v[228:231], v172 offset:38912
	ds_read_b128 v[232:235], v172 offset:39936
	global_load_lds_dwordx4 v[236:237], off
	v_lshl_add_u64 v[236:237], s[24:25], 0, v[132:133]
	s_mov_b32 m0, s43
	s_nop 0
	global_load_lds_dwordx4 v[236:237], off
	s_waitcnt lgkmcnt(8)
	s_setprio 1
	s_barrier
	s_waitcnt lgkmcnt(0)
	v_mfma_f32_16x16x32_bf16 v[126:129], v[144:147], v[204:207], v[126:129]
	v_mfma_f32_16x16x32_bf16 v[122:125], v[152:155], v[204:207], v[122:125]
	v_mfma_f32_16x16x32_bf16 v[110:113], v[144:147], v[212:215], v[110:113]
	v_mfma_f32_16x16x32_bf16 v[106:109], v[152:155], v[212:215], v[106:109]
	v_mfma_f32_16x16x32_bf16 v[94:97], v[144:147], v[220:223], v[94:97]
	v_mfma_f32_16x16x32_bf16 v[90:93], v[152:155], v[220:223], v[90:93]
	v_mfma_f32_16x16x32_bf16 v[78:81], v[144:147], v[228:231], v[78:81]
	v_mfma_f32_16x16x32_bf16 v[74:77], v[152:155], v[228:231], v[74:77]
	v_mfma_f32_16x16x32_bf16 v[126:129], v[148:151], v[208:211], v[126:129]
	v_mfma_f32_16x16x32_bf16 v[122:125], v[200:203], v[208:211], v[122:125]
	v_mfma_f32_16x16x32_bf16 v[110:113], v[148:151], v[216:219], v[110:113]
	v_mfma_f32_16x16x32_bf16 v[106:109], v[200:203], v[216:219], v[106:109]
	v_mfma_f32_16x16x32_bf16 v[94:97], v[148:151], v[224:227], v[94:97]
	v_mfma_f32_16x16x32_bf16 v[90:93], v[200:203], v[224:227], v[90:93]
	v_mfma_f32_16x16x32_bf16 v[78:81], v[148:151], v[232:235], v[78:81]
	v_mfma_f32_16x16x32_bf16 v[74:77], v[200:203], v[232:235], v[74:77]
	s_setprio 0
	s_barrier
	s_add_i32 s24, 0, 0x1c000
	s_add_i32 s25, s31, s39
	v_add_u32_e32 v173, s24, v131
	v_lshl_add_u64 v[156:157], v[156:157], 0, s[86:87]
	s_mov_b32 m0, s25
	ds_read_b128 v[236:239], v173
	ds_read_b128 v[240:243], v173 offset:1024
	ds_read_b128 v[244:247], v173 offset:2048
	ds_read_b128 v[248:251], v173 offset:3072
	global_load_lds_dwordx4 v[156:157], off
	v_lshl_add_u64 v[156:157], v[174:175], 0, s[86:87]
	s_add_i32 m0, s25, 0x2000
	s_nop 0
	global_load_lds_dwordx4 v[156:157], off
	s_setprio 1
	s_barrier
	s_waitcnt lgkmcnt(0)
	v_mfma_f32_16x16x32_bf16 v[118:121], v[236:239], v[204:207], v[118:121]
	v_mfma_f32_16x16x32_bf16 v[114:117], v[244:247], v[204:207], v[114:117]
	v_mfma_f32_16x16x32_bf16 v[102:105], v[236:239], v[212:215], v[102:105]
	v_mfma_f32_16x16x32_bf16 v[98:101], v[244:247], v[212:215], v[98:101]
	v_mfma_f32_16x16x32_bf16 v[86:89], v[236:239], v[220:223], v[86:89]
	v_mfma_f32_16x16x32_bf16 v[82:85], v[244:247], v[220:223], v[82:85]
	v_mfma_f32_16x16x32_bf16 v[70:73], v[236:239], v[228:231], v[70:73]
	v_mfma_f32_16x16x32_bf16 v[66:69], v[244:247], v[228:231], v[66:69]
	v_mfma_f32_16x16x32_bf16 v[118:121], v[240:243], v[208:211], v[118:121]
	v_mfma_f32_16x16x32_bf16 v[114:117], v[248:251], v[208:211], v[114:117]
	v_mfma_f32_16x16x32_bf16 v[102:105], v[240:243], v[216:219], v[102:105]
	v_mfma_f32_16x16x32_bf16 v[98:101], v[248:251], v[216:219], v[98:101]
	v_mfma_f32_16x16x32_bf16 v[86:89], v[240:243], v[224:227], v[86:89]
	v_mfma_f32_16x16x32_bf16 v[82:85], v[248:251], v[224:227], v[82:85]
	v_mfma_f32_16x16x32_bf16 v[70:73], v[240:243], v[232:235], v[70:73]
	v_mfma_f32_16x16x32_bf16 v[66:69], v[248:251], v[232:235], v[66:69]
	s_setprio 0
	s_mov_b32 m0, s45
	v_lshl_add_u64 v[156:157], v[182:183], 0, s[86:87]
	s_barrier
	ds_read_b128 v[204:207], v172 offset:49152
	ds_read_b128 v[208:211], v172 offset:50176
	ds_read_b128 v[212:215], v172 offset:51200
	ds_read_b128 v[216:219], v172 offset:52224
	ds_read_b128 v[220:223], v172 offset:53248
	ds_read_b128 v[224:227], v172 offset:54272
	ds_read_b128 v[228:231], v172 offset:55296
	ds_read_b128 v[232:235], v172 offset:56320
	global_load_lds_dwordx4 v[156:157], off
	v_lshl_add_u64 v[156:157], v[184:185], 0, s[86:87]
	s_mov_b32 m0, s46
	s_nop 0
	global_load_lds_dwordx4 v[156:157], off
	s_setprio 1
	s_barrier
; #define PG8_STAGE(bufoff, gbase, voff) do { _Pragma("unroll") for (int _i = 0; _i < 2; ++_i) \
;     __builtin_amdgcn_global_load_lds((const unsigned*)((const char*)(gbase) + (voff)[_i]), (PG8_LAS unsigned*)(lds + (bufoff) + ldsw + _i * 8192), 16, 0, 0); } while (0)
; template <class Epi, class Sched>
; __device__ __forceinline__ void gemm_phase(PG8_LAS unsigned char* lds, const int lda, const int ldb, const Sched& S, const Epi& E) {
;     ...
;       PG8_BAR; PG8_WAIT_L(0); PG8_MMA(1, 0, At, B0); PG8_BAR; PG8_SCHED;
;       PG8_STAGE(PG8_SB(1, 1), b3 + hstepB, voffB);
;       PG8_WAIT_V(6); PG8_BAR; PG8_MMA(1, 1, At, B1); PG8_BAR;
;     }
;   __device__ __forceinline__ void operator()(const f32x4 (&acc)[2][2][4][2], const Unit& u, int wr, int wc, int fr, int fq) const {
; #pragma unroll
;     for (int ai = 0; ai < 2; ++ai)
; #pragma unroll
;       for (int m = 0; m < 4; ++m) {
;         const int r = u.pm * 256 + ai * 128 + wr * 64 + m * 16 + fr;
; #pragma unroll
;         for (int bj = 0; bj < 2; ++bj)
; #pragma unroll
;           for (int n = 0; n < 2; ++n) {
;             const f32x4 v = acc[ai][bj][m][n];
;             const int c = u.pn * 256 + bj * 128 + wc * 32 + n * 16 + 4 * fq;
;             if (u.pn < 7) {
;               uint2 w; w.x = pack2(v[0], v[1]); w.y = pack2(v[2], v[3]);
;               *reinterpret_cast<uint2*>(PB + (size_t)r * PBW + c) = w;
;             } else {
;               const int nn = c - 1792, part = nn >> 8, ch = nn & 255;
;               if (u.pn == 7 && bj == 0 && wc == 1 && n == 1) {
;                 *reinterpret_cast<float4*>(AB + (size_t)r * 16 + 4 * fq) = make_float4(v[0], v[1], v[2], v[3]);
;               } else {
;                 u16* d; int cstride;
;                 if (r < ML) { const int b = r >> 11, tt = r & 2047; d = FT + ((size_t)(b * 256)) * 4096 + part * 2048 + tt; cstride = 4096; }
;                 else { const int rc = r - ML, b = rc >> 8, tt = rc & 255; d = FTC + ((size_t)(b * 256)) * 512 + part * 256 + tt; cstride = 512; }
; #pragma unroll
;                 for (int e = 0; e < 4; ++e) d[(size_t)(ch + e) * cstride] = f2bf(v[e]);
;                 if (u.pn == 7 && bj == 0 && wc == 0) {
; #pragma unroll
;                   for (int e = 0; e < 4; ++e) {
;                     const int kc = n * 16 + 4 * fq + e;
;                     if (kc >= 1 && kc <= 16) d[(size_t)(64 - kc) * cstride] = f2bf(v[e]);
	s_waitcnt lgkmcnt(0)
	v_mfma_f32_16x16x32_bf16 v[62:65], v[144:147], v[204:207], v[62:65]
	v_mfma_f32_16x16x32_bf16 v[58:61], v[152:155], v[204:207], v[58:61]
	v_mfma_f32_16x16x32_bf16 v[46:49], v[144:147], v[212:215], v[46:49]
	v_mfma_f32_16x16x32_bf16 v[42:45], v[152:155], v[212:215], v[42:45]
	v_mfma_f32_16x16x32_bf16 v[30:33], v[144:147], v[220:223], v[30:33]
	v_mfma_f32_16x16x32_bf16 v[26:29], v[152:155], v[220:223], v[26:29]
	v_mfma_f32_16x16x32_bf16 v[14:17], v[144:147], v[228:231], v[14:17]
	v_mfma_f32_16x16x32_bf16 v[10:13], v[152:155], v[228:231], v[10:13]
	v_mfma_f32_16x16x32_bf16 v[62:65], v[148:151], v[208:211], v[62:65]
	v_mfma_f32_16x16x32_bf16 v[58:61], v[200:203], v[208:211], v[58:61]
	v_mfma_f32_16x16x32_bf16 v[46:49], v[148:151], v[216:219], v[46:49]
	v_mfma_f32_16x16x32_bf16 v[42:45], v[200:203], v[216:219], v[42:45]
	v_mfma_f32_16x16x32_bf16 v[30:33], v[148:151], v[224:227], v[30:33]
	v_mfma_f32_16x16x32_bf16 v[26:29], v[200:203], v[224:227], v[26:29]
	v_mfma_f32_16x16x32_bf16 v[14:17], v[148:151], v[232:235], v[14:17]
	v_mfma_f32_16x16x32_bf16 v[10:13], v[200:203], v[232:235], v[10:13]
	s_setprio 0
	s_barrier
	s_add_u32 s12, s12, 0x40080
	s_addc_u32 s13, s13, 0
	s_add_i32 s24, s24, s39
	v_lshl_add_u64 v[144:145], s[12:13], 0, v[134:135]
	s_mov_b32 m0, s24
	s_nop 0
	global_load_lds_dwordx4 v[144:145], off
	v_lshl_add_u64 v[144:145], s[12:13], 0, v[132:133]
	s_add_i32 m0, s24, 0x2000
	s_nop 0
	global_load_lds_dwordx4 v[144:145], off
	s_waitcnt vmcnt(6)
	s_setprio 1
	s_barrier
	v_mfma_f32_16x16x32_bf16 v[54:57], v[236:239], v[204:207], v[54:57]
	v_mfma_f32_16x16x32_bf16 v[50:53], v[244:247], v[204:207], v[50:53]
	v_mfma_f32_16x16x32_bf16 v[38:41], v[236:239], v[212:215], v[38:41]
	v_mfma_f32_16x16x32_bf16 v[34:37], v[244:247], v[212:215], v[34:37]
	v_mfma_f32_16x16x32_bf16 v[22:25], v[236:239], v[220:223], v[22:25]
	v_mfma_f32_16x16x32_bf16 v[18:21], v[244:247], v[220:223], v[18:21]
	v_mfma_f32_16x16x32_bf16 v[6:9], v[236:239], v[228:231], v[6:9]
	v_mfma_f32_16x16x32_bf16 v[2:5], v[244:247], v[228:231], v[2:5]
	v_mfma_f32_16x16x32_bf16 v[54:57], v[240:243], v[208:211], v[54:57]
	v_mfma_f32_16x16x32_bf16 v[50:53], v[248:251], v[208:211], v[50:53]
	v_mfma_f32_16x16x32_bf16 v[38:41], v[240:243], v[216:219], v[38:41]
	v_mfma_f32_16x16x32_bf16 v[34:37], v[248:251], v[216:219], v[34:37]
	v_mfma_f32_16x16x32_bf16 v[22:25], v[240:243], v[224:227], v[22:25]
	v_mfma_f32_16x16x32_bf16 v[18:21], v[248:251], v[224:227], v[18:21]
	v_mfma_f32_16x16x32_bf16 v[6:9], v[240:243], v[232:235], v[6:9]
	v_mfma_f32_16x16x32_bf16 v[2:5], v[248:251], v[232:235], v[2:5]
	s_setprio 0
	s_add_i32 s30, s30, 2
	s_add_u32 s10, s10, 0x100
	s_addc_u32 s11, s11, 0
	s_add_u32 s28, s28, 0x100
	s_addc_u32 s29, s29, 0
	s_cmp_gt_u32 s30, 13
	s_barrier
	s_cbranch_scc0 .LBB0_685
	s_lshl_b32 s17, s2, 8
	s_add_i32 s17, s17, s44
	v_or_b32_e32 v152, s17, v1
	s_mov_b32 s2, 0xffff
	v_cmp_lt_i32_e64 s[12:13], s2, v152
	s_and_b32 s2, s17, 0xffffff00
	s_add_i32 s2, s2, 0xffff0000
	s_lshl_b64 s[28:29], s[2:3], 10
	s_ashr_i32 s2, s17, 3
	s_and_b32 s10, s2, 0xffffff00
	s_ashr_i32 s11, s10, 31
	s_lshl_b64 s[26:27], s[10:11], 13
	s_lshl_b32 s24, s48, 8
	s_cmp_gt_i32 s48, 6
	s_cselect_b64 s[30:31], -1, 0
	v_bitop3_b32 v146, s17, v186, v1 bitop3:0xc8
	v_bitop3_b32 v148, s17, v187, v1 bitop3:0xc8
	s_mov_b64 s[10:11], -1
	s_and_b64 vcc, exec, s[30:31]
	s_cbranch_vccz .LBB0_696
	s_and_saveexec_b64 s[10:11], s[12:13]
	s_xor_b64 s[10:11], exec, s[10:11]
	s_add_u32 s34, s54, s28
	s_addc_u32 s35, s55, s29
	s_or_saveexec_b64 s[10:11], s[10:11]
	s_add_i32 s2, s24, 0xfffff900
	v_mov_b64_e32 v[144:145], 0x200
	v_mov_b32_e32 v150, s2
	v_mov_b64_e32 v[154:155], s[34:35]
	v_mov_b64_e32 v[156:157], v[146:147]
	s_xor_b64 exec, exec, s[10:11]
	s_add_u32 s34, s69, s26
	s_addc_u32 s35, s52, s27
	s_lshl_b32 s2, s2, 3
	v_mov_b64_e32 v[144:145], 0x1000
	v_mov_b32_e32 v150, s2
	v_mov_b64_e32 v[154:155], s[34:35]
	v_mov_b64_e32 v[156:157], v[148:149]
	s_or_b64 exec, exec, s[10:11]
	v_ashrrev_i32_e32 v151, 31, v150
	v_lshl_add_u64 v[150:151], v[150:151], 1, v[154:155]
	v_lshlrev_b32_e32 v154, 1, v156
	v_mov_b32_e32 v155, v0
	v_mul_u32_u24_e32 v145, v144, v136
	v_lshl_add_u64 v[150:151], v[150:151], 0, v[154:155]
	v_lshlrev_b32_e32 v154, 1, v145
	v_cvt_pk_bf16_f32 v149, v126, s0
	v_lshl_add_u64 v[154:155], v[150:151], 0, v[154:155]
	v_mul_u32_u24_e32 v147, v144, v166
	global_store_short v[154:155], v149, off
	v_lshlrev_b32_e32 v154, 1, v147
	v_mov_b32_e32 v155, v0
	v_cvt_pk_bf16_f32 v145, v127, s0
	v_lshl_add_u64 v[154:155], v[150:151], 0, v[154:155]
	v_mul_u32_u24_e32 v153, v144, v167
	global_store_short v[154:155], v145, off
	v_lshlrev_b32_e32 v154, 1, v153
	v_mov_b32_e32 v155, v0
	s_cmp_lg_u32 s48, 7
	v_cvt_pk_bf16_f32 v147, v128, s0
	v_lshl_add_u64 v[154:155], v[150:151], 0, v[154:155]
	s_cselect_b64 s[10:11], -1, 0
	global_store_short v[154:155], v147, off
	v_mul_u32_u24_e32 v154, v144, v168
	s_xor_b64 s[34:35], s[14:15], -1
	v_lshlrev_b32_e32 v154, 1, v154
	v_mov_b32_e32 v155, v0
	s_or_b64 s[10:11], s[34:35], s[10:11]
	v_cvt_pk_bf16_f32 v153, v129, s0
	v_lshl_add_u64 v[154:155], v[150:151], 0, v[154:155]
	s_and_b64 vcc, exec, s[10:11]
	global_store_short v[154:155], v153, off
	s_cbranch_vccnz .LBB0_695
	s_and_saveexec_b64 s[10:11], s[4:5]
	s_cbranch_execz .LBB0_694
	v_mul_u32_u24_e32 v154, v144, v158
	v_lshlrev_b32_e32 v154, 1, v154
	v_mov_b32_e32 v155, v0
	v_lshl_add_u64 v[154:155], v[150:151], 0, v[154:155]
	global_store_short v[154:155], v149, off

; #define PG8_STAGE(bufoff, gbase, voff) do { _Pragma("unroll") for (int _i = 0; _i < 2; ++_i) \
;     __builtin_amdgcn_global_load_lds((const unsigned*)((const char*)(gbase) + (voff)[_i]), (PG8_LAS unsigned*)(lds + (bufoff) + ldsw + _i * 8192), 16, 0, 0); } while (0)
; #define PG8_LDA(dst, b, h) do { _Pragma("unroll") for (int m = 0; m < 4; ++m) _Pragma("unroll") for (int k = 0; k < 2; ++k) dst[m][k] = *(const PG8_LAS bf16x8*)(lds + PG8_SA(b, h) + aoff + m * 2048 + k * 1024); } while (0)
; #define PG8_LDB(dst, b, h) do { _Pragma("unroll") for (int n = 0; n < 2; ++n) _Pragma("unroll") for (int k = 0; k < 2; ++k) dst[n][k] = *(const PG8_LAS bf16x8*)(lds + PG8_SB(b, h) + boff + n * 2048 + k * 1024); } while (0)
; #define PG8_MMA(ai, bj, At, Bt) do { __builtin_amdgcn_s_setprio(1); _Pragma("unroll") for (int m = 0; m < 4; ++m) _Pragma("unroll") for (int n = 0; n < 2; ++n) _Pragma("unroll") for (int k = 0; k < 2; ++k) \
;     acc[ai][bj][m][n] = __builtin_amdgcn_mfma_f32_16x16x32_bf16(Bt[n][k], At[m][k], acc[ai][bj][m][n], 0, 0, 0); __builtin_amdgcn_s_setprio(0); } while (0)
; #define PG8_WAIT_L(n) asm volatile("s_waitcnt lgkmcnt(" #n ")" ::: "memory")
; #define PG8_BAR __builtin_amdgcn_s_barrier()
; #define PG8_SCHED __builtin_amdgcn_sched_barrier(0)
; template <class Epi, class Sched>
; __device__ __forceinline__ void gemm_phase(PG8_LAS unsigned char* lds, const int lda, const int ldb, const Sched& S, const Epi& E) {
;     ...
;     for (int t = 0; t < nt; t += 2) {
;       const bool last = (t == nt - 2);
;       const char* a1 = cA + (size_t)(t + 1) * kstep;
;       const char* a2 = last ? nA : cA + (size_t)(t + 2) * kstep; const char* b2 = last ? nB : cB + (size_t)(t + 2) * kstep;
;       const char* a3 = a2 + kstep; const char* b3 = b2 + kstep;
;       PG8_LDB(B0, 0, 0); PG8_SCHED; PG8_LDA(At, 0, 0); PG8_STAGE(PG8_SA(1, 1), a1 + hstepA, voffA);
;       PG8_WAIT_L(8); PG8_BAR; PG8_WAIT_L(0); PG8_MMA(0, 0, At, B0); PG8_BAR; PG8_SCHED;
;       PG8_LDB(B1, 0, 1); PG8_STAGE(PG8_SB(0, 0), b2, voffB);
;       PG8_BAR; PG8_WAIT_L(0); PG8_MMA(0, 1, At, B1); PG8_BAR;
;       PG8_LDA(At, 0, 1); PG8_STAGE(PG8_SA(0, 0), a2, voffA);
;       PG8_BAR; PG8_WAIT_L(0); PG8_MMA(1, 0, At, B0); PG8_BAR; PG8_SCHED;
.LBB0_1088:
	s_add_u32 s16, s14, 0xfff00080
	s_addc_u32 s17, s15, -1
	s_add_i32 s33, 0, 0x10000
	v_add_u32_e32 v145, s33, v1
	ds_read_b128 v[152:155], v145
	ds_read_b128 v[156:159], v145 offset:1024
	ds_read_b128 v[160:163], v145 offset:2048
	ds_read_b128 v[164:167], v145 offset:3072
	s_cmp_eq_u32 s34, 60
	s_cselect_b32 s19, s7, s17
	s_cselect_b32 s18, s13, s16
	s_cselect_b32 s17, s1, s31
	s_cselect_b32 s16, s29, s30
	v_lshl_add_u64 v[182:183], s[14:15], 0, v[140:141]
	s_add_i32 m0, s21, 0xc000
	ds_read_b128 v[168:171], v131
	ds_read_b128 v[172:175], v131 offset:1024
	ds_read_b128 v[200:203], v131 offset:2048
	ds_read_b128 v[204:207], v131 offset:3072
	ds_read_b128 v[208:211], v131 offset:4096
	ds_read_b128 v[212:215], v131 offset:5120
	ds_read_b128 v[216:219], v131 offset:6144
	ds_read_b128 v[220:223], v131 offset:7168
	global_load_lds_dwordx4 v[182:183], off
	v_lshl_add_u64 v[182:183], s[14:15], 0, v[142:143]
	s_add_i32 m0, s21, 0xe000
	s_nop 0
	global_load_lds_dwordx4 v[182:183], off
	s_waitcnt lgkmcnt(8)
	s_setprio 1
	s_barrier
	s_waitcnt lgkmcnt(0)
	v_mfma_f32_16x16x32_bf16 v[126:129], v[152:155], v[168:171], v[126:129]
	v_mfma_f32_16x16x32_bf16 v[122:125], v[160:163], v[168:171], v[122:125]
	v_mfma_f32_16x16x32_bf16 v[118:121], v[152:155], v[200:203], v[118:121]
	v_mfma_f32_16x16x32_bf16 v[114:117], v[160:163], v[200:203], v[114:117]
	v_mfma_f32_16x16x32_bf16 v[102:105], v[152:155], v[208:211], v[102:105]
	v_mfma_f32_16x16x32_bf16 v[98:101], v[160:163], v[208:211], v[98:101]
	v_mfma_f32_16x16x32_bf16 v[86:89], v[152:155], v[216:219], v[86:89]
	v_mfma_f32_16x16x32_bf16 v[82:85], v[160:163], v[216:219], v[82:85]
	v_mfma_f32_16x16x32_bf16 v[126:129], v[156:159], v[172:175], v[126:129]
	v_mfma_f32_16x16x32_bf16 v[122:125], v[164:167], v[172:175], v[122:125]
	v_mfma_f32_16x16x32_bf16 v[118:121], v[156:159], v[204:207], v[118:121]
	v_mfma_f32_16x16x32_bf16 v[114:117], v[164:167], v[204:207], v[114:117]
	v_mfma_f32_16x16x32_bf16 v[102:105], v[156:159], v[212:215], v[102:105]
	v_mfma_f32_16x16x32_bf16 v[98:101], v[164:167], v[212:215], v[98:101]
	v_mfma_f32_16x16x32_bf16 v[86:89], v[156:159], v[220:223], v[86:89]
	v_mfma_f32_16x16x32_bf16 v[82:85], v[164:167], v[220:223], v[82:85]
	s_setprio 0
	s_barrier
	s_add_i32 s35, 0, 0x14000
	s_add_i32 s33, s33, s20
	v_add_u32_e32 v145, s35, v1
	v_lshl_add_u64 v[182:183], s[16:17], 0, v[134:135]
	s_mov_b32 m0, s33
	ds_read_b128 v[224:227], v145
	ds_read_b128 v[228:231], v145 offset:1024
	ds_read_b128 v[232:235], v145 offset:2048
	ds_read_b128 v[236:239], v145 offset:3072
	global_load_lds_dwordx4 v[182:183], off
	v_lshl_add_u64 v[184:185], s[16:17], 0, v[132:133]
	s_add_i32 m0, s33, 0x2000
	s_nop 0
	global_load_lds_dwordx4 v[184:185], off
	s_setprio 1
	s_barrier
	s_waitcnt lgkmcnt(0)
	v_mfma_f32_16x16x32_bf16 v[110:113], v[224:227], v[168:171], v[110:113]
	v_mfma_f32_16x16x32_bf16 v[106:109], v[232:235], v[168:171], v[106:109]
	v_mfma_f32_16x16x32_bf16 v[94:97], v[224:227], v[200:203], v[94:97]
	v_mfma_f32_16x16x32_bf16 v[90:93], v[232:235], v[200:203], v[90:93]
	v_mfma_f32_16x16x32_bf16 v[78:81], v[224:227], v[208:211], v[78:81]
	v_mfma_f32_16x16x32_bf16 v[74:77], v[232:235], v[208:211], v[74:77]
	v_mfma_f32_16x16x32_bf16 v[70:73], v[224:227], v[216:219], v[70:73]
	v_mfma_f32_16x16x32_bf16 v[66:69], v[232:235], v[216:219], v[66:69]
	v_mfma_f32_16x16x32_bf16 v[110:113], v[228:231], v[172:175], v[110:113]
	v_mfma_f32_16x16x32_bf16 v[106:109], v[236:239], v[172:175], v[106:109]
	v_mfma_f32_16x16x32_bf16 v[94:97], v[228:231], v[204:207], v[94:97]
	v_mfma_f32_16x16x32_bf16 v[90:93], v[236:239], v[204:207], v[90:93]
	v_mfma_f32_16x16x32_bf16 v[78:81], v[228:231], v[212:215], v[78:81]
	v_mfma_f32_16x16x32_bf16 v[74:77], v[236:239], v[212:215], v[74:77]
	v_mfma_f32_16x16x32_bf16 v[70:73], v[228:231], v[220:223], v[70:73]
	v_mfma_f32_16x16x32_bf16 v[66:69], v[236:239], v[220:223], v[66:69]
	s_setprio 0
	s_mov_b32 m0, s21
	v_lshl_add_u64 v[240:241], s[18:19], 0, v[134:135]
	s_barrier
	ds_read_b128 v[168:171], v131 offset:16384
	ds_read_b128 v[172:175], v131 offset:17408
	ds_read_b128 v[200:203], v131 offset:18432
	ds_read_b128 v[204:207], v131 offset:19456
	ds_read_b128 v[208:211], v131 offset:20480
	ds_read_b128 v[212:215], v131 offset:21504
	ds_read_b128 v[216:219], v131 offset:22528
	ds_read_b128 v[220:223], v131 offset:23552
	global_load_lds_dwordx4 v[240:241], off
	v_lshl_add_u64 v[242:243], s[18:19], 0, v[132:133]
	s_mov_b32 m0, s22
	s_nop 0
	global_load_lds_dwordx4 v[242:243], off
	s_setprio 1
	s_barrier
	s_waitcnt lgkmcnt(0)
	v_mfma_f32_16x16x32_bf16 v[62:65], v[152:155], v[168:171], v[62:65]
	v_mfma_f32_16x16x32_bf16 v[58:61], v[160:163], v[168:171], v[58:61]
	v_mfma_f32_16x16x32_bf16 v[54:57], v[152:155], v[200:203], v[54:57]
	v_mfma_f32_16x16x32_bf16 v[46:49], v[160:163], v[200:203], v[46:49]
	v_mfma_f32_16x16x32_bf16 v[38:41], v[152:155], v[208:211], v[38:41]
	v_mfma_f32_16x16x32_bf16 v[34:37], v[160:163], v[208:211], v[34:37]
	v_mfma_f32_16x16x32_bf16 v[22:25], v[152:155], v[216:219], v[22:25]
	v_mfma_f32_16x16x32_bf16 v[18:21], v[160:163], v[216:219], v[18:21]
	v_mfma_f32_16x16x32_bf16 v[62:65], v[156:159], v[172:175], v[62:65]
	v_mfma_f32_16x16x32_bf16 v[58:61], v[164:167], v[172:175], v[58:61]
	v_mfma_f32_16x16x32_bf16 v[54:57], v[156:159], v[204:207], v[54:57]
	v_mfma_f32_16x16x32_bf16 v[46:49], v[164:167], v[204:207], v[46:49]
	v_mfma_f32_16x16x32_bf16 v[38:41], v[156:159], v[212:215], v[38:41]
	v_mfma_f32_16x16x32_bf16 v[34:37], v[164:167], v[212:215], v[34:37]
	v_mfma_f32_16x16x32_bf16 v[22:25], v[156:159], v[220:223], v[22:25]
	v_mfma_f32_16x16x32_bf16 v[18:21], v[164:167], v[220:223], v[18:21]
	s_setprio 0
	s_barrier
; #define PG8_STAGE(bufoff, gbase, voff) do { _Pragma("unroll") for (int _i = 0; _i < 2; ++_i) \
;     __builtin_amdgcn_global_load_lds((const unsigned*)((const char*)(gbase) + (voff)[_i]), (PG8_LAS unsigned*)(lds + (bufoff) + ldsw + _i * 8192), 16, 0, 0); } while (0)
; #define PG8_LDA(dst, b, h) do { _Pragma("unroll") for (int m = 0; m < 4; ++m) _Pragma("unroll") for (int k = 0; k < 2; ++k) dst[m][k] = *(const PG8_LAS bf16x8*)(lds + PG8_SA(b, h) + aoff + m * 2048 + k * 1024); } while (0)
; #define PG8_LDB(dst, b, h) do { _Pragma("unroll") for (int n = 0; n < 2; ++n) _Pragma("unroll") for (int k = 0; k < 2; ++k) dst[n][k] = *(const PG8_LAS bf16x8*)(lds + PG8_SB(b, h) + boff + n * 2048 + k * 1024); } while (0)
; #define PG8_MMA(ai, bj, At, Bt) do { __builtin_amdgcn_s_setprio(1); _Pragma("unroll") for (int m = 0; m < 4; ++m) _Pragma("unroll") for (int n = 0; n < 2; ++n) _Pragma("unroll") for (int k = 0; k < 2; ++k) \
;     acc[ai][bj][m][n] = __builtin_amdgcn_mfma_f32_16x16x32_bf16(Bt[n][k], At[m][k], acc[ai][bj][m][n], 0, 0, 0); __builtin_amdgcn_s_setprio(0); } while (0)
; #define PG8_WAIT_V(n) asm volatile("s_waitcnt vmcnt(" #n ")" ::: "memory")
; #define PG8_WAIT_L(n) asm volatile("s_waitcnt lgkmcnt(" #n ")" ::: "memory")
; #define PG8_BAR __builtin_amdgcn_s_barrier()
; #define PG8_SCHED __builtin_amdgcn_sched_barrier(0)
; template <class Epi, class Sched>
; __device__ __forceinline__ void gemm_phase(PG8_LAS unsigned char* lds, const int lda, const int ldb, const Sched& S, const Epi& E) {
;     ...
;       PG8_STAGE(PG8_SB(0, 1), b2 + hstepB, voffB);
;       PG8_WAIT_V(6); PG8_BAR; PG8_MMA(1, 1, At, B1); PG8_BAR;
;       PG8_LDB(B0, 1, 0); PG8_SCHED; PG8_LDA(At, 1, 0); PG8_STAGE(PG8_SA(0, 1), a2 + hstepA, voffA);
;       PG8_WAIT_L(8); PG8_BAR; PG8_WAIT_L(0); PG8_MMA(0, 0, At, B0); PG8_BAR; PG8_SCHED;
;       PG8_LDB(B1, 1, 1); PG8_STAGE(PG8_SB(1, 0), b3, voffB);
;       PG8_BAR; PG8_WAIT_L(0); PG8_MMA(0, 1, At, B1); PG8_BAR;
;       PG8_LDA(At, 1, 1); PG8_STAGE(PG8_SA(1, 0), a3, voffA);
;       PG8_BAR; PG8_WAIT_L(0); PG8_MMA(1, 0, At, B0); PG8_BAR; PG8_SCHED;
	s_add_u32 s36, s16, 0x100000
	s_addc_u32 s37, s17, 0
	s_add_i32 s33, s35, s20
	v_lshl_add_u64 v[152:153], s[36:37], 0, v[134:135]
	s_mov_b32 m0, s33
	s_nop 0
	global_load_lds_dwordx4 v[152:153], off
	v_lshl_add_u64 v[152:153], s[36:37], 0, v[132:133]
	s_add_i32 m0, s33, 0x2000
	s_nop 0
	global_load_lds_dwordx4 v[152:153], off
	s_waitcnt vmcnt(6)
	s_setprio 1
	s_barrier
	v_mfma_f32_16x16x32_bf16 v[50:53], v[224:227], v[168:171], v[50:53]
	v_mfma_f32_16x16x32_bf16 v[42:45], v[232:235], v[168:171], v[42:45]
	v_mfma_f32_16x16x32_bf16 v[30:33], v[224:227], v[200:203], v[30:33]
	v_mfma_f32_16x16x32_bf16 v[26:29], v[232:235], v[200:203], v[26:29]
	v_mfma_f32_16x16x32_bf16 v[14:17], v[224:227], v[208:211], v[14:17]
	v_mfma_f32_16x16x32_bf16 v[10:13], v[232:235], v[208:211], v[10:13]
	v_mfma_f32_16x16x32_bf16 v[6:9], v[224:227], v[216:219], v[6:9]
	v_mfma_f32_16x16x32_bf16 v[2:5], v[232:235], v[216:219], v[2:5]
	v_mfma_f32_16x16x32_bf16 v[50:53], v[228:231], v[172:175], v[50:53]
	v_mfma_f32_16x16x32_bf16 v[42:45], v[236:239], v[172:175], v[42:45]
	v_mfma_f32_16x16x32_bf16 v[30:33], v[228:231], v[204:207], v[30:33]
	v_mfma_f32_16x16x32_bf16 v[26:29], v[236:239], v[204:207], v[26:29]
	v_mfma_f32_16x16x32_bf16 v[14:17], v[228:231], v[212:215], v[14:17]
	v_mfma_f32_16x16x32_bf16 v[10:13], v[236:239], v[212:215], v[10:13]
	v_mfma_f32_16x16x32_bf16 v[6:9], v[228:231], v[220:223], v[6:9]
	v_mfma_f32_16x16x32_bf16 v[2:5], v[236:239], v[220:223], v[2:5]
	s_setprio 0
	s_add_i32 s33, 0, 0x18000
	v_add_u32_e32 v145, s33, v1
	s_barrier
	ds_read_b128 v[152:155], v145
	ds_read_b128 v[156:159], v145 offset:1024
	ds_read_b128 v[160:163], v145 offset:2048
	ds_read_b128 v[164:167], v145 offset:3072
	s_add_u32 s18, s18, 0x100000
	s_addc_u32 s19, s19, 0
	s_mov_b32 m0, s23
	v_lshl_add_u64 v[224:225], s[18:19], 0, v[134:135]
	ds_read_b128 v[168:171], v131 offset:32768
	ds_read_b128 v[172:175], v131 offset:33792
	ds_read_b128 v[200:203], v131 offset:34816
	ds_read_b128 v[204:207], v131 offset:35840
	ds_read_b128 v[208:211], v131 offset:36864
	ds_read_b128 v[212:215], v131 offset:37888
	ds_read_b128 v[216:219], v131 offset:38912
	ds_read_b128 v[220:223], v131 offset:39936
	global_load_lds_dwordx4 v[224:225], off
	v_lshl_add_u64 v[224:225], s[18:19], 0, v[132:133]
	s_mov_b32 m0, s24
	s_nop 0
	global_load_lds_dwordx4 v[224:225], off
	s_waitcnt lgkmcnt(8)
	s_setprio 1
	s_barrier
	s_waitcnt lgkmcnt(0)
	v_mfma_f32_16x16x32_bf16 v[126:129], v[152:155], v[168:171], v[126:129]
	v_mfma_f32_16x16x32_bf16 v[122:125], v[160:163], v[168:171], v[122:125]
	v_mfma_f32_16x16x32_bf16 v[118:121], v[152:155], v[200:203], v[118:121]
	v_mfma_f32_16x16x32_bf16 v[114:117], v[160:163], v[200:203], v[114:117]
	v_mfma_f32_16x16x32_bf16 v[102:105], v[152:155], v[208:211], v[102:105]
	v_mfma_f32_16x16x32_bf16 v[98:101], v[160:163], v[208:211], v[98:101]
	v_mfma_f32_16x16x32_bf16 v[86:89], v[152:155], v[216:219], v[86:89]
	v_mfma_f32_16x16x32_bf16 v[82:85], v[160:163], v[216:219], v[82:85]
	v_mfma_f32_16x16x32_bf16 v[126:129], v[156:159], v[172:175], v[126:129]
	v_mfma_f32_16x16x32_bf16 v[122:125], v[164:167], v[172:175], v[122:125]
	v_mfma_f32_16x16x32_bf16 v[118:121], v[156:159], v[204:207], v[118:121]
	v_mfma_f32_16x16x32_bf16 v[114:117], v[164:167], v[204:207], v[114:117]
	v_mfma_f32_16x16x32_bf16 v[102:105], v[156:159], v[212:215], v[102:105]
	v_mfma_f32_16x16x32_bf16 v[98:101], v[164:167], v[212:215], v[98:101]
	v_mfma_f32_16x16x32_bf16 v[86:89], v[156:159], v[220:223], v[86:89]
	v_mfma_f32_16x16x32_bf16 v[82:85], v[164:167], v[220:223], v[82:85]
	s_setprio 0
	s_barrier
	s_add_i32 s18, 0, 0x1c000
	s_add_i32 s19, s33, s20
	v_add_u32_e32 v145, s18, v1
	v_lshl_add_u64 v[182:183], v[182:183], 0, s[86:87]
	s_mov_b32 m0, s19
	ds_read_b128 v[224:227], v145
	ds_read_b128 v[228:231], v145 offset:1024
	ds_read_b128 v[232:235], v145 offset:2048
	ds_read_b128 v[236:239], v145 offset:3072
	global_load_lds_dwordx4 v[182:183], off
	v_lshl_add_u64 v[182:183], v[184:185], 0, s[86:87]
	s_add_i32 m0, s19, 0x2000
	s_nop 0
	global_load_lds_dwordx4 v[182:183], off
	s_setprio 1
	s_barrier
	s_waitcnt lgkmcnt(0)
	v_mfma_f32_16x16x32_bf16 v[110:113], v[224:227], v[168:171], v[110:113]
	v_mfma_f32_16x16x32_bf16 v[106:109], v[232:235], v[168:171], v[106:109]
	v_mfma_f32_16x16x32_bf16 v[94:97], v[224:227], v[200:203], v[94:97]
	v_mfma_f32_16x16x32_bf16 v[90:93], v[232:235], v[200:203], v[90:93]
	v_mfma_f32_16x16x32_bf16 v[78:81], v[224:227], v[208:211], v[78:81]
	v_mfma_f32_16x16x32_bf16 v[74:77], v[232:235], v[208:211], v[74:77]
	v_mfma_f32_16x16x32_bf16 v[70:73], v[224:227], v[216:219], v[70:73]
	v_mfma_f32_16x16x32_bf16 v[66:69], v[232:235], v[216:219], v[66:69]
	v_mfma_f32_16x16x32_bf16 v[110:113], v[228:231], v[172:175], v[110:113]
	v_mfma_f32_16x16x32_bf16 v[106:109], v[236:239], v[172:175], v[106:109]
	v_mfma_f32_16x16x32_bf16 v[94:97], v[228:231], v[204:207], v[94:97]
	v_mfma_f32_16x16x32_bf16 v[90:93], v[236:239], v[204:207], v[90:93]
	v_mfma_f32_16x16x32_bf16 v[78:81], v[228:231], v[212:215], v[78:81]
	v_mfma_f32_16x16x32_bf16 v[74:77], v[236:239], v[212:215], v[74:77]
	v_mfma_f32_16x16x32_bf16 v[70:73], v[228:231], v[220:223], v[70:73]
	v_mfma_f32_16x16x32_bf16 v[66:69], v[236:239], v[220:223], v[66:69]
	s_setprio 0
	s_mov_b32 m0, s25
	v_lshl_add_u64 v[182:183], v[240:241], 0, s[86:87]
	s_barrier
	ds_read_b128 v[168:171], v131 offset:49152
	ds_read_b128 v[172:175], v131 offset:50176
	ds_read_b128 v[200:203], v131 offset:51200
	ds_read_b128 v[204:207], v131 offset:52224
	ds_read_b128 v[208:211], v131 offset:53248
	ds_read_b128 v[212:215], v131 offset:54272
	ds_read_b128 v[216:219], v131 offset:55296
	ds_read_b128 v[220:223], v131 offset:56320
	global_load_lds_dwordx4 v[182:183], off
	v_lshl_add_u64 v[182:183], v[242:243], 0, s[86:87]
	s_mov_b32 m0, s26
	s_nop 0
	global_load_lds_dwordx4 v[182:183], off
	s_setprio 1
	s_barrier
; #define PG8_STAGE(bufoff, gbase, voff) do { _Pragma("unroll") for (int _i = 0; _i < 2; ++_i) \
;     __builtin_amdgcn_global_load_lds((const unsigned*)((const char*)(gbase) + (voff)[_i]), (PG8_LAS unsigned*)(lds + (bufoff) + ldsw + _i * 8192), 16, 0, 0); } while (0)
; #define PG8_MMA(ai, bj, At, Bt) do { __builtin_amdgcn_s_setprio(1); _Pragma("unroll") for (int m = 0; m < 4; ++m) _Pragma("unroll") for (int n = 0; n < 2; ++n) _Pragma("unroll") for (int k = 0; k < 2; ++k) \
;     acc[ai][bj][m][n] = __builtin_amdgcn_mfma_f32_16x16x32_bf16(Bt[n][k], At[m][k], acc[ai][bj][m][n], 0, 0, 0); __builtin_amdgcn_s_setprio(0); } while (0)
; #define PG8_WAIT_V(n) asm volatile("s_waitcnt vmcnt(" #n ")" ::: "memory")
; #define PG8_WAIT_L(n) asm volatile("s_waitcnt lgkmcnt(" #n ")" ::: "memory")
; #define PG8_BAR __builtin_amdgcn_s_barrier()
; #define PG8_SCHED __builtin_amdgcn_sched_barrier(0)
; template <class Epi, class Sched>
; __device__ __forceinline__ void gemm_phase(PG8_LAS unsigned char* lds, const int lda, const int ldb, const Sched& S, const Epi& E) {
;     ...
;       PG8_BAR; PG8_WAIT_L(0); PG8_MMA(1, 0, At, B0); PG8_BAR; PG8_SCHED;
;       PG8_STAGE(PG8_SB(1, 1), b3 + hstepB, voffB);
;       PG8_WAIT_V(6); PG8_BAR; PG8_MMA(1, 1, At, B1); PG8_BAR;
;     }
	s_waitcnt lgkmcnt(0)
	v_mfma_f32_16x16x32_bf16 v[62:65], v[152:155], v[168:171], v[62:65]
	v_mfma_f32_16x16x32_bf16 v[58:61], v[160:163], v[168:171], v[58:61]
	v_mfma_f32_16x16x32_bf16 v[54:57], v[152:155], v[200:203], v[54:57]
	v_mfma_f32_16x16x32_bf16 v[46:49], v[160:163], v[200:203], v[46:49]
	v_mfma_f32_16x16x32_bf16 v[38:41], v[152:155], v[208:211], v[38:41]
	v_mfma_f32_16x16x32_bf16 v[34:37], v[160:163], v[208:211], v[34:37]
	v_mfma_f32_16x16x32_bf16 v[22:25], v[152:155], v[216:219], v[22:25]
	v_mfma_f32_16x16x32_bf16 v[18:21], v[160:163], v[216:219], v[18:21]
	v_mfma_f32_16x16x32_bf16 v[62:65], v[156:159], v[172:175], v[62:65]
	v_mfma_f32_16x16x32_bf16 v[58:61], v[164:167], v[172:175], v[58:61]
	v_mfma_f32_16x16x32_bf16 v[54:57], v[156:159], v[204:207], v[54:57]
	v_mfma_f32_16x16x32_bf16 v[46:49], v[164:167], v[204:207], v[46:49]
	v_mfma_f32_16x16x32_bf16 v[38:41], v[156:159], v[212:215], v[38:41]
	v_mfma_f32_16x16x32_bf16 v[34:37], v[164:167], v[212:215], v[34:37]
	v_mfma_f32_16x16x32_bf16 v[22:25], v[156:159], v[220:223], v[22:25]
	v_mfma_f32_16x16x32_bf16 v[18:21], v[164:167], v[220:223], v[18:21]
	s_setprio 0
	s_barrier
	s_add_u32 s16, s16, 0x100080
	s_addc_u32 s17, s17, 0
	s_add_i32 s18, s18, s20
	v_lshl_add_u64 v[152:153], s[16:17], 0, v[134:135]
	s_mov_b32 m0, s18
	s_nop 0
	global_load_lds_dwordx4 v[152:153], off
	v_lshl_add_u64 v[152:153], s[16:17], 0, v[132:133]
	s_add_i32 m0, s18, 0x2000
	s_nop 0
	global_load_lds_dwordx4 v[152:153], off
	s_waitcnt vmcnt(6)
	s_setprio 1
	s_barrier
	v_mfma_f32_16x16x32_bf16 v[50:53], v[224:227], v[168:171], v[50:53]
	v_mfma_f32_16x16x32_bf16 v[42:45], v[232:235], v[168:171], v[42:45]
	v_mfma_f32_16x16x32_bf16 v[30:33], v[224:227], v[200:203], v[30:33]
	v_mfma_f32_16x16x32_bf16 v[26:29], v[232:235], v[200:203], v[26:29]
	v_mfma_f32_16x16x32_bf16 v[14:17], v[224:227], v[208:211], v[14:17]
	v_mfma_f32_16x16x32_bf16 v[10:13], v[232:235], v[208:211], v[10:13]
	v_mfma_f32_16x16x32_bf16 v[6:9], v[224:227], v[216:219], v[6:9]
	v_mfma_f32_16x16x32_bf16 v[2:5], v[232:235], v[216:219], v[2:5]
	v_mfma_f32_16x16x32_bf16 v[50:53], v[228:231], v[172:175], v[50:53]
	v_mfma_f32_16x16x32_bf16 v[42:45], v[236:239], v[172:175], v[42:45]
	v_mfma_f32_16x16x32_bf16 v[30:33], v[228:231], v[204:207], v[30:33]
	v_mfma_f32_16x16x32_bf16 v[26:29], v[236:239], v[204:207], v[26:29]
	v_mfma_f32_16x16x32_bf16 v[14:17], v[228:231], v[212:215], v[14:17]
	v_mfma_f32_16x16x32_bf16 v[10:13], v[236:239], v[212:215], v[10:13]
	v_mfma_f32_16x16x32_bf16 v[6:9], v[228:231], v[220:223], v[6:9]
	v_mfma_f32_16x16x32_bf16 v[2:5], v[236:239], v[220:223], v[2:5]
	s_setprio 0
	s_add_i32 s34, s34, 2
	s_add_u32 s14, s14, 0x100
	s_addc_u32 s15, s15, 0
	s_add_u32 s30, s30, 0x100
	s_addc_u32 s31, s31, 0
	s_cmp_gt_u32 s34, 61
	s_barrier
	s_cbranch_scc0 .LBB0_1088
; #define PG8_WAIT_V(n) asm volatile("s_waitcnt vmcnt(" #n ")" ::: "memory")
; #define PG8_BAR __builtin_amdgcn_s_barrier()
;   __device__ __forceinline__ int kt(const Unit& u) const { return ((u.pn & 7) < 4) ? 4 : 16; }
; template <class Epi, class Sched>
; __device__ __forceinline__ void gemm_phase(PG8_LAS unsigned char* lds, const int lda, const int ldb, const Sched& S, const Epi& E) {
;     ...
;     E(acc, cur, wr, wc, fr, fq);
;     if (!has_next) break;
; #pragma unroll
;     for (int a = 0; a < 2; ++a)
; #pragma unroll
;       for (int b = 0; b < 2; ++b)
; #pragma unroll
;         for (int m = 0; m < 4; ++m)
; #pragma unroll
;           for (int n = 0; n < 2; ++n) acc[a][b][m][n] = (f32x4){0.f, 0.f, 0.f, 0.f};
;     cur = nxt; cA = nA; cB = nB; ++ui;
;     nt = S.kt(cur);
;   }
;   PG8_WAIT_V(0);
;   if (wr == 0) PG8_BAR;
;   PG8_BAR;
;   __device__ __forceinline__ void operator()(const f32x4 (&acc)[2][2][4][2], const Unit& u, int wr, int wc, int fr, int fq) const {
; #pragma unroll
;     for (int ai = 0; ai < 2; ++ai)
; #pragma unroll
;       for (int m = 0; m < 4; ++m) {
;         const size_t r = (size_t)rowbase + (size_t)u.pn * rows_per_b + u.pm * 256 + ai * 128 + wr * 64 + m * 16 + fr;
; #pragma unroll
;         for (int bj = 0; bj < 2; ++bj)
; #pragma unroll
;           for (int n = 0; n < 2; ++n) {
;             const f32x4 v = acc[ai][bj][m][n];
;             const int c = 256 + bj * 128 + wc * 32 + n * 16 + 4 * fq;
;             uint2 w; w.x = pack2(v[0], v[1]); w.y = pack2(v[2], v[3]);
;             *reinterpret_cast<uint2*>(Y + r * 1024 + c) = w;
;           }
;       }
;   }
	s_lshl_b32 s14, s28, 8
	s_ashr_i32 s15, s14, 31
	s_ashr_i32 s13, s12, 31
	v_lshl_add_u64 v[152:153], v[136:137], 0, s[14:15]
	s_lshl_b64 s[12:13], s[12:13], 22
	v_lshlrev_b64 v[152:153], 11, v[152:153]
	v_lshl_add_u64 v[152:153], v[152:153], 0, s[12:13]
	v_readlane_b32 s12, v253, 54
	v_readlane_b32 s13, v253, 55
	v_mov_b32_e32 v145, v0
	v_cvt_pk_bf16_f32 v109, v108, v109
	v_lshl_add_u64 v[154:155], s[12:13], 0, v[152:153]
	v_lshl_add_u64 v[156:157], v[154:155], 0, v[144:145]
	v_cvt_pk_bf16_f32 v108, v106, v107
	v_or_b32_e32 v106, 0x8000, v152
	v_mov_b32_e32 v107, v153
	s_mov_b64 s[12:13], 0x40000
	v_cvt_pk_bf16_f32 v129, v128, v129
	v_cvt_pk_bf16_f32 v128, v126, v127
	v_cvt_pk_bf16_f32 v125, v124, v125
	v_cvt_pk_bf16_f32 v124, v122, v123
	v_cvt_pk_bf16_f32 v113, v112, v113
	v_cvt_pk_bf16_f32 v112, v110, v111
	global_store_dwordx2 v[156:157], v[108:109], off offset:800
	v_lshl_add_u64 v[106:107], v[138:139], 0, v[106:107]
	v_cvt_pk_bf16_f32 v109, v120, v121
	v_cvt_pk_bf16_f32 v108, v118, v119
	v_cvt_pk_bf16_f32 v93, v92, v93
	v_cvt_pk_bf16_f32 v92, v90, v91
	v_or_b32_e32 v90, 0x10000, v152
	v_mov_b32_e32 v91, v153
	v_cvt_pk_bf16_f32 v69, v68, v69
	v_cvt_pk_bf16_f32 v68, v66, v67
	v_lshl_add_u64 v[66:67], v[154:155], 0, s[12:13]
	s_mov_b64 s[12:13], 0x48000
	global_store_dwordx2 v[156:157], v[128:129], off offset:512
	global_store_dwordx2 v[156:157], v[124:125], off offset:544
	global_store_dwordx2 v[156:157], v[112:113], off offset:768
	global_store_dwordx2 v[106:107], v[108:109], off offset:512
	v_cvt_pk_bf16_f32 v109, v116, v117
	v_cvt_pk_bf16_f32 v108, v114, v115
	v_cvt_pk_bf16_f32 v97, v96, v97
	v_cvt_pk_bf16_f32 v96, v94, v95
	global_store_dwordx2 v[106:107], v[92:93], off offset:800
	v_lshl_add_u64 v[90:91], v[138:139], 0, v[90:91]
	v_cvt_pk_bf16_f32 v93, v104, v105
	v_cvt_pk_bf16_f32 v92, v102, v103
	v_cvt_pk_bf16_f32 v77, v76, v77
	v_cvt_pk_bf16_f32 v76, v74, v75
	v_or_b32_e32 v152, 0x18000, v152
	v_cvt_pk_bf16_f32 v45, v44, v45
	v_cvt_pk_bf16_f32 v44, v42, v43
	v_lshl_add_u64 v[42:43], v[154:155], 0, s[12:13]
	s_mov_b64 s[12:13], 0x50000
	global_store_dwordx2 v[106:107], v[108:109], off offset:544
	global_store_dwordx2 v[106:107], v[96:97], off offset:768
	global_store_dwordx2 v[90:91], v[92:93], off offset:512
	v_cvt_pk_bf16_f32 v93, v100, v101
	v_cvt_pk_bf16_f32 v92, v98, v99
	v_cvt_pk_bf16_f32 v81, v80, v81
	v_cvt_pk_bf16_f32 v80, v78, v79
	global_store_dwordx2 v[90:91], v[76:77], off offset:800
	v_lshl_add_u64 v[74:75], v[138:139], 0, v[152:153]
	v_cvt_pk_bf16_f32 v77, v88, v89
	v_cvt_pk_bf16_f32 v76, v86, v87
	v_mov_b32_e32 v151, v0
	v_cvt_pk_bf16_f32 v29, v28, v29
	v_cvt_pk_bf16_f32 v28, v26, v27
	v_lshl_add_u64 v[26:27], v[154:155], 0, s[12:13]
	s_mov_b64 s[12:13], 0x58000
	global_store_dwordx2 v[90:91], v[92:93], off offset:544
	global_store_dwordx2 v[90:91], v[80:81], off offset:768
	global_store_dwordx2 v[74:75], v[76:77], off offset:512
	v_cvt_pk_bf16_f32 v77, v84, v85
	v_cvt_pk_bf16_f32 v76, v82, v83
	v_cvt_pk_bf16_f32 v73, v72, v73
	v_cvt_pk_bf16_f32 v72, v70, v71
	v_cvt_pk_bf16_f32 v53, v52, v53
	v_cvt_pk_bf16_f32 v52, v50, v51
	v_lshl_add_u64 v[50:51], v[66:67], 0, v[150:151]
	v_cvt_pk_bf16_f32 v33, v32, v33
	v_cvt_pk_bf16_f32 v32, v30, v31
	v_lshl_add_u64 v[30:31], v[42:43], 0, v[150:151]
	v_cvt_pk_bf16_f32 v17, v16, v17
	v_cvt_pk_bf16_f32 v16, v14, v15
	v_lshl_add_u64 v[14:15], v[26:27], 0, v[150:151]
	v_cvt_pk_bf16_f32 v13, v12, v13
	v_cvt_pk_bf16_f32 v12, v10, v11
	v_lshl_add_u64 v[10:11], v[154:155], 0, s[12:13]
	global_store_dwordx2 v[74:75], v[76:77], off offset:544
	global_store_dwordx2 v[74:75], v[72:73], off offset:768
	global_store_dwordx2 v[74:75], v[68:69], off offset:800
	v_mov_b32_e32 v147, v0
	global_store_dwordx2 v[50:51], v[44:45], off offset:512
	v_lshl_add_u64 v[44:45], v[42:43], 0, v[144:145]
	v_cvt_pk_bf16_f32 v51, v56, v57
	v_cvt_pk_bf16_f32 v50, v54, v55
	global_store_dwordx2 v[30:31], v[28:29], off offset:512
	v_lshl_add_u64 v[28:29], v[26:27], 0, v[144:145]
	v_cvt_pk_bf16_f32 v31, v40, v41
	v_cvt_pk_bf16_f32 v30, v38, v39
	global_store_dwordx2 v[14:15], v[12:13], off offset:512
	v_lshl_add_u64 v[12:13], v[10:11], 0, v[144:145]
	v_cvt_pk_bf16_f32 v15, v24, v25
	v_cvt_pk_bf16_f32 v14, v22, v23
	v_mov_b32_e32 v149, v0
	global_store_dwordx2 v[44:45], v[50:51], off offset:512
	v_lshl_add_u64 v[44:45], v[42:43], 0, v[146:147]
	v_cvt_pk_bf16_f32 v49, v48, v49
	v_cvt_pk_bf16_f32 v48, v46, v47
	global_store_dwordx2 v[28:29], v[30:31], off offset:512
	v_lshl_add_u64 v[28:29], v[26:27], 0, v[146:147]
	v_cvt_pk_bf16_f32 v31, v36, v37
	v_cvt_pk_bf16_f32 v30, v34, v35
	global_store_dwordx2 v[12:13], v[14:15], off offset:512
	v_lshl_add_u64 v[12:13], v[10:11], 0, v[146:147]
	v_cvt_pk_bf16_f32 v15, v20, v21
	v_cvt_pk_bf16_f32 v14, v18, v19
	v_lshl_add_u64 v[68:69], v[66:67], 0, v[144:145]
	v_cvt_pk_bf16_f32 v65, v64, v65
	v_cvt_pk_bf16_f32 v64, v62, v63
	v_lshl_add_u64 v[62:63], v[66:67], 0, v[146:147]
	v_cvt_pk_bf16_f32 v61, v60, v61
	v_cvt_pk_bf16_f32 v60, v58, v59
	v_lshl_add_u64 v[58:59], v[66:67], 0, v[148:149]
	global_store_dwordx2 v[44:45], v[48:49], off offset:512
	v_lshl_add_u64 v[44:45], v[42:43], 0, v[148:149]
	global_store_dwordx2 v[28:29], v[30:31], off offset:512
	v_lshl_add_u64 v[28:29], v[26:27], 0, v[148:149]
	global_store_dwordx2 v[12:13], v[14:15], off offset:512
	v_lshl_add_u64 v[12:13], v[10:11], 0, v[148:149]
	v_cvt_pk_bf16_f32 v9, v8, v9
	v_cvt_pk_bf16_f32 v8, v6, v7
	v_lshl_add_u64 v[6:7], v[10:11], 0, v[150:151]
	v_cvt_pk_bf16_f32 v5, v4, v5
	v_cvt_pk_bf16_f32 v4, v2, v3
	s_and_b64 vcc, exec, s[4:5]
	s_mov_b32 s12, s0
	s_mov_b32 s28, s6
	s_mov_b64 s[16:17], s[10:11]
	s_mov_b64 s[14:15], s[8:9]
	global_store_dwordx2 v[68:69], v[64:65], off offset:512
	global_store_dwordx2 v[62:63], v[60:61], off offset:512
	global_store_dwordx2 v[58:59], v[52:53], off offset:512
	global_store_dwordx2 v[44:45], v[32:33], off offset:512
	global_store_dwordx2 v[28:29], v[16:17], off offset:512
	global_store_dwordx2 v[12:13], v[8:9], off offset:512
	global_store_dwordx2 v[6:7], v[4:5], off offset:512
	s_cbranch_vccz .LBB0_1081
	s_waitcnt vmcnt(0)
	s_cmpk_gt_u32 s2, 0xff
	s_movk_i32 s21, 0x210
	s_mov_b32 s26, 0x2aaaaaab
	s_movk_i32 s27, 0xff40
	s_cbranch_scc1 .LBB0_1092
	s_barrier

; #define PG8_STAGE(bufoff, gbase, voff) do { _Pragma("unroll") for (int _i = 0; _i < 2; ++_i) \
;     __builtin_amdgcn_global_load_lds((const unsigned*)((const char*)(gbase) + (voff)[_i]), (PG8_LAS unsigned*)(lds + (bufoff) + ldsw + _i * 8192), 16, 0, 0); } while (0)
; #define PG8_LDA(dst, b, h) do { _Pragma("unroll") for (int m = 0; m < 4; ++m) _Pragma("unroll") for (int k = 0; k < 2; ++k) dst[m][k] = *(const PG8_LAS bf16x8*)(lds + PG8_SA(b, h) + aoff + m * 2048 + k * 1024); } while (0)
; #define PG8_LDB(dst, b, h) do { _Pragma("unroll") for (int n = 0; n < 2; ++n) _Pragma("unroll") for (int k = 0; k < 2; ++k) dst[n][k] = *(const PG8_LAS bf16x8*)(lds + PG8_SB(b, h) + boff + n * 2048 + k * 1024); } while (0)
; #define PG8_MMA(ai, bj, At, Bt) do { __builtin_amdgcn_s_setprio(1); _Pragma("unroll") for (int m = 0; m < 4; ++m) _Pragma("unroll") for (int n = 0; n < 2; ++n) _Pragma("unroll") for (int k = 0; k < 2; ++k) \
;     acc[ai][bj][m][n] = __builtin_amdgcn_mfma_f32_16x16x32_bf16(Bt[n][k], At[m][k], acc[ai][bj][m][n], 0, 0, 0); __builtin_amdgcn_s_setprio(0); } while (0)
; #define PG8_WAIT_L(n) asm volatile("s_waitcnt lgkmcnt(" #n ")" ::: "memory")
; #define PG8_BAR __builtin_amdgcn_s_barrier()
; #define PG8_SCHED __builtin_amdgcn_sched_barrier(0)
; template <class Epi, class Sched>
; __device__ __forceinline__ void gemm_phase(PG8_LAS unsigned char* lds, const int lda, const int ldb, const Sched& S, const Epi& E) {
;     ...
;     for (int t = 0; t < nt; t += 2) {
;       const bool last = (t == nt - 2);
;       const char* a1 = cA + (size_t)(t + 1) * kstep;
;       const char* a2 = last ? nA : cA + (size_t)(t + 2) * kstep; const char* b2 = last ? nB : cB + (size_t)(t + 2) * kstep;
;       const char* a3 = a2 + kstep; const char* b3 = b2 + kstep;
;       PG8_LDB(B0, 0, 0); PG8_SCHED; PG8_LDA(At, 0, 0); PG8_STAGE(PG8_SA(1, 1), a1 + hstepA, voffA);
;       PG8_WAIT_L(8); PG8_BAR; PG8_WAIT_L(0); PG8_MMA(0, 0, At, B0); PG8_BAR; PG8_SCHED;
;       PG8_LDB(B1, 0, 1); PG8_STAGE(PG8_SB(0, 0), b2, voffB);
;       PG8_BAR; PG8_WAIT_L(0); PG8_MMA(0, 1, At, B1); PG8_BAR;
;       PG8_LDA(At, 0, 1); PG8_STAGE(PG8_SA(0, 0), a2, voffA);
;       PG8_BAR; PG8_WAIT_L(0); PG8_MMA(1, 0, At, B0); PG8_BAR; PG8_SCHED;
.LBB0_1412:
	s_add_i32 s33, s18, 2
	s_add_u32 s19, s14, 0xfffc0080
	s_addc_u32 s20, s15, -1
	s_add_i32 s44, 0, 0x10000
	v_add_u32_e32 v152, s44, v131
	ds_read_b128 v[140:143], v152
	ds_read_b128 v[144:147], v152 offset:1024
	ds_read_b128 v[148:151], v152 offset:2048
	ds_read_b128 v[152:155], v152 offset:3072
	s_cmp_eq_u32 s11, s18
	s_cselect_b32 s18, s12, s22
	s_cselect_b32 s21, s7, s20
	s_cselect_b32 s20, s6, s19
	s_cselect_b32 s19, s13, s23
	v_lshl_add_u64 v[182:183], s[14:15], 0, v[136:137]
	s_add_i32 m0, s17, 0xc000
	ds_read_b128 v[156:159], v201
	ds_read_b128 v[160:163], v201 offset:1024
	ds_read_b128 v[164:167], v201 offset:2048
	ds_read_b128 v[168:171], v201 offset:3072
	ds_read_b128 v[172:175], v201 offset:4096
	ds_read_b128 v[202:205], v201 offset:5120
	ds_read_b128 v[206:209], v201 offset:6144
	ds_read_b128 v[210:213], v201 offset:7168
	global_load_lds_dwordx4 v[182:183], off
	v_lshl_add_u64 v[182:183], s[14:15], 0, v[138:139]
	s_add_i32 m0, s17, 0xe000
	s_nop 0
	global_load_lds_dwordx4 v[182:183], off
	s_waitcnt lgkmcnt(8)
	s_setprio 1
	s_barrier
	s_waitcnt lgkmcnt(0)
	v_mfma_f32_16x16x32_bf16 v[126:129], v[140:143], v[156:159], v[126:129]
	v_mfma_f32_16x16x32_bf16 v[122:125], v[148:151], v[156:159], v[122:125]
	v_mfma_f32_16x16x32_bf16 v[118:121], v[140:143], v[164:167], v[118:121]
	v_mfma_f32_16x16x32_bf16 v[114:117], v[148:151], v[164:167], v[114:117]
	v_mfma_f32_16x16x32_bf16 v[110:113], v[140:143], v[172:175], v[110:113]
	v_mfma_f32_16x16x32_bf16 v[106:109], v[148:151], v[172:175], v[106:109]
	v_mfma_f32_16x16x32_bf16 v[102:105], v[140:143], v[206:209], v[102:105]
	v_mfma_f32_16x16x32_bf16 v[98:101], v[148:151], v[206:209], v[98:101]
	v_mfma_f32_16x16x32_bf16 v[126:129], v[144:147], v[160:163], v[126:129]
	v_mfma_f32_16x16x32_bf16 v[122:125], v[152:155], v[160:163], v[122:125]
	v_mfma_f32_16x16x32_bf16 v[118:121], v[144:147], v[168:171], v[118:121]
	v_mfma_f32_16x16x32_bf16 v[114:117], v[152:155], v[168:171], v[114:117]
	v_mfma_f32_16x16x32_bf16 v[110:113], v[144:147], v[202:205], v[110:113]
	v_mfma_f32_16x16x32_bf16 v[106:109], v[152:155], v[202:205], v[106:109]
	v_mfma_f32_16x16x32_bf16 v[102:105], v[144:147], v[210:213], v[102:105]
	v_mfma_f32_16x16x32_bf16 v[98:101], v[152:155], v[210:213], v[98:101]
	s_setprio 0
	s_barrier
	s_add_i32 s46, 0, 0x14000
	v_add_u32_e32 v182, s46, v131
	s_add_i32 s44, s44, s29
	ds_read_b128 v[214:217], v182
	ds_read_b128 v[218:221], v182 offset:1024
	ds_read_b128 v[222:225], v182 offset:2048
	ds_read_b128 v[226:229], v182 offset:3072
	v_lshl_add_u64 v[182:183], s[18:19], 0, v[134:135]
	s_mov_b32 m0, s44
	v_lshl_add_u64 v[184:185], s[18:19], 0, v[132:133]
	global_load_lds_dwordx4 v[182:183], off
	s_add_i32 m0, s44, 0x2000
	s_nop 0
	global_load_lds_dwordx4 v[184:185], off
	s_setprio 1
	s_barrier
	s_waitcnt lgkmcnt(0)
	v_mfma_f32_16x16x32_bf16 v[94:97], v[214:217], v[156:159], v[94:97]
	v_mfma_f32_16x16x32_bf16 v[90:93], v[222:225], v[156:159], v[90:93]
	v_mfma_f32_16x16x32_bf16 v[86:89], v[214:217], v[164:167], v[86:89]
	v_mfma_f32_16x16x32_bf16 v[82:85], v[222:225], v[164:167], v[82:85]
	v_mfma_f32_16x16x32_bf16 v[78:81], v[214:217], v[172:175], v[78:81]
	v_mfma_f32_16x16x32_bf16 v[74:77], v[222:225], v[172:175], v[74:77]
	v_mfma_f32_16x16x32_bf16 v[70:73], v[214:217], v[206:209], v[70:73]
	v_mfma_f32_16x16x32_bf16 v[66:69], v[222:225], v[206:209], v[66:69]
	v_mfma_f32_16x16x32_bf16 v[94:97], v[218:221], v[160:163], v[94:97]
	v_mfma_f32_16x16x32_bf16 v[90:93], v[226:229], v[160:163], v[90:93]
	v_mfma_f32_16x16x32_bf16 v[86:89], v[218:221], v[168:171], v[86:89]
	v_mfma_f32_16x16x32_bf16 v[82:85], v[226:229], v[168:171], v[82:85]
	v_mfma_f32_16x16x32_bf16 v[78:81], v[218:221], v[202:205], v[78:81]
	v_mfma_f32_16x16x32_bf16 v[74:77], v[226:229], v[202:205], v[74:77]
	v_mfma_f32_16x16x32_bf16 v[70:73], v[218:221], v[210:213], v[70:73]
	v_mfma_f32_16x16x32_bf16 v[66:69], v[226:229], v[210:213], v[66:69]
	s_setprio 0
	s_mov_b32 m0, s17
	v_lshl_add_u64 v[230:231], s[20:21], 0, v[134:135]
	s_barrier
	ds_read_b128 v[156:159], v201 offset:16384
	ds_read_b128 v[160:163], v201 offset:17408
	ds_read_b128 v[164:167], v201 offset:18432
	ds_read_b128 v[168:171], v201 offset:19456
	ds_read_b128 v[172:175], v201 offset:20480
	ds_read_b128 v[202:205], v201 offset:21504
	ds_read_b128 v[206:209], v201 offset:22528
	ds_read_b128 v[210:213], v201 offset:23552
	global_load_lds_dwordx4 v[230:231], off
	v_lshl_add_u64 v[232:233], s[20:21], 0, v[132:133]
	s_mov_b32 m0, s34
	s_nop 0
	global_load_lds_dwordx4 v[232:233], off
	s_setprio 1
	s_barrier
	s_waitcnt lgkmcnt(0)
	v_mfma_f32_16x16x32_bf16 v[62:65], v[140:143], v[156:159], v[62:65]
	v_mfma_f32_16x16x32_bf16 v[58:61], v[148:151], v[156:159], v[58:61]
	v_mfma_f32_16x16x32_bf16 v[54:57], v[140:143], v[164:167], v[54:57]
	v_mfma_f32_16x16x32_bf16 v[50:53], v[148:151], v[164:167], v[50:53]
	v_mfma_f32_16x16x32_bf16 v[46:49], v[140:143], v[172:175], v[46:49]
	v_mfma_f32_16x16x32_bf16 v[42:45], v[148:151], v[172:175], v[42:45]
	v_mfma_f32_16x16x32_bf16 v[38:41], v[140:143], v[206:209], v[38:41]
	v_mfma_f32_16x16x32_bf16 v[34:37], v[148:151], v[206:209], v[34:37]
	v_mfma_f32_16x16x32_bf16 v[62:65], v[144:147], v[160:163], v[62:65]
	v_mfma_f32_16x16x32_bf16 v[58:61], v[152:155], v[160:163], v[58:61]
	v_mfma_f32_16x16x32_bf16 v[54:57], v[144:147], v[168:171], v[54:57]
	v_mfma_f32_16x16x32_bf16 v[50:53], v[152:155], v[168:171], v[50:53]
	v_mfma_f32_16x16x32_bf16 v[46:49], v[144:147], v[202:205], v[46:49]
	v_mfma_f32_16x16x32_bf16 v[42:45], v[152:155], v[202:205], v[42:45]
	v_mfma_f32_16x16x32_bf16 v[38:41], v[144:147], v[210:213], v[38:41]
	v_mfma_f32_16x16x32_bf16 v[34:37], v[152:155], v[210:213], v[34:37]
	s_setprio 0
	s_barrier
; #define PG8_STAGE(bufoff, gbase, voff) do { _Pragma("unroll") for (int _i = 0; _i < 2; ++_i) \
;     __builtin_amdgcn_global_load_lds((const unsigned*)((const char*)(gbase) + (voff)[_i]), (PG8_LAS unsigned*)(lds + (bufoff) + ldsw + _i * 8192), 16, 0, 0); } while (0)
; #define PG8_LDA(dst, b, h) do { _Pragma("unroll") for (int m = 0; m < 4; ++m) _Pragma("unroll") for (int k = 0; k < 2; ++k) dst[m][k] = *(const PG8_LAS bf16x8*)(lds + PG8_SA(b, h) + aoff + m * 2048 + k * 1024); } while (0)
; #define PG8_LDB(dst, b, h) do { _Pragma("unroll") for (int n = 0; n < 2; ++n) _Pragma("unroll") for (int k = 0; k < 2; ++k) dst[n][k] = *(const PG8_LAS bf16x8*)(lds + PG8_SB(b, h) + boff + n * 2048 + k * 1024); } while (0)
; #define PG8_MMA(ai, bj, At, Bt) do { __builtin_amdgcn_s_setprio(1); _Pragma("unroll") for (int m = 0; m < 4; ++m) _Pragma("unroll") for (int n = 0; n < 2; ++n) _Pragma("unroll") for (int k = 0; k < 2; ++k) \
;     acc[ai][bj][m][n] = __builtin_amdgcn_mfma_f32_16x16x32_bf16(Bt[n][k], At[m][k], acc[ai][bj][m][n], 0, 0, 0); __builtin_amdgcn_s_setprio(0); } while (0)
; #define PG8_WAIT_V(n) asm volatile("s_waitcnt vmcnt(" #n ")" ::: "memory")
; #define PG8_WAIT_L(n) asm volatile("s_waitcnt lgkmcnt(" #n ")" ::: "memory")
; #define PG8_BAR __builtin_amdgcn_s_barrier()
; #define PG8_SCHED __builtin_amdgcn_sched_barrier(0)
; template <class Epi, class Sched>
; __device__ __forceinline__ void gemm_phase(PG8_LAS unsigned char* lds, const int lda, const int ldb, const Sched& S, const Epi& E) {
;     ...
;       PG8_STAGE(PG8_SB(0, 1), b2 + hstepB, voffB);
;       PG8_WAIT_V(6); PG8_BAR; PG8_MMA(1, 1, At, B1); PG8_BAR;
;       PG8_LDB(B0, 1, 0); PG8_SCHED; PG8_LDA(At, 1, 0); PG8_STAGE(PG8_SA(0, 1), a2 + hstepA, voffA);
;       PG8_WAIT_L(8); PG8_BAR; PG8_WAIT_L(0); PG8_MMA(0, 0, At, B0); PG8_BAR; PG8_SCHED;
;       PG8_LDB(B1, 1, 1); PG8_STAGE(PG8_SB(1, 0), b3, voffB);
;       PG8_BAR; PG8_WAIT_L(0); PG8_MMA(0, 1, At, B1); PG8_BAR;
;       PG8_LDA(At, 1, 1); PG8_STAGE(PG8_SA(1, 0), a3, voffA);
;       PG8_BAR; PG8_WAIT_L(0); PG8_MMA(1, 0, At, B0); PG8_BAR; PG8_SCHED;
	s_add_u32 s44, s18, 0x40000
	s_addc_u32 s45, s19, 0
	s_add_i32 s46, s46, s29
	v_lshl_add_u64 v[140:141], s[44:45], 0, v[134:135]
	s_mov_b32 m0, s46
	s_nop 0
	global_load_lds_dwordx4 v[140:141], off
	v_lshl_add_u64 v[140:141], s[44:45], 0, v[132:133]
	s_add_i32 m0, s46, 0x2000
	s_nop 0
	global_load_lds_dwordx4 v[140:141], off
	s_waitcnt vmcnt(6)
	s_setprio 1
	s_barrier
	v_mfma_f32_16x16x32_bf16 v[30:33], v[214:217], v[156:159], v[30:33]
	v_mfma_f32_16x16x32_bf16 v[26:29], v[222:225], v[156:159], v[26:29]
	v_mfma_f32_16x16x32_bf16 v[22:25], v[214:217], v[164:167], v[22:25]
	v_mfma_f32_16x16x32_bf16 v[18:21], v[222:225], v[164:167], v[18:21]
	v_mfma_f32_16x16x32_bf16 v[14:17], v[214:217], v[172:175], v[14:17]
	v_mfma_f32_16x16x32_bf16 v[10:13], v[222:225], v[172:175], v[10:13]
	v_mfma_f32_16x16x32_bf16 v[6:9], v[214:217], v[206:209], v[6:9]
	v_mfma_f32_16x16x32_bf16 v[2:5], v[222:225], v[206:209], v[2:5]
	v_mfma_f32_16x16x32_bf16 v[30:33], v[218:221], v[160:163], v[30:33]
	v_mfma_f32_16x16x32_bf16 v[26:29], v[226:229], v[160:163], v[26:29]
	v_mfma_f32_16x16x32_bf16 v[22:25], v[218:221], v[168:171], v[22:25]
	v_mfma_f32_16x16x32_bf16 v[18:21], v[226:229], v[168:171], v[18:21]
	v_mfma_f32_16x16x32_bf16 v[14:17], v[218:221], v[202:205], v[14:17]
	v_mfma_f32_16x16x32_bf16 v[10:13], v[226:229], v[202:205], v[10:13]
	v_mfma_f32_16x16x32_bf16 v[6:9], v[218:221], v[210:213], v[6:9]
	v_mfma_f32_16x16x32_bf16 v[2:5], v[226:229], v[210:213], v[2:5]
	s_setprio 0
	s_add_i32 s44, 0, 0x18000
	v_add_u32_e32 v152, s44, v131
	s_barrier
	ds_read_b128 v[140:143], v152
	ds_read_b128 v[144:147], v152 offset:1024
	ds_read_b128 v[148:151], v152 offset:2048
	ds_read_b128 v[152:155], v152 offset:3072
	s_add_u32 s20, s20, 0x40000
	s_addc_u32 s21, s21, 0
	s_mov_b32 m0, s35
	v_lshl_add_u64 v[214:215], s[20:21], 0, v[134:135]
	ds_read_b128 v[156:159], v201 offset:32768
	ds_read_b128 v[160:163], v201 offset:33792
	ds_read_b128 v[164:167], v201 offset:34816
	ds_read_b128 v[168:171], v201 offset:35840
	ds_read_b128 v[172:175], v201 offset:36864
	ds_read_b128 v[202:205], v201 offset:37888
	ds_read_b128 v[206:209], v201 offset:38912
	ds_read_b128 v[210:213], v201 offset:39936
	global_load_lds_dwordx4 v[214:215], off
	v_lshl_add_u64 v[214:215], s[20:21], 0, v[132:133]
	s_mov_b32 m0, s36
	s_nop 0
	global_load_lds_dwordx4 v[214:215], off
	s_waitcnt lgkmcnt(8)
	s_setprio 1
	s_barrier
	s_waitcnt lgkmcnt(0)
	v_mfma_f32_16x16x32_bf16 v[126:129], v[140:143], v[156:159], v[126:129]
	v_mfma_f32_16x16x32_bf16 v[122:125], v[148:151], v[156:159], v[122:125]
	v_mfma_f32_16x16x32_bf16 v[118:121], v[140:143], v[164:167], v[118:121]
	v_mfma_f32_16x16x32_bf16 v[114:117], v[148:151], v[164:167], v[114:117]
	v_mfma_f32_16x16x32_bf16 v[110:113], v[140:143], v[172:175], v[110:113]
	v_mfma_f32_16x16x32_bf16 v[106:109], v[148:151], v[172:175], v[106:109]
	v_mfma_f32_16x16x32_bf16 v[102:105], v[140:143], v[206:209], v[102:105]
	v_mfma_f32_16x16x32_bf16 v[98:101], v[148:151], v[206:209], v[98:101]
	v_mfma_f32_16x16x32_bf16 v[126:129], v[144:147], v[160:163], v[126:129]
	v_mfma_f32_16x16x32_bf16 v[122:125], v[152:155], v[160:163], v[122:125]
	v_mfma_f32_16x16x32_bf16 v[118:121], v[144:147], v[168:171], v[118:121]
	v_mfma_f32_16x16x32_bf16 v[114:117], v[152:155], v[168:171], v[114:117]
	v_mfma_f32_16x16x32_bf16 v[110:113], v[144:147], v[202:205], v[110:113]
	v_mfma_f32_16x16x32_bf16 v[106:109], v[152:155], v[202:205], v[106:109]
	v_mfma_f32_16x16x32_bf16 v[102:105], v[144:147], v[210:213], v[102:105]
	v_mfma_f32_16x16x32_bf16 v[98:101], v[152:155], v[210:213], v[98:101]
	s_setprio 0
	s_barrier
	s_add_i32 s20, 0, 0x1c000
	s_add_i32 s21, s44, s29
	v_add_u32_e32 v226, s20, v131
	v_lshl_add_u64 v[182:183], v[182:183], 0, s[86:87]
	s_mov_b32 m0, s21
	ds_read_b128 v[214:217], v226
	ds_read_b128 v[218:221], v226 offset:1024
	ds_read_b128 v[222:225], v226 offset:2048
	ds_read_b128 v[226:229], v226 offset:3072
	global_load_lds_dwordx4 v[182:183], off
	v_lshl_add_u64 v[182:183], v[184:185], 0, s[86:87]
	s_add_i32 m0, s21, 0x2000
	s_nop 0
	global_load_lds_dwordx4 v[182:183], off
	s_setprio 1
	s_barrier
; __device__ __forceinline__ int tid_l() { int t = threadIdx.x; asm volatile("" : "+v"(t)); return t; }
; #define PG8_STAGE(bufoff, gbase, voff) do { _Pragma("unroll") for (int _i = 0; _i < 2; ++_i) \
;     __builtin_amdgcn_global_load_lds((const unsigned*)((const char*)(gbase) + (voff)[_i]), (PG8_LAS unsigned*)(lds + (bufoff) + ldsw + _i * 8192), 16, 0, 0); } while (0)
; #define PG8_MMA(ai, bj, At, Bt) do { __builtin_amdgcn_s_setprio(1); _Pragma("unroll") for (int m = 0; m < 4; ++m) _Pragma("unroll") for (int n = 0; n < 2; ++n) _Pragma("unroll") for (int k = 0; k < 2; ++k) \
;     acc[ai][bj][m][n] = __builtin_amdgcn_mfma_f32_16x16x32_bf16(Bt[n][k], At[m][k], acc[ai][bj][m][n], 0, 0, 0); __builtin_amdgcn_s_setprio(0); } while (0)
; #define PG8_WAIT_V(n) asm volatile("s_waitcnt vmcnt(" #n ")" ::: "memory")
; #define PG8_WAIT_L(n) asm volatile("s_waitcnt lgkmcnt(" #n ")" ::: "memory")
; #define PG8_BAR __builtin_amdgcn_s_barrier()
; #define PG8_SCHED __builtin_amdgcn_sched_barrier(0)
; template <class Epi, class Sched>
; __device__ __forceinline__ void gemm_phase(PG8_LAS unsigned char* lds, const int lda, const int ldb, const Sched& S, const Epi& E) {
;     ...
;       PG8_BAR; PG8_WAIT_L(0); PG8_MMA(1, 0, At, B0); PG8_BAR; PG8_SCHED;
;       PG8_STAGE(PG8_SB(1, 1), b3 + hstepB, voffB);
;       PG8_WAIT_V(6); PG8_BAR; PG8_MMA(1, 1, At, B1); PG8_BAR;
;     }
;   __device__ __forceinline__ void operator()(const f32x4 (&acc)[2][2][4][2], const Unit& u, int wr, int wc, int fr, int fq) const {
;     const int s = u.pn & 7, dq = u.pn >> 3;
;     const int tid = tid_l();
;     if (s < 4) {
	s_waitcnt lgkmcnt(0)
	v_mfma_f32_16x16x32_bf16 v[94:97], v[214:217], v[156:159], v[94:97]
	v_mfma_f32_16x16x32_bf16 v[90:93], v[222:225], v[156:159], v[90:93]
	v_mfma_f32_16x16x32_bf16 v[86:89], v[214:217], v[164:167], v[86:89]
	v_mfma_f32_16x16x32_bf16 v[82:85], v[222:225], v[164:167], v[82:85]
	v_mfma_f32_16x16x32_bf16 v[78:81], v[214:217], v[172:175], v[78:81]
	v_mfma_f32_16x16x32_bf16 v[74:77], v[222:225], v[172:175], v[74:77]
	v_mfma_f32_16x16x32_bf16 v[70:73], v[214:217], v[206:209], v[70:73]
	v_mfma_f32_16x16x32_bf16 v[66:69], v[222:225], v[206:209], v[66:69]
	v_mfma_f32_16x16x32_bf16 v[94:97], v[218:221], v[160:163], v[94:97]
	v_mfma_f32_16x16x32_bf16 v[90:93], v[226:229], v[160:163], v[90:93]
	v_mfma_f32_16x16x32_bf16 v[86:89], v[218:221], v[168:171], v[86:89]
	v_mfma_f32_16x16x32_bf16 v[82:85], v[226:229], v[168:171], v[82:85]
	v_mfma_f32_16x16x32_bf16 v[78:81], v[218:221], v[202:205], v[78:81]
	v_mfma_f32_16x16x32_bf16 v[74:77], v[226:229], v[202:205], v[74:77]
	v_mfma_f32_16x16x32_bf16 v[70:73], v[218:221], v[210:213], v[70:73]
	v_mfma_f32_16x16x32_bf16 v[66:69], v[226:229], v[210:213], v[66:69]
	s_setprio 0
	s_mov_b32 m0, s39
	v_lshl_add_u64 v[182:183], v[230:231], 0, s[86:87]
	s_barrier
	ds_read_b128 v[156:159], v201 offset:49152
	ds_read_b128 v[160:163], v201 offset:50176
	ds_read_b128 v[164:167], v201 offset:51200
	ds_read_b128 v[168:171], v201 offset:52224
	ds_read_b128 v[172:175], v201 offset:53248
	ds_read_b128 v[202:205], v201 offset:54272
	ds_read_b128 v[206:209], v201 offset:55296
	ds_read_b128 v[210:213], v201 offset:56320
	global_load_lds_dwordx4 v[182:183], off
	v_lshl_add_u64 v[182:183], v[232:233], 0, s[86:87]
	s_mov_b32 m0, s40
	s_nop 0
	global_load_lds_dwordx4 v[182:183], off
	s_setprio 1
	s_barrier
	s_waitcnt lgkmcnt(0)
	v_mfma_f32_16x16x32_bf16 v[62:65], v[140:143], v[156:159], v[62:65]
	v_mfma_f32_16x16x32_bf16 v[58:61], v[148:151], v[156:159], v[58:61]
	v_mfma_f32_16x16x32_bf16 v[54:57], v[140:143], v[164:167], v[54:57]
	v_mfma_f32_16x16x32_bf16 v[50:53], v[148:151], v[164:167], v[50:53]
	v_mfma_f32_16x16x32_bf16 v[46:49], v[140:143], v[172:175], v[46:49]
	v_mfma_f32_16x16x32_bf16 v[42:45], v[148:151], v[172:175], v[42:45]
	v_mfma_f32_16x16x32_bf16 v[38:41], v[140:143], v[206:209], v[38:41]
	v_mfma_f32_16x16x32_bf16 v[34:37], v[148:151], v[206:209], v[34:37]
	v_mfma_f32_16x16x32_bf16 v[62:65], v[144:147], v[160:163], v[62:65]
	v_mfma_f32_16x16x32_bf16 v[58:61], v[152:155], v[160:163], v[58:61]
	v_mfma_f32_16x16x32_bf16 v[54:57], v[144:147], v[168:171], v[54:57]
	v_mfma_f32_16x16x32_bf16 v[50:53], v[152:155], v[168:171], v[50:53]
	v_mfma_f32_16x16x32_bf16 v[46:49], v[144:147], v[202:205], v[46:49]
	v_mfma_f32_16x16x32_bf16 v[42:45], v[152:155], v[202:205], v[42:45]
	v_mfma_f32_16x16x32_bf16 v[38:41], v[144:147], v[210:213], v[38:41]
	v_mfma_f32_16x16x32_bf16 v[34:37], v[152:155], v[210:213], v[34:37]
	s_setprio 0
	s_barrier
	s_add_u32 s18, s18, 0x40080
	s_addc_u32 s19, s19, 0
	s_add_i32 s20, s20, s29
	v_lshl_add_u64 v[140:141], s[18:19], 0, v[134:135]
	s_mov_b32 m0, s20
	s_nop 0
	global_load_lds_dwordx4 v[140:141], off
	v_lshl_add_u64 v[140:141], s[18:19], 0, v[132:133]
	s_add_i32 m0, s20, 0x2000
	s_nop 0
	global_load_lds_dwordx4 v[140:141], off
	s_waitcnt vmcnt(6)
	s_setprio 1
	s_barrier
	v_mfma_f32_16x16x32_bf16 v[30:33], v[214:217], v[156:159], v[30:33]
	v_mfma_f32_16x16x32_bf16 v[26:29], v[222:225], v[156:159], v[26:29]
	v_mfma_f32_16x16x32_bf16 v[22:25], v[214:217], v[164:167], v[22:25]
	v_mfma_f32_16x16x32_bf16 v[18:21], v[222:225], v[164:167], v[18:21]
	v_mfma_f32_16x16x32_bf16 v[14:17], v[214:217], v[172:175], v[14:17]
	v_mfma_f32_16x16x32_bf16 v[10:13], v[222:225], v[172:175], v[10:13]
	v_mfma_f32_16x16x32_bf16 v[6:9], v[214:217], v[206:209], v[6:9]
	v_mfma_f32_16x16x32_bf16 v[2:5], v[222:225], v[206:209], v[2:5]
	v_mfma_f32_16x16x32_bf16 v[30:33], v[218:221], v[160:163], v[30:33]
	v_mfma_f32_16x16x32_bf16 v[26:29], v[226:229], v[160:163], v[26:29]
	v_mfma_f32_16x16x32_bf16 v[22:25], v[218:221], v[168:171], v[22:25]
	v_mfma_f32_16x16x32_bf16 v[18:21], v[226:229], v[168:171], v[18:21]
	v_mfma_f32_16x16x32_bf16 v[14:17], v[218:221], v[202:205], v[14:17]
	v_mfma_f32_16x16x32_bf16 v[10:13], v[226:229], v[202:205], v[10:13]
	v_mfma_f32_16x16x32_bf16 v[6:9], v[218:221], v[210:213], v[6:9]
	v_mfma_f32_16x16x32_bf16 v[2:5], v[226:229], v[210:213], v[2:5]
	s_setprio 0
	s_add_u32 s14, s14, 0x100
	s_addc_u32 s15, s15, 0
	s_add_u32 s22, s22, 0x100
	s_addc_u32 s23, s23, 0
	s_cmp_ge_u32 s33, s43
	s_mov_b32 s18, s33
	s_barrier
	s_cbranch_scc0 .LBB0_1412
	s_and_b32 s11, s2, 7
	v_mov_b32_e32 v140, v176
	s_mov_b64 s[14:15], -1
	s_cmp_gt_u32 s11, 3
	v_ashrrev_i32_e32 v141, 31, v140
	s_cbranch_scc1 .LBB0_1416
	s_andn2_b64 vcc, exec, s[14:15]
	s_cbranch_vccz .LBB0_1417

; #define PG8_STAGE(bufoff, gbase, voff) do { _Pragma("unroll") for (int _i = 0; _i < 2; ++_i) \
;     __builtin_amdgcn_global_load_lds((const unsigned*)((const char*)(gbase) + (voff)[_i]), (PG8_LAS unsigned*)(lds + (bufoff) + ldsw + _i * 8192), 16, 0, 0); } while (0)
; #define PG8_LDA(dst, b, h) do { _Pragma("unroll") for (int m = 0; m < 4; ++m) _Pragma("unroll") for (int k = 0; k < 2; ++k) dst[m][k] = *(const PG8_LAS bf16x8*)(lds + PG8_SA(b, h) + aoff + m * 2048 + k * 1024); } while (0)
; #define PG8_LDB(dst, b, h) do { _Pragma("unroll") for (int n = 0; n < 2; ++n) _Pragma("unroll") for (int k = 0; k < 2; ++k) dst[n][k] = *(const PG8_LAS bf16x8*)(lds + PG8_SB(b, h) + boff + n * 2048 + k * 1024); } while (0)
; #define PG8_MMA(ai, bj, At, Bt) do { __builtin_amdgcn_s_setprio(1); _Pragma("unroll") for (int m = 0; m < 4; ++m) _Pragma("unroll") for (int n = 0; n < 2; ++n) _Pragma("unroll") for (int k = 0; k < 2; ++k) \
;     acc[ai][bj][m][n] = __builtin_amdgcn_mfma_f32_16x16x32_bf16(Bt[n][k], At[m][k], acc[ai][bj][m][n], 0, 0, 0); __builtin_amdgcn_s_setprio(0); } while (0)
; #define PG8_WAIT_L(n) asm volatile("s_waitcnt lgkmcnt(" #n ")" ::: "memory")
; #define PG8_BAR __builtin_amdgcn_s_barrier()
; #define PG8_SCHED __builtin_amdgcn_sched_barrier(0)
; template <class Epi, class Sched>
; __device__ __forceinline__ void gemm_phase(PG8_LAS unsigned char* lds, const int lda, const int ldb, const Sched& S, const Epi& E) {
;     ...
;     for (int t = 0; t < nt; t += 2) {
;       const bool last = (t == nt - 2);
;       const char* a1 = cA + (size_t)(t + 1) * kstep;
;       const char* a2 = last ? nA : cA + (size_t)(t + 2) * kstep; const char* b2 = last ? nB : cB + (size_t)(t + 2) * kstep;
;       const char* a3 = a2 + kstep; const char* b3 = b2 + kstep;
;       PG8_LDB(B0, 0, 0); PG8_SCHED; PG8_LDA(At, 0, 0); PG8_STAGE(PG8_SA(1, 1), a1 + hstepA, voffA);
;       PG8_WAIT_L(8); PG8_BAR; PG8_WAIT_L(0); PG8_MMA(0, 0, At, B0); PG8_BAR; PG8_SCHED;
;       PG8_LDB(B1, 0, 1); PG8_STAGE(PG8_SB(0, 0), b2, voffB);
;       PG8_BAR; PG8_WAIT_L(0); PG8_MMA(0, 1, At, B1); PG8_BAR;
;       PG8_LDA(At, 0, 1); PG8_STAGE(PG8_SA(0, 0), a2, voffA);
;       PG8_BAR; PG8_WAIT_L(0); PG8_MMA(1, 0, At, B0); PG8_BAR; PG8_SCHED;
.LBB0_1482:
	s_add_u32 s20, s18, 0x100
	s_addc_u32 s21, s19, 0
	s_add_i32 s33, 0, 0x10000
	v_add_u32_e32 v154, s33, v131
	ds_read_b128 v[140:143], v154
	ds_read_b128 v[146:149], v154 offset:1024
	ds_read_b128 v[150:153], v154 offset:2048
	ds_read_b128 v[154:157], v154 offset:3072
	s_cmp_eq_u32 s54, 12
	s_cselect_b32 s25, s11, s21
	s_cselect_b32 s24, s50, s20
	s_cselect_b32 s23, s1, s53
	s_cselect_b32 s22, s51, s52
	v_lshl_add_u64 v[174:175], s[18:19], 0, v[136:137]
	s_add_i32 m0, s17, 0xc000
	ds_read_b128 v[158:161], v145
	ds_read_b128 v[162:165], v145 offset:1024
	ds_read_b128 v[166:169], v145 offset:2048
	ds_read_b128 v[170:173], v145 offset:3072
	ds_read_b128 v[200:203], v145 offset:4096
	ds_read_b128 v[204:207], v145 offset:5120
	ds_read_b128 v[208:211], v145 offset:6144
	ds_read_b128 v[212:215], v145 offset:7168
	global_load_lds_dwordx4 v[174:175], off
	v_lshl_add_u64 v[174:175], s[18:19], 0, v[138:139]
	s_add_i32 m0, s17, 0xe000
	s_nop 0
	global_load_lds_dwordx4 v[174:175], off
	s_waitcnt lgkmcnt(8)
	s_setprio 1
	s_barrier
	s_waitcnt lgkmcnt(0)
	v_mfma_f32_16x16x32_bf16 v[126:129], v[140:143], v[158:161], v[126:129]
	v_mfma_f32_16x16x32_bf16 v[122:125], v[150:153], v[158:161], v[122:125]
	v_mfma_f32_16x16x32_bf16 v[110:113], v[140:143], v[166:169], v[110:113]
	v_mfma_f32_16x16x32_bf16 v[106:109], v[150:153], v[166:169], v[106:109]
	v_mfma_f32_16x16x32_bf16 v[94:97], v[140:143], v[200:203], v[94:97]
	v_mfma_f32_16x16x32_bf16 v[90:93], v[150:153], v[200:203], v[90:93]
	v_mfma_f32_16x16x32_bf16 v[78:81], v[140:143], v[208:211], v[78:81]
	v_mfma_f32_16x16x32_bf16 v[74:77], v[150:153], v[208:211], v[74:77]
	v_mfma_f32_16x16x32_bf16 v[126:129], v[146:149], v[162:165], v[126:129]
	v_mfma_f32_16x16x32_bf16 v[122:125], v[154:157], v[162:165], v[122:125]
	v_mfma_f32_16x16x32_bf16 v[110:113], v[146:149], v[170:173], v[110:113]
	v_mfma_f32_16x16x32_bf16 v[106:109], v[154:157], v[170:173], v[106:109]
	v_mfma_f32_16x16x32_bf16 v[94:97], v[146:149], v[204:207], v[94:97]
	v_mfma_f32_16x16x32_bf16 v[90:93], v[154:157], v[204:207], v[90:93]
	v_mfma_f32_16x16x32_bf16 v[78:81], v[146:149], v[212:215], v[78:81]
	v_mfma_f32_16x16x32_bf16 v[74:77], v[154:157], v[212:215], v[74:77]
	s_setprio 0
	s_barrier
	s_add_i32 s55, 0, 0x14000
	v_add_u32_e32 v174, s55, v131
	s_add_i32 s18, s33, s34
	ds_read_b128 v[216:219], v174
	ds_read_b128 v[220:223], v174 offset:1024
	ds_read_b128 v[224:227], v174 offset:2048
	ds_read_b128 v[228:231], v174 offset:3072
	v_lshl_add_u64 v[174:175], s[22:23], 0, v[134:135]
	s_mov_b32 m0, s18
	v_lshl_add_u64 v[182:183], s[22:23], 0, v[132:133]
	global_load_lds_dwordx4 v[174:175], off
	s_add_i32 m0, s18, 0x2000
	s_nop 0
	global_load_lds_dwordx4 v[182:183], off
	s_setprio 1
	s_barrier
	s_waitcnt lgkmcnt(0)
	v_mfma_f32_16x16x32_bf16 v[118:121], v[216:219], v[158:161], v[118:121]
	v_mfma_f32_16x16x32_bf16 v[114:117], v[224:227], v[158:161], v[114:117]
	v_mfma_f32_16x16x32_bf16 v[102:105], v[216:219], v[166:169], v[102:105]
	v_mfma_f32_16x16x32_bf16 v[98:101], v[224:227], v[166:169], v[98:101]
	v_mfma_f32_16x16x32_bf16 v[86:89], v[216:219], v[200:203], v[86:89]
	v_mfma_f32_16x16x32_bf16 v[82:85], v[224:227], v[200:203], v[82:85]
	v_mfma_f32_16x16x32_bf16 v[70:73], v[216:219], v[208:211], v[70:73]
	v_mfma_f32_16x16x32_bf16 v[66:69], v[224:227], v[208:211], v[66:69]
	v_mfma_f32_16x16x32_bf16 v[118:121], v[220:223], v[162:165], v[118:121]
	v_mfma_f32_16x16x32_bf16 v[114:117], v[228:231], v[162:165], v[114:117]
	v_mfma_f32_16x16x32_bf16 v[102:105], v[220:223], v[170:173], v[102:105]
	v_mfma_f32_16x16x32_bf16 v[98:101], v[228:231], v[170:173], v[98:101]
	v_mfma_f32_16x16x32_bf16 v[86:89], v[220:223], v[204:207], v[86:89]
	v_mfma_f32_16x16x32_bf16 v[82:85], v[228:231], v[204:207], v[82:85]
	v_mfma_f32_16x16x32_bf16 v[70:73], v[220:223], v[212:215], v[70:73]
	v_mfma_f32_16x16x32_bf16 v[66:69], v[228:231], v[212:215], v[66:69]
	s_setprio 0
	s_mov_b32 m0, s17
	v_lshl_add_u64 v[184:185], s[24:25], 0, v[134:135]
	s_barrier
	ds_read_b128 v[158:161], v145 offset:16384
	ds_read_b128 v[162:165], v145 offset:17408
	ds_read_b128 v[166:169], v145 offset:18432
	ds_read_b128 v[170:173], v145 offset:19456
	ds_read_b128 v[200:203], v145 offset:20480
	ds_read_b128 v[204:207], v145 offset:21504
	ds_read_b128 v[208:211], v145 offset:22528
	ds_read_b128 v[212:215], v145 offset:23552
	global_load_lds_dwordx4 v[184:185], off
	v_lshl_add_u64 v[232:233], s[24:25], 0, v[132:133]
	s_mov_b32 m0, s37
	s_nop 0
	global_load_lds_dwordx4 v[232:233], off
	s_setprio 1
	s_barrier
	s_waitcnt lgkmcnt(0)
	v_mfma_f32_16x16x32_bf16 v[62:65], v[140:143], v[158:161], v[62:65]
	v_mfma_f32_16x16x32_bf16 v[58:61], v[150:153], v[158:161], v[58:61]
	v_mfma_f32_16x16x32_bf16 v[46:49], v[140:143], v[166:169], v[46:49]
	v_mfma_f32_16x16x32_bf16 v[42:45], v[150:153], v[166:169], v[42:45]
	v_mfma_f32_16x16x32_bf16 v[30:33], v[140:143], v[200:203], v[30:33]
	v_mfma_f32_16x16x32_bf16 v[26:29], v[150:153], v[200:203], v[26:29]
	v_mfma_f32_16x16x32_bf16 v[14:17], v[140:143], v[208:211], v[14:17]
	v_mfma_f32_16x16x32_bf16 v[10:13], v[150:153], v[208:211], v[10:13]
	v_mfma_f32_16x16x32_bf16 v[62:65], v[146:149], v[162:165], v[62:65]
	v_mfma_f32_16x16x32_bf16 v[58:61], v[154:157], v[162:165], v[58:61]
	v_mfma_f32_16x16x32_bf16 v[46:49], v[146:149], v[170:173], v[46:49]
	v_mfma_f32_16x16x32_bf16 v[42:45], v[154:157], v[170:173], v[42:45]
	v_mfma_f32_16x16x32_bf16 v[30:33], v[146:149], v[204:207], v[30:33]
	v_mfma_f32_16x16x32_bf16 v[26:29], v[154:157], v[204:207], v[26:29]
	v_mfma_f32_16x16x32_bf16 v[14:17], v[146:149], v[212:215], v[14:17]
	v_mfma_f32_16x16x32_bf16 v[10:13], v[154:157], v[212:215], v[10:13]
	s_setprio 0
	s_barrier
; #define PG8_STAGE(bufoff, gbase, voff) do { _Pragma("unroll") for (int _i = 0; _i < 2; ++_i) \
;     __builtin_amdgcn_global_load_lds((const unsigned*)((const char*)(gbase) + (voff)[_i]), (PG8_LAS unsigned*)(lds + (bufoff) + ldsw + _i * 8192), 16, 0, 0); } while (0)
; #define PG8_LDA(dst, b, h) do { _Pragma("unroll") for (int m = 0; m < 4; ++m) _Pragma("unroll") for (int k = 0; k < 2; ++k) dst[m][k] = *(const PG8_LAS bf16x8*)(lds + PG8_SA(b, h) + aoff + m * 2048 + k * 1024); } while (0)
; #define PG8_LDB(dst, b, h) do { _Pragma("unroll") for (int n = 0; n < 2; ++n) _Pragma("unroll") for (int k = 0; k < 2; ++k) dst[n][k] = *(const PG8_LAS bf16x8*)(lds + PG8_SB(b, h) + boff + n * 2048 + k * 1024); } while (0)
; #define PG8_MMA(ai, bj, At, Bt) do { __builtin_amdgcn_s_setprio(1); _Pragma("unroll") for (int m = 0; m < 4; ++m) _Pragma("unroll") for (int n = 0; n < 2; ++n) _Pragma("unroll") for (int k = 0; k < 2; ++k) \
;     acc[ai][bj][m][n] = __builtin_amdgcn_mfma_f32_16x16x32_bf16(Bt[n][k], At[m][k], acc[ai][bj][m][n], 0, 0, 0); __builtin_amdgcn_s_setprio(0); } while (0)
; #define PG8_WAIT_V(n) asm volatile("s_waitcnt vmcnt(" #n ")" ::: "memory")
; #define PG8_WAIT_L(n) asm volatile("s_waitcnt lgkmcnt(" #n ")" ::: "memory")
; #define PG8_BAR __builtin_amdgcn_s_barrier()
; #define PG8_SCHED __builtin_amdgcn_sched_barrier(0)
; template <class Epi, class Sched>
; __device__ __forceinline__ void gemm_phase(PG8_LAS unsigned char* lds, const int lda, const int ldb, const Sched& S, const Epi& E) {
;     ...
;       PG8_STAGE(PG8_SB(0, 1), b2 + hstepB, voffB);
;       PG8_WAIT_V(6); PG8_BAR; PG8_MMA(1, 1, At, B1); PG8_BAR;
;       PG8_LDB(B0, 1, 0); PG8_SCHED; PG8_LDA(At, 1, 0); PG8_STAGE(PG8_SA(0, 1), a2 + hstepA, voffA);
;       PG8_WAIT_L(8); PG8_BAR; PG8_WAIT_L(0); PG8_MMA(0, 0, At, B0); PG8_BAR; PG8_SCHED;
;       PG8_LDB(B1, 1, 1); PG8_STAGE(PG8_SB(1, 0), b3, voffB);
;       PG8_BAR; PG8_WAIT_L(0); PG8_MMA(0, 1, At, B1); PG8_BAR;
;       PG8_LDA(At, 1, 1); PG8_STAGE(PG8_SA(1, 0), a3, voffA);
;       PG8_BAR; PG8_WAIT_L(0); PG8_MMA(1, 0, At, B0); PG8_BAR; PG8_SCHED;
	s_add_u32 s18, s22, 0x40000
	s_addc_u32 s19, s23, 0
	s_add_i32 s33, s55, s34
	v_lshl_add_u64 v[140:141], s[18:19], 0, v[134:135]
	s_mov_b32 m0, s33
	s_nop 0
	global_load_lds_dwordx4 v[140:141], off
	v_lshl_add_u64 v[140:141], s[18:19], 0, v[132:133]
	s_add_i32 m0, s33, 0x2000
	s_nop 0
	global_load_lds_dwordx4 v[140:141], off
	s_waitcnt vmcnt(6)
	s_setprio 1
	s_barrier
	v_mfma_f32_16x16x32_bf16 v[54:57], v[216:219], v[158:161], v[54:57]
	v_mfma_f32_16x16x32_bf16 v[50:53], v[224:227], v[158:161], v[50:53]
	v_mfma_f32_16x16x32_bf16 v[38:41], v[216:219], v[166:169], v[38:41]
	v_mfma_f32_16x16x32_bf16 v[34:37], v[224:227], v[166:169], v[34:37]
	v_mfma_f32_16x16x32_bf16 v[22:25], v[216:219], v[200:203], v[22:25]
	v_mfma_f32_16x16x32_bf16 v[18:21], v[224:227], v[200:203], v[18:21]
	v_mfma_f32_16x16x32_bf16 v[6:9], v[216:219], v[208:211], v[6:9]
	v_mfma_f32_16x16x32_bf16 v[2:5], v[224:227], v[208:211], v[2:5]
	v_mfma_f32_16x16x32_bf16 v[54:57], v[220:223], v[162:165], v[54:57]
	v_mfma_f32_16x16x32_bf16 v[50:53], v[228:231], v[162:165], v[50:53]
	v_mfma_f32_16x16x32_bf16 v[38:41], v[220:223], v[170:173], v[38:41]
	v_mfma_f32_16x16x32_bf16 v[34:37], v[228:231], v[170:173], v[34:37]
	v_mfma_f32_16x16x32_bf16 v[22:25], v[220:223], v[204:207], v[22:25]
	v_mfma_f32_16x16x32_bf16 v[18:21], v[228:231], v[204:207], v[18:21]
	v_mfma_f32_16x16x32_bf16 v[6:9], v[220:223], v[212:215], v[6:9]
	v_mfma_f32_16x16x32_bf16 v[2:5], v[228:231], v[212:215], v[2:5]
	s_setprio 0
	s_add_i32 s33, 0, 0x18000
	v_add_u32_e32 v154, s33, v131
	s_barrier
	ds_read_b128 v[140:143], v154
	ds_read_b128 v[146:149], v154 offset:1024
	ds_read_b128 v[150:153], v154 offset:2048
	ds_read_b128 v[154:157], v154 offset:3072
	s_add_u32 s18, s24, 0x40000
	s_addc_u32 s19, s25, 0
	s_mov_b32 m0, s38
	v_lshl_add_u64 v[216:217], s[18:19], 0, v[134:135]
	ds_read_b128 v[158:161], v145 offset:32768
	ds_read_b128 v[162:165], v145 offset:33792
	ds_read_b128 v[166:169], v145 offset:34816
	ds_read_b128 v[170:173], v145 offset:35840
	ds_read_b128 v[200:203], v145 offset:36864
	ds_read_b128 v[204:207], v145 offset:37888
	ds_read_b128 v[208:211], v145 offset:38912
	ds_read_b128 v[212:215], v145 offset:39936
	global_load_lds_dwordx4 v[216:217], off
	v_lshl_add_u64 v[216:217], s[18:19], 0, v[132:133]
	s_mov_b32 m0, s39
	s_nop 0
	global_load_lds_dwordx4 v[216:217], off
	s_waitcnt lgkmcnt(8)
	s_setprio 1
	s_barrier
	s_waitcnt lgkmcnt(0)
	v_mfma_f32_16x16x32_bf16 v[126:129], v[140:143], v[158:161], v[126:129]
	v_mfma_f32_16x16x32_bf16 v[122:125], v[150:153], v[158:161], v[122:125]
	v_mfma_f32_16x16x32_bf16 v[110:113], v[140:143], v[166:169], v[110:113]
	v_mfma_f32_16x16x32_bf16 v[106:109], v[150:153], v[166:169], v[106:109]
	v_mfma_f32_16x16x32_bf16 v[94:97], v[140:143], v[200:203], v[94:97]
	v_mfma_f32_16x16x32_bf16 v[90:93], v[150:153], v[200:203], v[90:93]
	v_mfma_f32_16x16x32_bf16 v[78:81], v[140:143], v[208:211], v[78:81]
	v_mfma_f32_16x16x32_bf16 v[74:77], v[150:153], v[208:211], v[74:77]
	v_mfma_f32_16x16x32_bf16 v[126:129], v[146:149], v[162:165], v[126:129]
	v_mfma_f32_16x16x32_bf16 v[122:125], v[154:157], v[162:165], v[122:125]
	v_mfma_f32_16x16x32_bf16 v[110:113], v[146:149], v[170:173], v[110:113]
	v_mfma_f32_16x16x32_bf16 v[106:109], v[154:157], v[170:173], v[106:109]
	v_mfma_f32_16x16x32_bf16 v[94:97], v[146:149], v[204:207], v[94:97]
	v_mfma_f32_16x16x32_bf16 v[90:93], v[154:157], v[204:207], v[90:93]
	v_mfma_f32_16x16x32_bf16 v[78:81], v[146:149], v[212:215], v[78:81]
	v_mfma_f32_16x16x32_bf16 v[74:77], v[154:157], v[212:215], v[74:77]
	s_setprio 0
	s_barrier
	s_add_i32 s24, 0, 0x1c000
	s_add_i32 s18, s33, s34
	v_add_u32_e32 v228, s24, v131
	v_lshl_add_u64 v[174:175], v[174:175], 0, s[86:87]
	s_mov_b32 m0, s18
	ds_read_b128 v[216:219], v228
	ds_read_b128 v[220:223], v228 offset:1024
	ds_read_b128 v[224:227], v228 offset:2048
	ds_read_b128 v[228:231], v228 offset:3072
	global_load_lds_dwordx4 v[174:175], off
	v_lshl_add_u64 v[174:175], v[182:183], 0, s[86:87]
	s_add_i32 m0, s18, 0x2000
	s_nop 0
	global_load_lds_dwordx4 v[174:175], off
	s_setprio 1
	s_barrier
; #define PG8_STAGE(bufoff, gbase, voff) do { _Pragma("unroll") for (int _i = 0; _i < 2; ++_i) \
;     __builtin_amdgcn_global_load_lds((const unsigned*)((const char*)(gbase) + (voff)[_i]), (PG8_LAS unsigned*)(lds + (bufoff) + ldsw + _i * 8192), 16, 0, 0); } while (0)
; #define PG8_MMA(ai, bj, At, Bt) do { __builtin_amdgcn_s_setprio(1); _Pragma("unroll") for (int m = 0; m < 4; ++m) _Pragma("unroll") for (int n = 0; n < 2; ++n) _Pragma("unroll") for (int k = 0; k < 2; ++k) \
;     acc[ai][bj][m][n] = __builtin_amdgcn_mfma_f32_16x16x32_bf16(Bt[n][k], At[m][k], acc[ai][bj][m][n], 0, 0, 0); __builtin_amdgcn_s_setprio(0); } while (0)
; #define PG8_WAIT_V(n) asm volatile("s_waitcnt vmcnt(" #n ")" ::: "memory")
; #define PG8_WAIT_L(n) asm volatile("s_waitcnt lgkmcnt(" #n ")" ::: "memory")
; #define PG8_BAR __builtin_amdgcn_s_barrier()
; #define PG8_SCHED __builtin_amdgcn_sched_barrier(0)
; template <class Epi, class Sched>
; __device__ __forceinline__ void gemm_phase(PG8_LAS unsigned char* lds, const int lda, const int ldb, const Sched& S, const Epi& E) {
;     ...
;       PG8_BAR; PG8_WAIT_L(0); PG8_MMA(1, 0, At, B0); PG8_BAR; PG8_SCHED;
;       PG8_STAGE(PG8_SB(1, 1), b3 + hstepB, voffB);
;       PG8_WAIT_V(6); PG8_BAR; PG8_MMA(1, 1, At, B1); PG8_BAR;
;     }
;   __device__ __forceinline__ void operator()(const f32x4 (&acc)[2][2][4][2], const Unit& u, int wr, int wc, int fr, int fq) const {
;     const int mr = (u.pm * 256 < ML) ? ((u.pm * 256) >> 11) : 32;
;     const float* gp = mod + (size_t)mr * 6144 + gate_off;
	s_waitcnt lgkmcnt(0)
	v_mfma_f32_16x16x32_bf16 v[118:121], v[216:219], v[158:161], v[118:121]
	v_mfma_f32_16x16x32_bf16 v[114:117], v[224:227], v[158:161], v[114:117]
	v_mfma_f32_16x16x32_bf16 v[102:105], v[216:219], v[166:169], v[102:105]
	v_mfma_f32_16x16x32_bf16 v[98:101], v[224:227], v[166:169], v[98:101]
	v_mfma_f32_16x16x32_bf16 v[86:89], v[216:219], v[200:203], v[86:89]
	v_mfma_f32_16x16x32_bf16 v[82:85], v[224:227], v[200:203], v[82:85]
	v_mfma_f32_16x16x32_bf16 v[70:73], v[216:219], v[208:211], v[70:73]
	v_mfma_f32_16x16x32_bf16 v[66:69], v[224:227], v[208:211], v[66:69]
	v_mfma_f32_16x16x32_bf16 v[118:121], v[220:223], v[162:165], v[118:121]
	v_mfma_f32_16x16x32_bf16 v[114:117], v[228:231], v[162:165], v[114:117]
	v_mfma_f32_16x16x32_bf16 v[102:105], v[220:223], v[170:173], v[102:105]
	v_mfma_f32_16x16x32_bf16 v[98:101], v[228:231], v[170:173], v[98:101]
	v_mfma_f32_16x16x32_bf16 v[86:89], v[220:223], v[204:207], v[86:89]
	v_mfma_f32_16x16x32_bf16 v[82:85], v[228:231], v[204:207], v[82:85]
	v_mfma_f32_16x16x32_bf16 v[70:73], v[220:223], v[212:215], v[70:73]
	v_mfma_f32_16x16x32_bf16 v[66:69], v[228:231], v[212:215], v[66:69]
	s_setprio 0
	s_mov_b32 m0, s44
	v_lshl_add_u64 v[174:175], v[184:185], 0, s[86:87]
	s_barrier
	ds_read_b128 v[158:161], v145 offset:49152
	ds_read_b128 v[162:165], v145 offset:50176
	ds_read_b128 v[166:169], v145 offset:51200
	ds_read_b128 v[170:173], v145 offset:52224
	ds_read_b128 v[200:203], v145 offset:53248
	ds_read_b128 v[204:207], v145 offset:54272
	ds_read_b128 v[208:211], v145 offset:55296
	ds_read_b128 v[212:215], v145 offset:56320
	global_load_lds_dwordx4 v[174:175], off
	v_lshl_add_u64 v[174:175], v[232:233], 0, s[86:87]
	s_mov_b32 m0, s45
	s_nop 0
	global_load_lds_dwordx4 v[174:175], off
	s_setprio 1
	s_barrier
	s_waitcnt lgkmcnt(0)
	v_mfma_f32_16x16x32_bf16 v[62:65], v[140:143], v[158:161], v[62:65]
	v_mfma_f32_16x16x32_bf16 v[58:61], v[150:153], v[158:161], v[58:61]
	v_mfma_f32_16x16x32_bf16 v[46:49], v[140:143], v[166:169], v[46:49]
	v_mfma_f32_16x16x32_bf16 v[42:45], v[150:153], v[166:169], v[42:45]
	v_mfma_f32_16x16x32_bf16 v[30:33], v[140:143], v[200:203], v[30:33]
	v_mfma_f32_16x16x32_bf16 v[26:29], v[150:153], v[200:203], v[26:29]
	v_mfma_f32_16x16x32_bf16 v[14:17], v[140:143], v[208:211], v[14:17]
	v_mfma_f32_16x16x32_bf16 v[10:13], v[150:153], v[208:211], v[10:13]
	v_mfma_f32_16x16x32_bf16 v[62:65], v[146:149], v[162:165], v[62:65]
	v_mfma_f32_16x16x32_bf16 v[58:61], v[154:157], v[162:165], v[58:61]
	v_mfma_f32_16x16x32_bf16 v[46:49], v[146:149], v[170:173], v[46:49]
	v_mfma_f32_16x16x32_bf16 v[42:45], v[154:157], v[170:173], v[42:45]
	v_mfma_f32_16x16x32_bf16 v[30:33], v[146:149], v[204:207], v[30:33]
	v_mfma_f32_16x16x32_bf16 v[26:29], v[154:157], v[204:207], v[26:29]
	v_mfma_f32_16x16x32_bf16 v[14:17], v[146:149], v[212:215], v[14:17]
	v_mfma_f32_16x16x32_bf16 v[10:13], v[154:157], v[212:215], v[10:13]
	s_setprio 0
	s_barrier
	s_add_u32 s18, s22, 0x40080
	s_addc_u32 s19, s23, 0
	s_add_i32 s22, s24, s34
	v_lshl_add_u64 v[140:141], s[18:19], 0, v[134:135]
	s_mov_b32 m0, s22
	s_nop 0
	global_load_lds_dwordx4 v[140:141], off
	v_lshl_add_u64 v[140:141], s[18:19], 0, v[132:133]
	s_add_i32 m0, s22, 0x2000
	s_nop 0
	global_load_lds_dwordx4 v[140:141], off
	s_waitcnt vmcnt(6)
	s_setprio 1
	s_barrier
	v_mfma_f32_16x16x32_bf16 v[54:57], v[216:219], v[158:161], v[54:57]
	v_mfma_f32_16x16x32_bf16 v[50:53], v[224:227], v[158:161], v[50:53]
	v_mfma_f32_16x16x32_bf16 v[38:41], v[216:219], v[166:169], v[38:41]
	v_mfma_f32_16x16x32_bf16 v[34:37], v[224:227], v[166:169], v[34:37]
	v_mfma_f32_16x16x32_bf16 v[22:25], v[216:219], v[200:203], v[22:25]
	v_mfma_f32_16x16x32_bf16 v[18:21], v[224:227], v[200:203], v[18:21]
	v_mfma_f32_16x16x32_bf16 v[6:9], v[216:219], v[208:211], v[6:9]
	v_mfma_f32_16x16x32_bf16 v[2:5], v[224:227], v[208:211], v[2:5]
	v_mfma_f32_16x16x32_bf16 v[54:57], v[220:223], v[162:165], v[54:57]
	v_mfma_f32_16x16x32_bf16 v[50:53], v[228:231], v[162:165], v[50:53]
	v_mfma_f32_16x16x32_bf16 v[38:41], v[220:223], v[170:173], v[38:41]
	v_mfma_f32_16x16x32_bf16 v[34:37], v[228:231], v[170:173], v[34:37]
	v_mfma_f32_16x16x32_bf16 v[22:25], v[220:223], v[204:207], v[22:25]
	v_mfma_f32_16x16x32_bf16 v[18:21], v[228:231], v[204:207], v[18:21]
	v_mfma_f32_16x16x32_bf16 v[6:9], v[220:223], v[212:215], v[6:9]
	v_mfma_f32_16x16x32_bf16 v[2:5], v[228:231], v[212:215], v[2:5]
	s_setprio 0
	s_add_i32 s54, s54, 2
	s_add_u32 s52, s52, 0x100
	s_addc_u32 s53, s53, 0
	s_cmp_gt_u32 s54, 13
	s_mov_b64 s[18:19], s[20:21]
	s_barrier
	s_cbranch_scc0 .LBB0_1482
	s_cmpk_gt_i32 s16, 0xff
	s_mov_b64 s[18:19], 0x30000
	s_cbranch_scc1 .LBB0_1478
	s_ashr_i32 s1, s16, 3
	s_mul_hi_i32 s19, s1, 0x1800
	s_mul_i32 s18, s1, 0x1800
	s_branch .LBB0_1478

; #define PG8_STAGE(bufoff, gbase, voff) do { _Pragma("unroll") for (int _i = 0; _i < 2; ++_i) \
;     __builtin_amdgcn_global_load_lds((const unsigned*)((const char*)(gbase) + (voff)[_i]), (PG8_LAS unsigned*)(lds + (bufoff) + ldsw + _i * 8192), 16, 0, 0); } while (0)
; #define PG8_LDA(dst, b, h) do { _Pragma("unroll") for (int m = 0; m < 4; ++m) _Pragma("unroll") for (int k = 0; k < 2; ++k) dst[m][k] = *(const PG8_LAS bf16x8*)(lds + PG8_SA(b, h) + aoff + m * 2048 + k * 1024); } while (0)
; #define PG8_LDB(dst, b, h) do { _Pragma("unroll") for (int n = 0; n < 2; ++n) _Pragma("unroll") for (int k = 0; k < 2; ++k) dst[n][k] = *(const PG8_LAS bf16x8*)(lds + PG8_SB(b, h) + boff + n * 2048 + k * 1024); } while (0)
; #define PG8_MMA(ai, bj, At, Bt) do { __builtin_amdgcn_s_setprio(1); _Pragma("unroll") for (int m = 0; m < 4; ++m) _Pragma("unroll") for (int n = 0; n < 2; ++n) _Pragma("unroll") for (int k = 0; k < 2; ++k) \
;     acc[ai][bj][m][n] = __builtin_amdgcn_mfma_f32_16x16x32_bf16(Bt[n][k], At[m][k], acc[ai][bj][m][n], 0, 0, 0); __builtin_amdgcn_s_setprio(0); } while (0)
; #define PG8_WAIT_L(n) asm volatile("s_waitcnt lgkmcnt(" #n ")" ::: "memory")
; #define PG8_BAR __builtin_amdgcn_s_barrier()
; #define PG8_SCHED __builtin_amdgcn_sched_barrier(0)
; template <class Epi, class Sched>
; __device__ __forceinline__ void gemm_phase(PG8_LAS unsigned char* lds, const int lda, const int ldb, const Sched& S, const Epi& E) {
;     ...
;     for (int t = 0; t < nt; t += 2) {
;       const bool last = (t == nt - 2);
;       const char* a1 = cA + (size_t)(t + 1) * kstep;
;       const char* a2 = last ? nA : cA + (size_t)(t + 2) * kstep; const char* b2 = last ? nB : cB + (size_t)(t + 2) * kstep;
;       const char* a3 = a2 + kstep; const char* b3 = b2 + kstep;
;       PG8_LDB(B0, 0, 0); PG8_SCHED; PG8_LDA(At, 0, 0); PG8_STAGE(PG8_SA(1, 1), a1 + hstepA, voffA);
;       PG8_WAIT_L(8); PG8_BAR; PG8_WAIT_L(0); PG8_MMA(0, 0, At, B0); PG8_BAR; PG8_SCHED;
;       PG8_LDB(B1, 0, 1); PG8_STAGE(PG8_SB(0, 0), b2, voffB);
;       PG8_BAR; PG8_WAIT_L(0); PG8_MMA(0, 1, At, B1); PG8_BAR;
;       PG8_LDA(At, 0, 1); PG8_STAGE(PG8_SA(0, 0), a2, voffA);
;       PG8_BAR; PG8_WAIT_L(0); PG8_MMA(1, 0, At, B0); PG8_BAR; PG8_SCHED;
.LBB0_1604:
	s_add_u32 s20, s18, 0xfffc0080
	s_addc_u32 s21, s19, -1
	s_add_i32 s33, 0, 0x10000
	v_add_u32_e32 v154, s33, v131
	ds_read_b128 v[142:145], v154
	ds_read_b128 v[146:149], v154 offset:1024
	ds_read_b128 v[150:153], v154 offset:2048
	ds_read_b128 v[154:157], v154 offset:3072
	s_cmp_eq_u32 s46, 12
	s_cselect_b32 s23, s11, s21
	s_cselect_b32 s22, s42, s20
	s_cselect_b32 s21, s1, s45
	s_cselect_b32 s20, s43, s44
	v_lshl_add_u64 v[174:175], s[18:19], 0, v[136:137]
	s_add_i32 m0, s17, 0xc000
	ds_read_b128 v[158:161], v141
	ds_read_b128 v[162:165], v141 offset:1024
	ds_read_b128 v[166:169], v141 offset:2048
	ds_read_b128 v[170:173], v141 offset:3072
	ds_read_b128 v[200:203], v141 offset:4096
	ds_read_b128 v[204:207], v141 offset:5120
	ds_read_b128 v[208:211], v141 offset:6144
	ds_read_b128 v[212:215], v141 offset:7168
	global_load_lds_dwordx4 v[174:175], off
	v_lshl_add_u64 v[174:175], s[18:19], 0, v[138:139]
	s_add_i32 m0, s17, 0xe000
	s_nop 0
	global_load_lds_dwordx4 v[174:175], off
	s_waitcnt lgkmcnt(8)
	s_setprio 1
	s_barrier
	s_waitcnt lgkmcnt(0)
	v_mfma_f32_16x16x32_bf16 v[126:129], v[142:145], v[158:161], v[126:129]
	v_mfma_f32_16x16x32_bf16 v[118:121], v[150:153], v[158:161], v[118:121]
	v_mfma_f32_16x16x32_bf16 v[110:113], v[142:145], v[166:169], v[110:113]
	v_mfma_f32_16x16x32_bf16 v[102:105], v[150:153], v[166:169], v[102:105]
	v_mfma_f32_16x16x32_bf16 v[94:97], v[142:145], v[200:203], v[94:97]
	v_mfma_f32_16x16x32_bf16 v[86:89], v[150:153], v[200:203], v[86:89]
	v_mfma_f32_16x16x32_bf16 v[78:81], v[142:145], v[208:211], v[78:81]
	v_mfma_f32_16x16x32_bf16 v[70:73], v[150:153], v[208:211], v[70:73]
	v_mfma_f32_16x16x32_bf16 v[126:129], v[146:149], v[162:165], v[126:129]
	v_mfma_f32_16x16x32_bf16 v[118:121], v[154:157], v[162:165], v[118:121]
	v_mfma_f32_16x16x32_bf16 v[110:113], v[146:149], v[170:173], v[110:113]
	v_mfma_f32_16x16x32_bf16 v[102:105], v[154:157], v[170:173], v[102:105]
	v_mfma_f32_16x16x32_bf16 v[94:97], v[146:149], v[204:207], v[94:97]
	v_mfma_f32_16x16x32_bf16 v[86:89], v[154:157], v[204:207], v[86:89]
	v_mfma_f32_16x16x32_bf16 v[78:81], v[146:149], v[212:215], v[78:81]
	v_mfma_f32_16x16x32_bf16 v[70:73], v[154:157], v[212:215], v[70:73]
	s_setprio 0
	s_barrier
	s_add_i32 s47, 0, 0x14000
	v_add_u32_e32 v174, s47, v131
	s_add_i32 s33, s33, s30
	ds_read_b128 v[216:219], v174
	ds_read_b128 v[220:223], v174 offset:1024
	ds_read_b128 v[224:227], v174 offset:2048
	ds_read_b128 v[228:231], v174 offset:3072
	v_lshl_add_u64 v[174:175], s[20:21], 0, v[134:135]
	s_mov_b32 m0, s33
	v_lshl_add_u64 v[182:183], s[20:21], 0, v[132:133]
	global_load_lds_dwordx4 v[174:175], off
	s_add_i32 m0, s33, 0x2000
	s_nop 0
	global_load_lds_dwordx4 v[182:183], off
	s_setprio 1
	s_barrier
	s_waitcnt lgkmcnt(0)
	v_mfma_f32_16x16x32_bf16 v[122:125], v[216:219], v[158:161], v[122:125]
	v_mfma_f32_16x16x32_bf16 v[114:117], v[224:227], v[158:161], v[114:117]
	v_mfma_f32_16x16x32_bf16 v[106:109], v[216:219], v[166:169], v[106:109]
	v_mfma_f32_16x16x32_bf16 v[98:101], v[224:227], v[166:169], v[98:101]
	v_mfma_f32_16x16x32_bf16 v[90:93], v[216:219], v[200:203], v[90:93]
	v_mfma_f32_16x16x32_bf16 v[82:85], v[224:227], v[200:203], v[82:85]
	v_mfma_f32_16x16x32_bf16 v[74:77], v[216:219], v[208:211], v[74:77]
	v_mfma_f32_16x16x32_bf16 v[66:69], v[224:227], v[208:211], v[66:69]
	v_mfma_f32_16x16x32_bf16 v[122:125], v[220:223], v[162:165], v[122:125]
	v_mfma_f32_16x16x32_bf16 v[114:117], v[228:231], v[162:165], v[114:117]
	v_mfma_f32_16x16x32_bf16 v[106:109], v[220:223], v[170:173], v[106:109]
	v_mfma_f32_16x16x32_bf16 v[98:101], v[228:231], v[170:173], v[98:101]
	v_mfma_f32_16x16x32_bf16 v[90:93], v[220:223], v[204:207], v[90:93]
	v_mfma_f32_16x16x32_bf16 v[82:85], v[228:231], v[204:207], v[82:85]
	v_mfma_f32_16x16x32_bf16 v[74:77], v[220:223], v[212:215], v[74:77]
	v_mfma_f32_16x16x32_bf16 v[66:69], v[228:231], v[212:215], v[66:69]
	s_setprio 0
	s_mov_b32 m0, s17
	v_lshl_add_u64 v[184:185], s[22:23], 0, v[134:135]
	s_barrier
	ds_read_b128 v[158:161], v141 offset:16384
	ds_read_b128 v[162:165], v141 offset:17408
	ds_read_b128 v[166:169], v141 offset:18432
	ds_read_b128 v[170:173], v141 offset:19456
	ds_read_b128 v[200:203], v141 offset:20480
	ds_read_b128 v[204:207], v141 offset:21504
	ds_read_b128 v[208:211], v141 offset:22528
	ds_read_b128 v[212:215], v141 offset:23552
	global_load_lds_dwordx4 v[184:185], off
	v_lshl_add_u64 v[232:233], s[22:23], 0, v[132:133]
	s_mov_b32 m0, s35
	s_nop 0
	global_load_lds_dwordx4 v[232:233], off
	s_setprio 1
	s_barrier
	s_waitcnt lgkmcnt(0)
	v_mfma_f32_16x16x32_bf16 v[62:65], v[142:145], v[158:161], v[62:65]
	v_mfma_f32_16x16x32_bf16 v[54:57], v[150:153], v[158:161], v[54:57]
	v_mfma_f32_16x16x32_bf16 v[46:49], v[142:145], v[166:169], v[46:49]
	v_mfma_f32_16x16x32_bf16 v[38:41], v[150:153], v[166:169], v[38:41]
	v_mfma_f32_16x16x32_bf16 v[30:33], v[142:145], v[200:203], v[30:33]
	v_mfma_f32_16x16x32_bf16 v[22:25], v[150:153], v[200:203], v[22:25]
	v_mfma_f32_16x16x32_bf16 v[14:17], v[142:145], v[208:211], v[14:17]
	v_mfma_f32_16x16x32_bf16 v[6:9], v[150:153], v[208:211], v[6:9]
	v_mfma_f32_16x16x32_bf16 v[62:65], v[146:149], v[162:165], v[62:65]
	v_mfma_f32_16x16x32_bf16 v[54:57], v[154:157], v[162:165], v[54:57]
	v_mfma_f32_16x16x32_bf16 v[46:49], v[146:149], v[170:173], v[46:49]
	v_mfma_f32_16x16x32_bf16 v[38:41], v[154:157], v[170:173], v[38:41]
	v_mfma_f32_16x16x32_bf16 v[30:33], v[146:149], v[204:207], v[30:33]
	v_mfma_f32_16x16x32_bf16 v[22:25], v[154:157], v[204:207], v[22:25]
	v_mfma_f32_16x16x32_bf16 v[14:17], v[146:149], v[212:215], v[14:17]
	v_mfma_f32_16x16x32_bf16 v[6:9], v[154:157], v[212:215], v[6:9]
	s_setprio 0
	s_barrier
; #define PG8_STAGE(bufoff, gbase, voff) do { _Pragma("unroll") for (int _i = 0; _i < 2; ++_i) \
;     __builtin_amdgcn_global_load_lds((const unsigned*)((const char*)(gbase) + (voff)[_i]), (PG8_LAS unsigned*)(lds + (bufoff) + ldsw + _i * 8192), 16, 0, 0); } while (0)
; #define PG8_LDA(dst, b, h) do { _Pragma("unroll") for (int m = 0; m < 4; ++m) _Pragma("unroll") for (int k = 0; k < 2; ++k) dst[m][k] = *(const PG8_LAS bf16x8*)(lds + PG8_SA(b, h) + aoff + m * 2048 + k * 1024); } while (0)
; #define PG8_LDB(dst, b, h) do { _Pragma("unroll") for (int n = 0; n < 2; ++n) _Pragma("unroll") for (int k = 0; k < 2; ++k) dst[n][k] = *(const PG8_LAS bf16x8*)(lds + PG8_SB(b, h) + boff + n * 2048 + k * 1024); } while (0)
; #define PG8_MMA(ai, bj, At, Bt) do { __builtin_amdgcn_s_setprio(1); _Pragma("unroll") for (int m = 0; m < 4; ++m) _Pragma("unroll") for (int n = 0; n < 2; ++n) _Pragma("unroll") for (int k = 0; k < 2; ++k) \
;     acc[ai][bj][m][n] = __builtin_amdgcn_mfma_f32_16x16x32_bf16(Bt[n][k], At[m][k], acc[ai][bj][m][n], 0, 0, 0); __builtin_amdgcn_s_setprio(0); } while (0)
; #define PG8_WAIT_V(n) asm volatile("s_waitcnt vmcnt(" #n ")" ::: "memory")
; #define PG8_WAIT_L(n) asm volatile("s_waitcnt lgkmcnt(" #n ")" ::: "memory")
; #define PG8_BAR __builtin_amdgcn_s_barrier()
; #define PG8_SCHED __builtin_amdgcn_sched_barrier(0)
; template <class Epi, class Sched>
; __device__ __forceinline__ void gemm_phase(PG8_LAS unsigned char* lds, const int lda, const int ldb, const Sched& S, const Epi& E) {
;     ...
;       PG8_STAGE(PG8_SB(0, 1), b2 + hstepB, voffB);
;       PG8_WAIT_V(6); PG8_BAR; PG8_MMA(1, 1, At, B1); PG8_BAR;
;       PG8_LDB(B0, 1, 0); PG8_SCHED; PG8_LDA(At, 1, 0); PG8_STAGE(PG8_SA(0, 1), a2 + hstepA, voffA);
;       PG8_WAIT_L(8); PG8_BAR; PG8_WAIT_L(0); PG8_MMA(0, 0, At, B0); PG8_BAR; PG8_SCHED;
;       PG8_LDB(B1, 1, 1); PG8_STAGE(PG8_SB(1, 0), b3, voffB);
;       PG8_BAR; PG8_WAIT_L(0); PG8_MMA(0, 1, At, B1); PG8_BAR;
;       PG8_LDA(At, 1, 1); PG8_STAGE(PG8_SA(1, 0), a3, voffA);
;       PG8_BAR; PG8_WAIT_L(0); PG8_MMA(1, 0, At, B0); PG8_BAR; PG8_SCHED;
	s_add_u32 s48, s20, 0x40000
	s_addc_u32 s49, s21, 0
	s_add_i32 s33, s47, s30
	v_lshl_add_u64 v[142:143], s[48:49], 0, v[134:135]
	s_mov_b32 m0, s33
	s_nop 0
	global_load_lds_dwordx4 v[142:143], off
	v_lshl_add_u64 v[142:143], s[48:49], 0, v[132:133]
	s_add_i32 m0, s33, 0x2000
	s_nop 0
	global_load_lds_dwordx4 v[142:143], off
	s_waitcnt vmcnt(6)
	s_setprio 1
	s_barrier
	v_mfma_f32_16x16x32_bf16 v[58:61], v[216:219], v[158:161], v[58:61]
	v_mfma_f32_16x16x32_bf16 v[50:53], v[224:227], v[158:161], v[50:53]
	v_mfma_f32_16x16x32_bf16 v[42:45], v[216:219], v[166:169], v[42:45]
	v_mfma_f32_16x16x32_bf16 v[34:37], v[224:227], v[166:169], v[34:37]
	v_mfma_f32_16x16x32_bf16 v[26:29], v[216:219], v[200:203], v[26:29]
	v_mfma_f32_16x16x32_bf16 v[18:21], v[224:227], v[200:203], v[18:21]
	v_mfma_f32_16x16x32_bf16 v[10:13], v[216:219], v[208:211], v[10:13]
	v_mfma_f32_16x16x32_bf16 v[2:5], v[224:227], v[208:211], v[2:5]
	v_mfma_f32_16x16x32_bf16 v[58:61], v[220:223], v[162:165], v[58:61]
	v_mfma_f32_16x16x32_bf16 v[50:53], v[228:231], v[162:165], v[50:53]
	v_mfma_f32_16x16x32_bf16 v[42:45], v[220:223], v[170:173], v[42:45]
	v_mfma_f32_16x16x32_bf16 v[34:37], v[228:231], v[170:173], v[34:37]
	v_mfma_f32_16x16x32_bf16 v[26:29], v[220:223], v[204:207], v[26:29]
	v_mfma_f32_16x16x32_bf16 v[18:21], v[228:231], v[204:207], v[18:21]
	v_mfma_f32_16x16x32_bf16 v[10:13], v[220:223], v[212:215], v[10:13]
	v_mfma_f32_16x16x32_bf16 v[2:5], v[228:231], v[212:215], v[2:5]
	s_setprio 0
	s_add_i32 s33, 0, 0x18000
	v_add_u32_e32 v154, s33, v131
	s_barrier
	ds_read_b128 v[142:145], v154
	ds_read_b128 v[146:149], v154 offset:1024
	ds_read_b128 v[150:153], v154 offset:2048
	ds_read_b128 v[154:157], v154 offset:3072
	s_add_u32 s22, s22, 0x40000
	s_addc_u32 s23, s23, 0
	s_mov_b32 m0, s36
	v_lshl_add_u64 v[216:217], s[22:23], 0, v[134:135]
	ds_read_b128 v[158:161], v141 offset:32768
	ds_read_b128 v[162:165], v141 offset:33792
	ds_read_b128 v[166:169], v141 offset:34816
	ds_read_b128 v[170:173], v141 offset:35840
	ds_read_b128 v[200:203], v141 offset:36864
	ds_read_b128 v[204:207], v141 offset:37888
	ds_read_b128 v[208:211], v141 offset:38912
	ds_read_b128 v[212:215], v141 offset:39936
	global_load_lds_dwordx4 v[216:217], off
	v_lshl_add_u64 v[216:217], s[22:23], 0, v[132:133]
	s_mov_b32 m0, s37
	s_nop 0
	global_load_lds_dwordx4 v[216:217], off
	s_waitcnt lgkmcnt(8)
	s_setprio 1
	s_barrier
	s_waitcnt lgkmcnt(0)
	v_mfma_f32_16x16x32_bf16 v[126:129], v[142:145], v[158:161], v[126:129]
	v_mfma_f32_16x16x32_bf16 v[118:121], v[150:153], v[158:161], v[118:121]
	v_mfma_f32_16x16x32_bf16 v[110:113], v[142:145], v[166:169], v[110:113]
	v_mfma_f32_16x16x32_bf16 v[102:105], v[150:153], v[166:169], v[102:105]
	v_mfma_f32_16x16x32_bf16 v[94:97], v[142:145], v[200:203], v[94:97]
	v_mfma_f32_16x16x32_bf16 v[86:89], v[150:153], v[200:203], v[86:89]
	v_mfma_f32_16x16x32_bf16 v[78:81], v[142:145], v[208:211], v[78:81]
	v_mfma_f32_16x16x32_bf16 v[70:73], v[150:153], v[208:211], v[70:73]
	v_mfma_f32_16x16x32_bf16 v[126:129], v[146:149], v[162:165], v[126:129]
	v_mfma_f32_16x16x32_bf16 v[118:121], v[154:157], v[162:165], v[118:121]
	v_mfma_f32_16x16x32_bf16 v[110:113], v[146:149], v[170:173], v[110:113]
	v_mfma_f32_16x16x32_bf16 v[102:105], v[154:157], v[170:173], v[102:105]
	v_mfma_f32_16x16x32_bf16 v[94:97], v[146:149], v[204:207], v[94:97]
	v_mfma_f32_16x16x32_bf16 v[86:89], v[154:157], v[204:207], v[86:89]
	v_mfma_f32_16x16x32_bf16 v[78:81], v[146:149], v[212:215], v[78:81]
	v_mfma_f32_16x16x32_bf16 v[70:73], v[154:157], v[212:215], v[70:73]
	s_setprio 0
	s_barrier
	s_add_i32 s22, 0, 0x1c000
	s_add_i32 s23, s33, s30
	v_add_u32_e32 v228, s22, v131
	v_lshl_add_u64 v[174:175], v[174:175], 0, s[86:87]
	s_mov_b32 m0, s23
	ds_read_b128 v[216:219], v228
	ds_read_b128 v[220:223], v228 offset:1024
	ds_read_b128 v[224:227], v228 offset:2048
	ds_read_b128 v[228:231], v228 offset:3072
	global_load_lds_dwordx4 v[174:175], off
	v_lshl_add_u64 v[174:175], v[182:183], 0, s[86:87]
	s_add_i32 m0, s23, 0x2000
	s_nop 0
	global_load_lds_dwordx4 v[174:175], off
	s_setprio 1
	s_barrier
	s_waitcnt lgkmcnt(0)
	v_mfma_f32_16x16x32_bf16 v[122:125], v[216:219], v[158:161], v[122:125]
	v_mfma_f32_16x16x32_bf16 v[114:117], v[224:227], v[158:161], v[114:117]
	v_mfma_f32_16x16x32_bf16 v[106:109], v[216:219], v[166:169], v[106:109]
	v_mfma_f32_16x16x32_bf16 v[98:101], v[224:227], v[166:169], v[98:101]
	v_mfma_f32_16x16x32_bf16 v[90:93], v[216:219], v[200:203], v[90:93]
	v_mfma_f32_16x16x32_bf16 v[82:85], v[224:227], v[200:203], v[82:85]
	v_mfma_f32_16x16x32_bf16 v[74:77], v[216:219], v[208:211], v[74:77]
	v_mfma_f32_16x16x32_bf16 v[66:69], v[224:227], v[208:211], v[66:69]
	v_mfma_f32_16x16x32_bf16 v[122:125], v[220:223], v[162:165], v[122:125]
	v_mfma_f32_16x16x32_bf16 v[114:117], v[228:231], v[162:165], v[114:117]
	v_mfma_f32_16x16x32_bf16 v[106:109], v[220:223], v[170:173], v[106:109]
	v_mfma_f32_16x16x32_bf16 v[98:101], v[228:231], v[170:173], v[98:101]
	v_mfma_f32_16x16x32_bf16 v[90:93], v[220:223], v[204:207], v[90:93]
	v_mfma_f32_16x16x32_bf16 v[82:85], v[228:231], v[204:207], v[82:85]
	v_mfma_f32_16x16x32_bf16 v[74:77], v[220:223], v[212:215], v[74:77]
	v_mfma_f32_16x16x32_bf16 v[66:69], v[228:231], v[212:215], v[66:69]
	s_setprio 0
	s_mov_b32 m0, s38
	v_lshl_add_u64 v[174:175], v[184:185], 0, s[86:87]
	s_barrier
	ds_read_b128 v[158:161], v141 offset:49152
	ds_read_b128 v[162:165], v141 offset:50176
	ds_read_b128 v[166:169], v141 offset:51200
	ds_read_b128 v[170:173], v141 offset:52224
	ds_read_b128 v[200:203], v141 offset:53248
	ds_read_b128 v[204:207], v141 offset:54272
	ds_read_b128 v[208:211], v141 offset:55296
	ds_read_b128 v[212:215], v141 offset:56320
	global_load_lds_dwordx4 v[174:175], off
	v_lshl_add_u64 v[174:175], v[232:233], 0, s[86:87]
	s_mov_b32 m0, s39
	s_nop 0
	global_load_lds_dwordx4 v[174:175], off
	s_setprio 1
	s_barrier
; __device__ __forceinline__ float silu_f(float x) { return x * sigm(x); }
; #define PG8_STAGE(bufoff, gbase, voff) do { _Pragma("unroll") for (int _i = 0; _i < 2; ++_i) \
;     __builtin_amdgcn_global_load_lds((const unsigned*)((const char*)(gbase) + (voff)[_i]), (PG8_LAS unsigned*)(lds + (bufoff) + ldsw + _i * 8192), 16, 0, 0); } while (0)
; #define PG8_LDA(dst, b, h) do { _Pragma("unroll") for (int m = 0; m < 4; ++m) _Pragma("unroll") for (int k = 0; k < 2; ++k) dst[m][k] = *(const PG8_LAS bf16x8*)(lds + PG8_SA(b, h) + aoff + m * 2048 + k * 1024); } while (0)
; #define PG8_MMA(ai, bj, At, Bt) do { __builtin_amdgcn_s_setprio(1); _Pragma("unroll") for (int m = 0; m < 4; ++m) _Pragma("unroll") for (int n = 0; n < 2; ++n) _Pragma("unroll") for (int k = 0; k < 2; ++k) \
;     acc[ai][bj][m][n] = __builtin_amdgcn_mfma_f32_16x16x32_bf16(Bt[n][k], At[m][k], acc[ai][bj][m][n], 0, 0, 0); __builtin_amdgcn_s_setprio(0); } while (0)
; #define PG8_WAIT_V(n) asm volatile("s_waitcnt vmcnt(" #n ")" ::: "memory")
; #define PG8_WAIT_L(n) asm volatile("s_waitcnt lgkmcnt(" #n ")" ::: "memory")
; #define PG8_BAR __builtin_amdgcn_s_barrier()
; #define PG8_SCHED __builtin_amdgcn_sched_barrier(0)
; template <class Epi, class Sched>
; __device__ __forceinline__ void gemm_phase(PG8_LAS unsigned char* lds, const int lda, const int ldb, const Sched& S, const Epi& E) {
;     ...
;       PG8_LDA(At, 1, 1); PG8_STAGE(PG8_SA(1, 0), a3, voffA);
;       PG8_BAR; PG8_WAIT_L(0); PG8_MMA(1, 0, At, B0); PG8_BAR; PG8_SCHED;
;       PG8_STAGE(PG8_SB(1, 1), b3 + hstepB, voffB);
;       PG8_WAIT_V(6); PG8_BAR; PG8_MMA(1, 1, At, B1); PG8_BAR;
;   __device__ __forceinline__ void operator()(const f32x4 (&acc)[2][2][4][2], const Unit& u, int wr, int wc, int fr, int fq) const {
;     ...
;         const int r = u.pm * 256 + ai * 128 + wr * 64 + m * 16 + fr;
; #pragma unroll
;         for (int n = 0; n < 2; ++n) {
;           const f32x4 g = acc[ai][0][m][n], up = acc[ai][1][m][n];
;           const int c = u.pn * 128 + wc * 32 + n * 16 + 4 * fq;
;           uint2 w;
;           w.x = pack2(silu_f(g[0]) * up[0], silu_f(g[1]) * up[1]);
;           w.y = pack2(silu_f(g[2]) * up[2], silu_f(g[3]) * up[3]);
;           *reinterpret_cast<uint2*>(HID + (size_t)r * DFF + c) = w;
;         }
	s_waitcnt lgkmcnt(0)
	v_mfma_f32_16x16x32_bf16 v[62:65], v[142:145], v[158:161], v[62:65]
	v_mfma_f32_16x16x32_bf16 v[54:57], v[150:153], v[158:161], v[54:57]
	v_mfma_f32_16x16x32_bf16 v[46:49], v[142:145], v[166:169], v[46:49]
	v_mfma_f32_16x16x32_bf16 v[38:41], v[150:153], v[166:169], v[38:41]
	v_mfma_f32_16x16x32_bf16 v[30:33], v[142:145], v[200:203], v[30:33]
	v_mfma_f32_16x16x32_bf16 v[22:25], v[150:153], v[200:203], v[22:25]
	v_mfma_f32_16x16x32_bf16 v[14:17], v[142:145], v[208:211], v[14:17]
	v_mfma_f32_16x16x32_bf16 v[6:9], v[150:153], v[208:211], v[6:9]
	v_mfma_f32_16x16x32_bf16 v[62:65], v[146:149], v[162:165], v[62:65]
	v_mfma_f32_16x16x32_bf16 v[54:57], v[154:157], v[162:165], v[54:57]
	v_mfma_f32_16x16x32_bf16 v[46:49], v[146:149], v[170:173], v[46:49]
	v_mfma_f32_16x16x32_bf16 v[38:41], v[154:157], v[170:173], v[38:41]
	v_mfma_f32_16x16x32_bf16 v[30:33], v[146:149], v[204:207], v[30:33]
	v_mfma_f32_16x16x32_bf16 v[22:25], v[154:157], v[204:207], v[22:25]
	v_mfma_f32_16x16x32_bf16 v[14:17], v[146:149], v[212:215], v[14:17]
	v_mfma_f32_16x16x32_bf16 v[6:9], v[154:157], v[212:215], v[6:9]
	s_setprio 0
	s_barrier
	s_add_u32 s20, s20, 0x40080
	s_addc_u32 s21, s21, 0
	s_add_i32 s22, s22, s30
	v_lshl_add_u64 v[142:143], s[20:21], 0, v[134:135]
	s_mov_b32 m0, s22
	s_nop 0
	global_load_lds_dwordx4 v[142:143], off
	v_lshl_add_u64 v[142:143], s[20:21], 0, v[132:133]
	s_add_i32 m0, s22, 0x2000
	s_nop 0
	global_load_lds_dwordx4 v[142:143], off
	s_waitcnt vmcnt(6)
	s_setprio 1
	s_barrier
	v_mfma_f32_16x16x32_bf16 v[58:61], v[216:219], v[158:161], v[58:61]
	v_mfma_f32_16x16x32_bf16 v[50:53], v[224:227], v[158:161], v[50:53]
	v_mfma_f32_16x16x32_bf16 v[42:45], v[216:219], v[166:169], v[42:45]
	v_mfma_f32_16x16x32_bf16 v[34:37], v[224:227], v[166:169], v[34:37]
	v_mfma_f32_16x16x32_bf16 v[26:29], v[216:219], v[200:203], v[26:29]
	v_mfma_f32_16x16x32_bf16 v[18:21], v[224:227], v[200:203], v[18:21]
	v_mfma_f32_16x16x32_bf16 v[10:13], v[216:219], v[208:211], v[10:13]
	v_mfma_f32_16x16x32_bf16 v[2:5], v[224:227], v[208:211], v[2:5]
	v_mfma_f32_16x16x32_bf16 v[58:61], v[220:223], v[162:165], v[58:61]
	v_mfma_f32_16x16x32_bf16 v[50:53], v[228:231], v[162:165], v[50:53]
	v_mfma_f32_16x16x32_bf16 v[42:45], v[220:223], v[170:173], v[42:45]
	v_mfma_f32_16x16x32_bf16 v[34:37], v[228:231], v[170:173], v[34:37]
	v_mfma_f32_16x16x32_bf16 v[26:29], v[220:223], v[204:207], v[26:29]
	v_mfma_f32_16x16x32_bf16 v[18:21], v[228:231], v[204:207], v[18:21]
	v_mfma_f32_16x16x32_bf16 v[10:13], v[220:223], v[212:215], v[10:13]
	v_mfma_f32_16x16x32_bf16 v[2:5], v[228:231], v[212:215], v[2:5]
	s_setprio 0
	s_add_i32 s46, s46, 2
	s_add_u32 s18, s18, 0x100
	s_addc_u32 s19, s19, 0
	s_add_u32 s44, s44, 0x100
	s_addc_u32 s45, s45, 0
	s_cmp_gt_u32 s46, 13
	s_barrier
	s_cbranch_scc0 .LBB0_1604
	v_mul_f32_e32 v143, 0xbfb8aa3b, v126
	v_exp_f32_e32 v143, v143
	v_lshl_or_b32 v144, s41, 7, v140
	v_lshl_add_u32 v142, s16, 8, v1
	v_ashrrev_i32_e32 v145, 31, v144
	v_add_f32_e32 v143, 1.0, v143
	v_rcp_f32_e32 v146, v143
	v_mul_f32_e32 v143, 0xbfb8aa3b, v127
	v_exp_f32_e32 v143, v143
	s_and_b64 vcc, exec, s[6:7]
	s_mov_b32 s41, s0
	s_mov_b32 s16, s10
	v_add_f32_e32 v143, 1.0, v143
	v_rcp_f32_e32 v147, v143
	s_mov_b64 s[20:21], s[14:15]
	v_pk_mul_f32 v[126:127], v[126:127], v[146:147]
	s_nop 0
	v_pk_mul_f32 v[122:123], v[126:127], v[122:123]
	s_nop 0
	v_cvt_pk_bf16_f32 v126, v122, v123
	v_mul_f32_e32 v122, 0xbfb8aa3b, v128
	v_mul_f32_e32 v123, 0xbfb8aa3b, v129
	v_exp_f32_e32 v122, v122
	v_exp_f32_e32 v123, v123
	v_add_f32_e32 v122, 1.0, v122
	v_add_f32_e32 v123, 1.0, v123
	v_rcp_f32_e32 v122, v122
	v_rcp_f32_e32 v123, v123
	s_nop 0
	v_pk_mul_f32 v[122:123], v[128:129], v[122:123]
	s_nop 0
	v_pk_mul_f32 v[122:123], v[122:123], v[124:125]
	v_lshlrev_b64 v[124:125], 1, v[144:145]
	v_cvt_pk_bf16_f32 v127, v122, v123
	v_mov_b64_e32 v[122:123], s[84:85]
	v_mad_i64_i32 v[128:129], s[18:19], v142, s50, v[122:123]
	v_lshl_add_u64 v[128:129], v[128:129], 0, v[124:125]
	global_store_dwordx2 v[128:129], v[126:127], off
	v_mul_f32_e32 v126, 0xbfb8aa3b, v118
	v_mul_f32_e32 v127, 0xbfb8aa3b, v119
	v_exp_f32_e32 v126, v126
	v_exp_f32_e32 v127, v127
	v_add_f32_e32 v126, 1.0, v126
	v_add_f32_e32 v127, 1.0, v127
	v_rcp_f32_e32 v126, v126
	v_rcp_f32_e32 v127, v127
	s_nop 0
	v_pk_mul_f32 v[118:119], v[118:119], v[126:127]
	s_nop 0
	v_pk_mul_f32 v[114:115], v[118:119], v[114:115]
	s_nop 0
	v_cvt_pk_bf16_f32 v114, v114, v115
	v_mul_f32_e32 v115, 0xbfb8aa3b, v120
	v_exp_f32_e32 v115, v115
	s_nop 0
	v_add_f32_e32 v115, 1.0, v115
	v_rcp_f32_e32 v118, v115
	v_mul_f32_e32 v115, 0xbfb8aa3b, v121
	v_exp_f32_e32 v115, v115
	s_nop 0
	v_add_f32_e32 v115, 1.0, v115
	v_rcp_f32_e32 v119, v115
	s_nop 0
	v_pk_mul_f32 v[118:119], v[120:121], v[118:119]
	s_nop 0
	v_pk_mul_f32 v[116:117], v[118:119], v[116:117]
	s_nop 0
	v_cvt_pk_bf16_f32 v115, v116, v117
	global_store_dwordx2 v[128:129], v[114:115], off offset:32
	v_mul_f32_e32 v114, 0xbfb8aa3b, v110
	v_mul_f32_e32 v115, 0xbfb8aa3b, v111
	v_exp_f32_e32 v114, v114
	v_exp_f32_e32 v115, v115
	v_or_b32_e32 v116, 16, v142
	v_add_f32_e32 v114, 1.0, v114
	v_add_f32_e32 v115, 1.0, v115
	v_rcp_f32_e32 v114, v114
	v_rcp_f32_e32 v115, v115
	s_nop 0
	v_pk_mul_f32 v[110:111], v[110:111], v[114:115]
	s_nop 0
	v_pk_mul_f32 v[106:107], v[110:111], v[106:107]
	s_nop 0
	v_cvt_pk_bf16_f32 v106, v106, v107
	v_mul_f32_e32 v107, 0xbfb8aa3b, v112
	v_exp_f32_e32 v107, v107
	s_nop 0
	v_add_f32_e32 v107, 1.0, v107
	v_rcp_f32_e32 v110, v107
	v_mul_f32_e32 v107, 0xbfb8aa3b, v113
	v_exp_f32_e32 v107, v107
	s_nop 0
	v_add_f32_e32 v107, 1.0, v107
	v_rcp_f32_e32 v111, v107
	s_nop 0
; __device__ __forceinline__ float silu_f(float x) { return x * sigm(x); }
;   __device__ __forceinline__ void operator()(const f32x4 (&acc)[2][2][4][2], const Unit& u, int wr, int wc, int fr, int fq) const {
;     ...
;         const int r = u.pm * 256 + ai * 128 + wr * 64 + m * 16 + fr;
; #pragma unroll
;         for (int n = 0; n < 2; ++n) {
;           const f32x4 g = acc[ai][0][m][n], up = acc[ai][1][m][n];
;           const int c = u.pn * 128 + wc * 32 + n * 16 + 4 * fq;
;           uint2 w;
;           w.x = pack2(silu_f(g[0]) * up[0], silu_f(g[1]) * up[1]);
;           w.y = pack2(silu_f(g[2]) * up[2], silu_f(g[3]) * up[3]);
;           *reinterpret_cast<uint2*>(HID + (size_t)r * DFF + c) = w;
;         }
	v_pk_mul_f32 v[110:111], v[112:113], v[110:111]
	s_nop 0
	v_pk_mul_f32 v[108:109], v[110:111], v[108:109]
	s_nop 0
	v_cvt_pk_bf16_f32 v107, v108, v109
	v_mad_i64_i32 v[108:109], s[18:19], v116, s50, v[122:123]
	v_lshl_add_u64 v[108:109], v[108:109], 0, v[124:125]
	global_store_dwordx2 v[108:109], v[106:107], off
	v_mul_f32_e32 v106, 0xbfb8aa3b, v102
	v_mul_f32_e32 v107, 0xbfb8aa3b, v103
	v_exp_f32_e32 v106, v106
	v_exp_f32_e32 v107, v107
	v_add_f32_e32 v106, 1.0, v106
	v_add_f32_e32 v107, 1.0, v107
	v_rcp_f32_e32 v106, v106
	v_rcp_f32_e32 v107, v107
	s_nop 0
	v_pk_mul_f32 v[102:103], v[102:103], v[106:107]
	s_nop 0
	v_pk_mul_f32 v[98:99], v[102:103], v[98:99]
	s_nop 0
	v_cvt_pk_bf16_f32 v98, v98, v99
	v_mul_f32_e32 v99, 0xbfb8aa3b, v104
	v_exp_f32_e32 v99, v99
	s_nop 0
	v_add_f32_e32 v99, 1.0, v99
	v_rcp_f32_e32 v102, v99
	v_mul_f32_e32 v99, 0xbfb8aa3b, v105
	v_exp_f32_e32 v99, v99
	s_nop 0
	v_add_f32_e32 v99, 1.0, v99
	v_rcp_f32_e32 v103, v99
	s_nop 0
	v_pk_mul_f32 v[102:103], v[104:105], v[102:103]
	s_nop 0
	v_pk_mul_f32 v[100:101], v[102:103], v[100:101]
	s_nop 0
	v_cvt_pk_bf16_f32 v99, v100, v101
	global_store_dwordx2 v[108:109], v[98:99], off offset:32
	v_mul_f32_e32 v98, 0xbfb8aa3b, v94
	v_mul_f32_e32 v99, 0xbfb8aa3b, v95
	v_exp_f32_e32 v98, v98
	v_exp_f32_e32 v99, v99
	v_or_b32_e32 v100, 32, v142
	v_add_f32_e32 v98, 1.0, v98
	v_add_f32_e32 v99, 1.0, v99
	v_rcp_f32_e32 v98, v98
	v_rcp_f32_e32 v99, v99
	s_nop 0
	v_pk_mul_f32 v[94:95], v[94:95], v[98:99]
	s_nop 0
	v_pk_mul_f32 v[90:91], v[94:95], v[90:91]
	s_nop 0
	v_cvt_pk_bf16_f32 v90, v90, v91
	v_mul_f32_e32 v91, 0xbfb8aa3b, v96
	v_exp_f32_e32 v91, v91
	s_nop 0
	v_add_f32_e32 v91, 1.0, v91
	v_rcp_f32_e32 v94, v91
	v_mul_f32_e32 v91, 0xbfb8aa3b, v97
	v_exp_f32_e32 v91, v91
	s_nop 0
	v_add_f32_e32 v91, 1.0, v91
	v_rcp_f32_e32 v95, v91
	s_nop 0
	v_pk_mul_f32 v[94:95], v[96:97], v[94:95]
	s_nop 0
	v_pk_mul_f32 v[92:93], v[94:95], v[92:93]
	s_nop 0
	v_cvt_pk_bf16_f32 v91, v92, v93
	v_mad_i64_i32 v[92:93], s[18:19], v100, s50, v[122:123]
	v_lshl_add_u64 v[92:93], v[92:93], 0, v[124:125]
	global_store_dwordx2 v[92:93], v[90:91], off
	v_mul_f32_e32 v90, 0xbfb8aa3b, v86
	v_mul_f32_e32 v91, 0xbfb8aa3b, v87
	v_exp_f32_e32 v90, v90
	v_exp_f32_e32 v91, v91
	v_add_f32_e32 v90, 1.0, v90
	v_add_f32_e32 v91, 1.0, v91
	v_rcp_f32_e32 v90, v90
	v_rcp_f32_e32 v91, v91
	s_nop 0
	v_pk_mul_f32 v[86:87], v[86:87], v[90:91]
	s_nop 0
	v_pk_mul_f32 v[82:83], v[86:87], v[82:83]
	s_nop 0
	v_cvt_pk_bf16_f32 v82, v82, v83
	v_mul_f32_e32 v83, 0xbfb8aa3b, v88
	v_exp_f32_e32 v83, v83
	s_nop 0
	v_add_f32_e32 v83, 1.0, v83
	v_rcp_f32_e32 v86, v83
	v_mul_f32_e32 v83, 0xbfb8aa3b, v89
	v_exp_f32_e32 v83, v83
	s_nop 0
	v_add_f32_e32 v83, 1.0, v83
	v_rcp_f32_e32 v87, v83
	s_nop 0
	v_pk_mul_f32 v[86:87], v[88:89], v[86:87]
	s_nop 0
	v_pk_mul_f32 v[84:85], v[86:87], v[84:85]
	s_nop 0
	v_cvt_pk_bf16_f32 v83, v84, v85
	global_store_dwordx2 v[92:93], v[82:83], off offset:32
	v_mul_f32_e32 v82, 0xbfb8aa3b, v78
	v_mul_f32_e32 v83, 0xbfb8aa3b, v79
	v_exp_f32_e32 v82, v82
	v_exp_f32_e32 v83, v83
	v_or_b32_e32 v84, 48, v142
	v_add_f32_e32 v82, 1.0, v82
	v_add_f32_e32 v83, 1.0, v83
	v_rcp_f32_e32 v82, v82
	v_rcp_f32_e32 v83, v83
	s_nop 0
	v_pk_mul_f32 v[78:79], v[78:79], v[82:83]
	s_nop 0
	v_pk_mul_f32 v[74:75], v[78:79], v[74:75]
	s_nop 0
	v_cvt_pk_bf16_f32 v74, v74, v75
	v_mul_f32_e32 v75, 0xbfb8aa3b, v80
	v_exp_f32_e32 v75, v75
	s_nop 0
	v_add_f32_e32 v75, 1.0, v75
	v_rcp_f32_e32 v78, v75
	v_mul_f32_e32 v75, 0xbfb8aa3b, v81
	v_exp_f32_e32 v75, v75
	s_nop 0
	v_add_f32_e32 v75, 1.0, v75
	v_rcp_f32_e32 v79, v75
	s_nop 0
	v_pk_mul_f32 v[78:79], v[80:81], v[78:79]
	s_nop 0
	v_pk_mul_f32 v[76:77], v[78:79], v[76:77]
	s_nop 0
	v_cvt_pk_bf16_f32 v75, v76, v77
	v_mad_i64_i32 v[76:77], s[18:19], v84, s50, v[122:123]
	v_lshl_add_u64 v[76:77], v[76:77], 0, v[124:125]
	global_store_dwordx2 v[76:77], v[74:75], off
	v_mul_f32_e32 v74, 0xbfb8aa3b, v70
	v_mul_f32_e32 v75, 0xbfb8aa3b, v71
	v_exp_f32_e32 v74, v74
	v_exp_f32_e32 v75, v75
	v_add_f32_e32 v74, 1.0, v74
	v_add_f32_e32 v75, 1.0, v75
	v_rcp_f32_e32 v74, v74
	v_rcp_f32_e32 v75, v75
	s_nop 0
	v_pk_mul_f32 v[70:71], v[70:71], v[74:75]
	s_nop 0
	v_pk_mul_f32 v[66:67], v[70:71], v[66:67]
	s_nop 0
	v_cvt_pk_bf16_f32 v66, v66, v67
	v_mul_f32_e32 v67, 0xbfb8aa3b, v72
	v_exp_f32_e32 v67, v67
	s_nop 0
	v_add_f32_e32 v67, 1.0, v67
	v_rcp_f32_e32 v70, v67
	v_mul_f32_e32 v67, 0xbfb8aa3b, v73
	v_exp_f32_e32 v67, v67
	s_nop 0
	v_add_f32_e32 v67, 1.0, v67
	v_rcp_f32_e32 v71, v67
	s_nop 0
	v_pk_mul_f32 v[70:71], v[72:73], v[70:71]
	s_nop 0
	v_pk_mul_f32 v[68:69], v[70:71], v[68:69]
	s_nop 0
	v_cvt_pk_bf16_f32 v67, v68, v69
	global_store_dwordx2 v[76:77], v[66:67], off offset:32
	v_mul_f32_e32 v66, 0xbfb8aa3b, v62
	v_mul_f32_e32 v67, 0xbfb8aa3b, v63
	v_exp_f32_e32 v66, v66
	v_exp_f32_e32 v67, v67
	v_add_u32_e32 v68, 0x80, v142
	v_add_f32_e32 v66, 1.0, v66
	v_add_f32_e32 v67, 1.0, v67
	v_rcp_f32_e32 v66, v66
	v_rcp_f32_e32 v67, v67
	s_nop 0
	v_pk_mul_f32 v[62:63], v[62:63], v[66:67]
	s_nop 0
	v_pk_mul_f32 v[58:59], v[62:63], v[58:59]
	s_nop 0
	v_cvt_pk_bf16_f32 v58, v58, v59
	v_mul_f32_e32 v59, 0xbfb8aa3b, v64
	v_exp_f32_e32 v59, v59
	s_nop 0
	v_add_f32_e32 v59, 1.0, v59
	v_rcp_f32_e32 v62, v59
	v_mul_f32_e32 v59, 0xbfb8aa3b, v65
	v_exp_f32_e32 v59, v59
	s_nop 0
	v_add_f32_e32 v59, 1.0, v59
	v_rcp_f32_e32 v63, v59
	s_nop 0
	v_pk_mul_f32 v[62:63], v[64:65], v[62:63]
	s_nop 0
	v_pk_mul_f32 v[60:61], v[62:63], v[60:61]
	s_nop 0
	v_cvt_pk_bf16_f32 v59, v60, v61
	v_mad_i64_i32 v[60:61], s[18:19], v68, s50, v[122:123]
	v_lshl_add_u64 v[60:61], v[60:61], 0, v[124:125]
	global_store_dwordx2 v[60:61], v[58:59], off
; __device__ __forceinline__ float silu_f(float x) { return x * sigm(x); }
; #define PG8_WAIT_V(n) asm volatile("s_waitcnt vmcnt(" #n ")" ::: "memory")
; #define PG8_BAR __builtin_amdgcn_s_barrier()
;   __device__ __forceinline__ int kt(const Unit& u) const { return ((u.pn & 7) < 4) ? 4 : 16; }
; template <class Epi, class Sched>
; __device__ __forceinline__ void gemm_phase(PG8_LAS unsigned char* lds, const int lda, const int ldb, const Sched& S, const Epi& E) {
;     ...
;     cur = nxt; cA = nA; cB = nB; ++ui;
;     nt = S.kt(cur);
;   }
;   PG8_WAIT_V(0);
;   if (wr == 0) PG8_BAR;
;   PG8_BAR;
;   __device__ __forceinline__ void operator()(const f32x4 (&acc)[2][2][4][2], const Unit& u, int wr, int wc, int fr, int fq) const {
;     ...
;         const int r = u.pm * 256 + ai * 128 + wr * 64 + m * 16 + fr;
; #pragma unroll
;         for (int n = 0; n < 2; ++n) {
;           const f32x4 g = acc[ai][0][m][n], up = acc[ai][1][m][n];
;           const int c = u.pn * 128 + wc * 32 + n * 16 + 4 * fq;
;           uint2 w;
;           w.x = pack2(silu_f(g[0]) * up[0], silu_f(g[1]) * up[1]);
;           w.y = pack2(silu_f(g[2]) * up[2], silu_f(g[3]) * up[3]);
;           *reinterpret_cast<uint2*>(HID + (size_t)r * DFF + c) = w;
;         }
	v_mul_f32_e32 v58, 0xbfb8aa3b, v54
	v_mul_f32_e32 v59, 0xbfb8aa3b, v55
	v_exp_f32_e32 v58, v58
	v_exp_f32_e32 v59, v59
	v_add_f32_e32 v58, 1.0, v58
	v_add_f32_e32 v59, 1.0, v59
	v_rcp_f32_e32 v58, v58
	v_rcp_f32_e32 v59, v59
	s_nop 0
	v_pk_mul_f32 v[54:55], v[54:55], v[58:59]
	s_nop 0
	v_pk_mul_f32 v[50:51], v[54:55], v[50:51]
	s_nop 0
	v_cvt_pk_bf16_f32 v50, v50, v51
	v_mul_f32_e32 v51, 0xbfb8aa3b, v56
	v_exp_f32_e32 v51, v51
	s_nop 0
	v_add_f32_e32 v51, 1.0, v51
	v_rcp_f32_e32 v54, v51
	v_mul_f32_e32 v51, 0xbfb8aa3b, v57
	v_exp_f32_e32 v51, v51
	s_nop 0
	v_add_f32_e32 v51, 1.0, v51
	v_rcp_f32_e32 v55, v51
	s_nop 0
	v_pk_mul_f32 v[54:55], v[56:57], v[54:55]
	s_nop 0
	v_pk_mul_f32 v[52:53], v[54:55], v[52:53]
	s_nop 0
	v_cvt_pk_bf16_f32 v51, v52, v53
	global_store_dwordx2 v[60:61], v[50:51], off offset:32
	v_mul_f32_e32 v50, 0xbfb8aa3b, v46
	v_mul_f32_e32 v51, 0xbfb8aa3b, v47
	v_exp_f32_e32 v50, v50
	v_exp_f32_e32 v51, v51
	v_add_u32_e32 v52, 0x90, v142
	v_add_f32_e32 v50, 1.0, v50
	v_add_f32_e32 v51, 1.0, v51
	v_rcp_f32_e32 v50, v50
	v_rcp_f32_e32 v51, v51
	s_nop 0
	v_pk_mul_f32 v[46:47], v[46:47], v[50:51]
	s_nop 0
	v_pk_mul_f32 v[42:43], v[46:47], v[42:43]
	s_nop 0
	v_cvt_pk_bf16_f32 v42, v42, v43
	v_mul_f32_e32 v43, 0xbfb8aa3b, v48
	v_exp_f32_e32 v43, v43
	s_nop 0
	v_add_f32_e32 v43, 1.0, v43
	v_rcp_f32_e32 v46, v43
	v_mul_f32_e32 v43, 0xbfb8aa3b, v49
	v_exp_f32_e32 v43, v43
	s_nop 0
	v_add_f32_e32 v43, 1.0, v43
	v_rcp_f32_e32 v47, v43
	s_nop 0
	v_pk_mul_f32 v[46:47], v[48:49], v[46:47]
	s_nop 0
	v_pk_mul_f32 v[44:45], v[46:47], v[44:45]
	s_nop 0
	v_cvt_pk_bf16_f32 v43, v44, v45
	v_mad_i64_i32 v[44:45], s[18:19], v52, s50, v[122:123]
	v_lshl_add_u64 v[44:45], v[44:45], 0, v[124:125]
	global_store_dwordx2 v[44:45], v[42:43], off
	v_mul_f32_e32 v42, 0xbfb8aa3b, v38
	v_mul_f32_e32 v43, 0xbfb8aa3b, v39
	v_exp_f32_e32 v42, v42
	v_exp_f32_e32 v43, v43
	v_add_f32_e32 v42, 1.0, v42
	v_add_f32_e32 v43, 1.0, v43
	v_rcp_f32_e32 v42, v42
	v_rcp_f32_e32 v43, v43
	s_nop 0
	v_pk_mul_f32 v[38:39], v[38:39], v[42:43]
	s_nop 0
	v_pk_mul_f32 v[34:35], v[38:39], v[34:35]
	s_nop 0
	v_cvt_pk_bf16_f32 v34, v34, v35
	v_mul_f32_e32 v35, 0xbfb8aa3b, v40
	v_exp_f32_e32 v35, v35
	s_nop 0
	v_add_f32_e32 v35, 1.0, v35
	v_rcp_f32_e32 v38, v35
	v_mul_f32_e32 v35, 0xbfb8aa3b, v41
	v_exp_f32_e32 v35, v35
	s_nop 0
	v_add_f32_e32 v35, 1.0, v35
	v_rcp_f32_e32 v39, v35
	s_nop 0
	v_pk_mul_f32 v[38:39], v[40:41], v[38:39]
	s_nop 0
	v_pk_mul_f32 v[36:37], v[38:39], v[36:37]
	s_nop 0
	v_cvt_pk_bf16_f32 v35, v36, v37
	global_store_dwordx2 v[44:45], v[34:35], off offset:32
	v_mul_f32_e32 v34, 0xbfb8aa3b, v30
	v_mul_f32_e32 v35, 0xbfb8aa3b, v31
	v_exp_f32_e32 v34, v34
	v_exp_f32_e32 v35, v35
	v_add_u32_e32 v36, 0xa0, v142
	v_add_f32_e32 v34, 1.0, v34
	v_add_f32_e32 v35, 1.0, v35
	v_rcp_f32_e32 v34, v34
	v_rcp_f32_e32 v35, v35
	s_nop 0
	v_pk_mul_f32 v[30:31], v[30:31], v[34:35]
	s_nop 0
	v_pk_mul_f32 v[26:27], v[30:31], v[26:27]
	s_nop 0
	v_cvt_pk_bf16_f32 v26, v26, v27
	v_mul_f32_e32 v27, 0xbfb8aa3b, v32
	v_exp_f32_e32 v27, v27
	s_nop 0
	v_add_f32_e32 v27, 1.0, v27
	v_rcp_f32_e32 v30, v27
	v_mul_f32_e32 v27, 0xbfb8aa3b, v33
	v_exp_f32_e32 v27, v27
	s_nop 0
	v_add_f32_e32 v27, 1.0, v27
	v_rcp_f32_e32 v31, v27
	s_nop 0
	v_pk_mul_f32 v[30:31], v[32:33], v[30:31]
	s_nop 0
	v_pk_mul_f32 v[28:29], v[30:31], v[28:29]
	s_nop 0
	v_cvt_pk_bf16_f32 v27, v28, v29
	v_mad_i64_i32 v[28:29], s[18:19], v36, s50, v[122:123]
	v_lshl_add_u64 v[28:29], v[28:29], 0, v[124:125]
	global_store_dwordx2 v[28:29], v[26:27], off
	v_mul_f32_e32 v26, 0xbfb8aa3b, v22
	v_mul_f32_e32 v27, 0xbfb8aa3b, v23
	v_exp_f32_e32 v26, v26
	v_exp_f32_e32 v27, v27
	v_add_f32_e32 v26, 1.0, v26
	v_add_f32_e32 v27, 1.0, v27
	v_rcp_f32_e32 v26, v26
	v_rcp_f32_e32 v27, v27
	s_nop 0
	v_pk_mul_f32 v[22:23], v[22:23], v[26:27]
	s_nop 0
	v_pk_mul_f32 v[18:19], v[22:23], v[18:19]
	s_nop 0
	v_cvt_pk_bf16_f32 v18, v18, v19
	v_mul_f32_e32 v19, 0xbfb8aa3b, v24
	v_exp_f32_e32 v19, v19
	s_nop 0
	v_add_f32_e32 v19, 1.0, v19
	v_rcp_f32_e32 v22, v19
	v_mul_f32_e32 v19, 0xbfb8aa3b, v25
	v_exp_f32_e32 v19, v19
	s_nop 0
	v_add_f32_e32 v19, 1.0, v19
	v_rcp_f32_e32 v23, v19
	s_nop 0
	v_pk_mul_f32 v[22:23], v[24:25], v[22:23]
	s_nop 0
	v_pk_mul_f32 v[20:21], v[22:23], v[20:21]
	s_nop 0
	v_cvt_pk_bf16_f32 v19, v20, v21
	global_store_dwordx2 v[28:29], v[18:19], off offset:32
	v_mul_f32_e32 v18, 0xbfb8aa3b, v14
	v_mul_f32_e32 v19, 0xbfb8aa3b, v15
	v_exp_f32_e32 v18, v18
	v_exp_f32_e32 v19, v19
	v_add_u32_e32 v20, 0xb0, v142
	v_add_f32_e32 v18, 1.0, v18
	v_add_f32_e32 v19, 1.0, v19
	v_rcp_f32_e32 v18, v18
	v_rcp_f32_e32 v19, v19
	s_nop 0
	v_pk_mul_f32 v[14:15], v[14:15], v[18:19]
	s_nop 0
	v_pk_mul_f32 v[10:11], v[14:15], v[10:11]
	s_nop 0
	v_cvt_pk_bf16_f32 v10, v10, v11
	v_mul_f32_e32 v11, 0xbfb8aa3b, v16
	v_exp_f32_e32 v11, v11
	s_nop 0
	v_add_f32_e32 v11, 1.0, v11
	v_rcp_f32_e32 v14, v11
	v_mul_f32_e32 v11, 0xbfb8aa3b, v17
	v_exp_f32_e32 v11, v11
	s_nop 0
	v_add_f32_e32 v11, 1.0, v11
	v_rcp_f32_e32 v15, v11
	s_nop 0
	v_pk_mul_f32 v[14:15], v[16:17], v[14:15]
	s_nop 0
	v_pk_mul_f32 v[12:13], v[14:15], v[12:13]
	s_nop 0
	v_cvt_pk_bf16_f32 v11, v12, v13
	v_mad_i64_i32 v[12:13], s[18:19], v20, s50, v[122:123]
	v_lshl_add_u64 v[12:13], v[12:13], 0, v[124:125]
	global_store_dwordx2 v[12:13], v[10:11], off
	v_mul_f32_e32 v10, 0xbfb8aa3b, v6
	v_mul_f32_e32 v11, 0xbfb8aa3b, v7
	v_exp_f32_e32 v10, v10
	v_exp_f32_e32 v11, v11
	s_mov_b64 s[18:19], s[12:13]
	v_add_f32_e32 v10, 1.0, v10
	v_add_f32_e32 v11, 1.0, v11
	v_rcp_f32_e32 v10, v10
	v_rcp_f32_e32 v11, v11
	s_nop 0
	v_pk_mul_f32 v[6:7], v[6:7], v[10:11]
	s_nop 0
	v_pk_mul_f32 v[2:3], v[6:7], v[2:3]
	s_nop 0
	v_cvt_pk_bf16_f32 v2, v2, v3
	v_mul_f32_e32 v3, 0xbfb8aa3b, v8
	v_exp_f32_e32 v3, v3
	s_nop 0
	v_add_f32_e32 v3, 1.0, v3
	v_rcp_f32_e32 v6, v3
	v_mul_f32_e32 v3, 0xbfb8aa3b, v9
	v_exp_f32_e32 v3, v3
	s_nop 0
	v_add_f32_e32 v3, 1.0, v3
	v_rcp_f32_e32 v7, v3
	s_nop 0
	v_pk_mul_f32 v[6:7], v[8:9], v[6:7]
	s_nop 0
	v_pk_mul_f32 v[4:5], v[6:7], v[4:5]
	s_nop 0
	v_cvt_pk_bf16_f32 v3, v4, v5
	global_store_dwordx2 v[12:13], v[2:3], off offset:32
	s_cbranch_vccz .LBB0_1601
	s_waitcnt vmcnt(0)
	v_readlane_b32 s40, v253, 12
	s_cmpk_gt_u32 s9, 0xff
	v_readlane_b32 s41, v253, 13
	v_readlane_b32 s44, v253, 16
	v_readlane_b32 s45, v253, 17
	v_readlane_b32 s52, v253, 24
	v_readlane_b32 s53, v253, 25
	v_readlane_b32 s54, v253, 26
	v_readlane_b32 s55, v253, 27
	v_readlane_b32 s38, v255, 23
	v_readlane_b32 s42, v253, 14
	v_readlane_b32 s43, v253, 15
	v_readlane_b32 s46, v253, 18
	v_readlane_b32 s47, v253, 19
	v_readlane_b32 s48, v253, 20
	v_readlane_b32 s49, v253, 21
	v_readlane_b32 s50, v253, 22
	v_readlane_b32 s51, v253, 23
	v_readlane_b32 s39, v255, 24
	s_cbranch_scc1 .LBB0_1608
	s_barrier

; #define PG8_STAGE(bufoff, gbase, voff) do { _Pragma("unroll") for (int _i = 0; _i < 2; ++_i) \
;     __builtin_amdgcn_global_load_lds((const unsigned*)((const char*)(gbase) + (voff)[_i]), (PG8_LAS unsigned*)(lds + (bufoff) + ldsw + _i * 8192), 16, 0, 0); } while (0)
; #define PG8_LDA(dst, b, h) do { _Pragma("unroll") for (int m = 0; m < 4; ++m) _Pragma("unroll") for (int k = 0; k < 2; ++k) dst[m][k] = *(const PG8_LAS bf16x8*)(lds + PG8_SA(b, h) + aoff + m * 2048 + k * 1024); } while (0)
; #define PG8_LDB(dst, b, h) do { _Pragma("unroll") for (int n = 0; n < 2; ++n) _Pragma("unroll") for (int k = 0; k < 2; ++k) dst[n][k] = *(const PG8_LAS bf16x8*)(lds + PG8_SB(b, h) + boff + n * 2048 + k * 1024); } while (0)
; #define PG8_MMA(ai, bj, At, Bt) do { __builtin_amdgcn_s_setprio(1); _Pragma("unroll") for (int m = 0; m < 4; ++m) _Pragma("unroll") for (int n = 0; n < 2; ++n) _Pragma("unroll") for (int k = 0; k < 2; ++k) \
;     acc[ai][bj][m][n] = __builtin_amdgcn_mfma_f32_16x16x32_bf16(Bt[n][k], At[m][k], acc[ai][bj][m][n], 0, 0, 0); __builtin_amdgcn_s_setprio(0); } while (0)
; #define PG8_WAIT_L(n) asm volatile("s_waitcnt lgkmcnt(" #n ")" ::: "memory")
; #define PG8_BAR __builtin_amdgcn_s_barrier()
; #define PG8_SCHED __builtin_amdgcn_sched_barrier(0)
; template <class Epi, class Sched>
; __device__ __forceinline__ void gemm_phase(PG8_LAS unsigned char* lds, const int lda, const int ldb, const Sched& S, const Epi& E) {
;     ...
;     for (int t = 0; t < nt; t += 2) {
;       const bool last = (t == nt - 2);
;       const char* a1 = cA + (size_t)(t + 1) * kstep;
;       const char* a2 = last ? nA : cA + (size_t)(t + 2) * kstep; const char* b2 = last ? nB : cB + (size_t)(t + 2) * kstep;
;       const char* a3 = a2 + kstep; const char* b3 = b2 + kstep;
;       PG8_LDB(B0, 0, 0); PG8_SCHED; PG8_LDA(At, 0, 0); PG8_STAGE(PG8_SA(1, 1), a1 + hstepA, voffA);
;       PG8_WAIT_L(8); PG8_BAR; PG8_WAIT_L(0); PG8_MMA(0, 0, At, B0); PG8_BAR; PG8_SCHED;
;       PG8_LDB(B1, 0, 1); PG8_STAGE(PG8_SB(0, 0), b2, voffB);
;       PG8_BAR; PG8_WAIT_L(0); PG8_MMA(0, 1, At, B1); PG8_BAR;
;       PG8_LDA(At, 0, 1); PG8_STAGE(PG8_SA(0, 0), a2, voffA);
;       PG8_BAR; PG8_WAIT_L(0); PG8_MMA(1, 0, At, B0); PG8_BAR; PG8_SCHED;
.LBB0_1673:
	s_add_u32 s12, s10, 0x100
	s_addc_u32 s13, s11, 0
	s_add_i32 s33, 0, 0x10000
	v_add_u32_e32 v154, s33, v131
	ds_read_b128 v[140:143], v154
	ds_read_b128 v[146:149], v154 offset:1024
	ds_read_b128 v[150:153], v154 offset:2048
	ds_read_b128 v[154:157], v154 offset:3072
	s_cmp_eq_u32 s41, 40
	s_cselect_b32 s17, s7, s13
	s_cselect_b32 s16, s6, s12
	s_cselect_b32 s15, s1, s40
	s_cselect_b32 s14, s0, s39
	v_lshl_add_u64 v[174:175], s[10:11], 0, v[136:137]
	s_add_i32 m0, s23, 0xc000
	ds_read_b128 v[158:161], v145
	ds_read_b128 v[162:165], v145 offset:1024
	ds_read_b128 v[166:169], v145 offset:2048
	ds_read_b128 v[170:173], v145 offset:3072
	ds_read_b128 v[200:203], v145 offset:4096
	ds_read_b128 v[204:207], v145 offset:5120
	ds_read_b128 v[208:211], v145 offset:6144
	ds_read_b128 v[212:215], v145 offset:7168
	global_load_lds_dwordx4 v[174:175], off
	v_lshl_add_u64 v[174:175], s[10:11], 0, v[138:139]
	s_add_i32 m0, s23, 0xe000
	s_nop 0
	global_load_lds_dwordx4 v[174:175], off
	s_waitcnt lgkmcnt(8)
	s_setprio 1
	s_barrier
	s_waitcnt lgkmcnt(0)
	v_mfma_f32_16x16x32_bf16 v[126:129], v[140:143], v[158:161], v[126:129]
	v_mfma_f32_16x16x32_bf16 v[122:125], v[150:153], v[158:161], v[122:125]
	v_mfma_f32_16x16x32_bf16 v[110:113], v[140:143], v[166:169], v[110:113]
	v_mfma_f32_16x16x32_bf16 v[106:109], v[150:153], v[166:169], v[106:109]
	v_mfma_f32_16x16x32_bf16 v[94:97], v[140:143], v[200:203], v[94:97]
	v_mfma_f32_16x16x32_bf16 v[90:93], v[150:153], v[200:203], v[90:93]
	v_mfma_f32_16x16x32_bf16 v[78:81], v[140:143], v[208:211], v[78:81]
	v_mfma_f32_16x16x32_bf16 v[74:77], v[150:153], v[208:211], v[74:77]
	v_mfma_f32_16x16x32_bf16 v[126:129], v[146:149], v[162:165], v[126:129]
	v_mfma_f32_16x16x32_bf16 v[122:125], v[154:157], v[162:165], v[122:125]
	v_mfma_f32_16x16x32_bf16 v[110:113], v[146:149], v[170:173], v[110:113]
	v_mfma_f32_16x16x32_bf16 v[106:109], v[154:157], v[170:173], v[106:109]
	v_mfma_f32_16x16x32_bf16 v[94:97], v[146:149], v[204:207], v[94:97]
	v_mfma_f32_16x16x32_bf16 v[90:93], v[154:157], v[204:207], v[90:93]
	v_mfma_f32_16x16x32_bf16 v[78:81], v[146:149], v[212:215], v[78:81]
	v_mfma_f32_16x16x32_bf16 v[74:77], v[154:157], v[212:215], v[74:77]
	s_setprio 0
	s_barrier
	s_add_i32 s42, 0, 0x14000
	v_add_u32_e32 v174, s42, v131
	s_add_i32 s10, s33, s20
	ds_read_b128 v[216:219], v174
	ds_read_b128 v[220:223], v174 offset:1024
	ds_read_b128 v[224:227], v174 offset:2048
	ds_read_b128 v[228:231], v174 offset:3072
	v_lshl_add_u64 v[174:175], s[14:15], 0, v[134:135]
	s_mov_b32 m0, s10
	v_lshl_add_u64 v[182:183], s[14:15], 0, v[132:133]
	global_load_lds_dwordx4 v[174:175], off
	s_add_i32 m0, s10, 0x2000
	s_nop 0
	global_load_lds_dwordx4 v[182:183], off
	s_setprio 1
	s_barrier
	s_waitcnt lgkmcnt(0)
	v_mfma_f32_16x16x32_bf16 v[118:121], v[216:219], v[158:161], v[118:121]
	v_mfma_f32_16x16x32_bf16 v[114:117], v[224:227], v[158:161], v[114:117]
	v_mfma_f32_16x16x32_bf16 v[102:105], v[216:219], v[166:169], v[102:105]
	v_mfma_f32_16x16x32_bf16 v[98:101], v[224:227], v[166:169], v[98:101]
	v_mfma_f32_16x16x32_bf16 v[86:89], v[216:219], v[200:203], v[86:89]
	v_mfma_f32_16x16x32_bf16 v[82:85], v[224:227], v[200:203], v[82:85]
	v_mfma_f32_16x16x32_bf16 v[70:73], v[216:219], v[208:211], v[70:73]
	v_mfma_f32_16x16x32_bf16 v[66:69], v[224:227], v[208:211], v[66:69]
	v_mfma_f32_16x16x32_bf16 v[118:121], v[220:223], v[162:165], v[118:121]
	v_mfma_f32_16x16x32_bf16 v[114:117], v[228:231], v[162:165], v[114:117]
	v_mfma_f32_16x16x32_bf16 v[102:105], v[220:223], v[170:173], v[102:105]
	v_mfma_f32_16x16x32_bf16 v[98:101], v[228:231], v[170:173], v[98:101]
	v_mfma_f32_16x16x32_bf16 v[86:89], v[220:223], v[204:207], v[86:89]
	v_mfma_f32_16x16x32_bf16 v[82:85], v[228:231], v[204:207], v[82:85]
	v_mfma_f32_16x16x32_bf16 v[70:73], v[220:223], v[212:215], v[70:73]
	v_mfma_f32_16x16x32_bf16 v[66:69], v[228:231], v[212:215], v[66:69]
	s_setprio 0
	s_mov_b32 m0, s23
	v_lshl_add_u64 v[184:185], s[16:17], 0, v[134:135]
	s_barrier
	ds_read_b128 v[158:161], v145 offset:16384
	ds_read_b128 v[162:165], v145 offset:17408
	ds_read_b128 v[166:169], v145 offset:18432
	ds_read_b128 v[170:173], v145 offset:19456
	ds_read_b128 v[200:203], v145 offset:20480
	ds_read_b128 v[204:207], v145 offset:21504
	ds_read_b128 v[208:211], v145 offset:22528
	ds_read_b128 v[212:215], v145 offset:23552
	global_load_lds_dwordx4 v[184:185], off
	v_lshl_add_u64 v[232:233], s[16:17], 0, v[132:133]
	s_mov_b32 m0, s24
	s_nop 0
	global_load_lds_dwordx4 v[232:233], off
	s_setprio 1
	s_barrier
	s_waitcnt lgkmcnt(0)
	v_mfma_f32_16x16x32_bf16 v[62:65], v[140:143], v[158:161], v[62:65]
	v_mfma_f32_16x16x32_bf16 v[58:61], v[150:153], v[158:161], v[58:61]
	v_mfma_f32_16x16x32_bf16 v[46:49], v[140:143], v[166:169], v[46:49]
	v_mfma_f32_16x16x32_bf16 v[42:45], v[150:153], v[166:169], v[42:45]
	v_mfma_f32_16x16x32_bf16 v[30:33], v[140:143], v[200:203], v[30:33]
	v_mfma_f32_16x16x32_bf16 v[26:29], v[150:153], v[200:203], v[26:29]
	v_mfma_f32_16x16x32_bf16 v[14:17], v[140:143], v[208:211], v[14:17]
	v_mfma_f32_16x16x32_bf16 v[10:13], v[150:153], v[208:211], v[10:13]
	v_mfma_f32_16x16x32_bf16 v[62:65], v[146:149], v[162:165], v[62:65]
	v_mfma_f32_16x16x32_bf16 v[58:61], v[154:157], v[162:165], v[58:61]
	v_mfma_f32_16x16x32_bf16 v[46:49], v[146:149], v[170:173], v[46:49]
	v_mfma_f32_16x16x32_bf16 v[42:45], v[154:157], v[170:173], v[42:45]
	v_mfma_f32_16x16x32_bf16 v[30:33], v[146:149], v[204:207], v[30:33]
	v_mfma_f32_16x16x32_bf16 v[26:29], v[154:157], v[204:207], v[26:29]
	v_mfma_f32_16x16x32_bf16 v[14:17], v[146:149], v[212:215], v[14:17]
	v_mfma_f32_16x16x32_bf16 v[10:13], v[154:157], v[212:215], v[10:13]
	s_setprio 0
	s_barrier
; #define PG8_STAGE(bufoff, gbase, voff) do { _Pragma("unroll") for (int _i = 0; _i < 2; ++_i) \
;     __builtin_amdgcn_global_load_lds((const unsigned*)((const char*)(gbase) + (voff)[_i]), (PG8_LAS unsigned*)(lds + (bufoff) + ldsw + _i * 8192), 16, 0, 0); } while (0)
; #define PG8_LDA(dst, b, h) do { _Pragma("unroll") for (int m = 0; m < 4; ++m) _Pragma("unroll") for (int k = 0; k < 2; ++k) dst[m][k] = *(const PG8_LAS bf16x8*)(lds + PG8_SA(b, h) + aoff + m * 2048 + k * 1024); } while (0)
; #define PG8_LDB(dst, b, h) do { _Pragma("unroll") for (int n = 0; n < 2; ++n) _Pragma("unroll") for (int k = 0; k < 2; ++k) dst[n][k] = *(const PG8_LAS bf16x8*)(lds + PG8_SB(b, h) + boff + n * 2048 + k * 1024); } while (0)
; #define PG8_MMA(ai, bj, At, Bt) do { __builtin_amdgcn_s_setprio(1); _Pragma("unroll") for (int m = 0; m < 4; ++m) _Pragma("unroll") for (int n = 0; n < 2; ++n) _Pragma("unroll") for (int k = 0; k < 2; ++k) \
;     acc[ai][bj][m][n] = __builtin_amdgcn_mfma_f32_16x16x32_bf16(Bt[n][k], At[m][k], acc[ai][bj][m][n], 0, 0, 0); __builtin_amdgcn_s_setprio(0); } while (0)
; #define PG8_WAIT_V(n) asm volatile("s_waitcnt vmcnt(" #n ")" ::: "memory")
; #define PG8_WAIT_L(n) asm volatile("s_waitcnt lgkmcnt(" #n ")" ::: "memory")
; #define PG8_BAR __builtin_amdgcn_s_barrier()
; #define PG8_SCHED __builtin_amdgcn_sched_barrier(0)
; template <class Epi, class Sched>
; __device__ __forceinline__ void gemm_phase(PG8_LAS unsigned char* lds, const int lda, const int ldb, const Sched& S, const Epi& E) {
;     ...
;       PG8_STAGE(PG8_SB(0, 1), b2 + hstepB, voffB);
;       PG8_WAIT_V(6); PG8_BAR; PG8_MMA(1, 1, At, B1); PG8_BAR;
;       PG8_LDB(B0, 1, 0); PG8_SCHED; PG8_LDA(At, 1, 0); PG8_STAGE(PG8_SA(0, 1), a2 + hstepA, voffA);
;       PG8_WAIT_L(8); PG8_BAR; PG8_WAIT_L(0); PG8_MMA(0, 0, At, B0); PG8_BAR; PG8_SCHED;
;       PG8_LDB(B1, 1, 1); PG8_STAGE(PG8_SB(1, 0), b3, voffB);
;       PG8_BAR; PG8_WAIT_L(0); PG8_MMA(0, 1, At, B1); PG8_BAR;
	s_add_u32 s10, s14, 0xb0000
	s_addc_u32 s11, s15, 0
	s_add_i32 s33, s42, s20
	v_lshl_add_u64 v[140:141], s[10:11], 0, v[134:135]
	s_mov_b32 m0, s33
	s_nop 0
	global_load_lds_dwordx4 v[140:141], off
	v_lshl_add_u64 v[140:141], s[10:11], 0, v[132:133]
	s_add_i32 m0, s33, 0x2000
	s_nop 0
	global_load_lds_dwordx4 v[140:141], off
	s_waitcnt vmcnt(6)
	s_setprio 1
	s_barrier
	v_mfma_f32_16x16x32_bf16 v[54:57], v[216:219], v[158:161], v[54:57]
	v_mfma_f32_16x16x32_bf16 v[50:53], v[224:227], v[158:161], v[50:53]
	v_mfma_f32_16x16x32_bf16 v[38:41], v[216:219], v[166:169], v[38:41]
	v_mfma_f32_16x16x32_bf16 v[34:37], v[224:227], v[166:169], v[34:37]
	v_mfma_f32_16x16x32_bf16 v[22:25], v[216:219], v[200:203], v[22:25]
	v_mfma_f32_16x16x32_bf16 v[18:21], v[224:227], v[200:203], v[18:21]
	v_mfma_f32_16x16x32_bf16 v[6:9], v[216:219], v[208:211], v[6:9]
	v_mfma_f32_16x16x32_bf16 v[2:5], v[224:227], v[208:211], v[2:5]
	v_mfma_f32_16x16x32_bf16 v[54:57], v[220:223], v[162:165], v[54:57]
	v_mfma_f32_16x16x32_bf16 v[50:53], v[228:231], v[162:165], v[50:53]
	v_mfma_f32_16x16x32_bf16 v[38:41], v[220:223], v[170:173], v[38:41]
	v_mfma_f32_16x16x32_bf16 v[34:37], v[228:231], v[170:173], v[34:37]
	v_mfma_f32_16x16x32_bf16 v[22:25], v[220:223], v[204:207], v[22:25]
	v_mfma_f32_16x16x32_bf16 v[18:21], v[228:231], v[204:207], v[18:21]
	v_mfma_f32_16x16x32_bf16 v[6:9], v[220:223], v[212:215], v[6:9]
	v_mfma_f32_16x16x32_bf16 v[2:5], v[228:231], v[212:215], v[2:5]
	s_setprio 0
	s_add_i32 s33, 0, 0x18000
	v_add_u32_e32 v154, s33, v131
	s_barrier
	ds_read_b128 v[140:143], v154
	ds_read_b128 v[146:149], v154 offset:1024
	ds_read_b128 v[150:153], v154 offset:2048
	ds_read_b128 v[154:157], v154 offset:3072
	s_add_u32 s10, s16, 0xb0000
	s_addc_u32 s11, s17, 0
	s_mov_b32 m0, s25
	v_lshl_add_u64 v[216:217], s[10:11], 0, v[134:135]
	ds_read_b128 v[158:161], v145 offset:32768
	ds_read_b128 v[162:165], v145 offset:33792
	ds_read_b128 v[166:169], v145 offset:34816
	ds_read_b128 v[170:173], v145 offset:35840
	ds_read_b128 v[200:203], v145 offset:36864
	ds_read_b128 v[204:207], v145 offset:37888
	ds_read_b128 v[208:211], v145 offset:38912
	ds_read_b128 v[212:215], v145 offset:39936
	global_load_lds_dwordx4 v[216:217], off
	v_lshl_add_u64 v[216:217], s[10:11], 0, v[132:133]
	s_mov_b32 m0, s26
	s_nop 0
	global_load_lds_dwordx4 v[216:217], off
	s_waitcnt lgkmcnt(8)
	s_setprio 1
	s_barrier
	s_waitcnt lgkmcnt(0)
	v_mfma_f32_16x16x32_bf16 v[126:129], v[140:143], v[158:161], v[126:129]
	v_mfma_f32_16x16x32_bf16 v[122:125], v[150:153], v[158:161], v[122:125]
	v_mfma_f32_16x16x32_bf16 v[110:113], v[140:143], v[166:169], v[110:113]
	v_mfma_f32_16x16x32_bf16 v[106:109], v[150:153], v[166:169], v[106:109]
	v_mfma_f32_16x16x32_bf16 v[94:97], v[140:143], v[200:203], v[94:97]
	v_mfma_f32_16x16x32_bf16 v[90:93], v[150:153], v[200:203], v[90:93]
	v_mfma_f32_16x16x32_bf16 v[78:81], v[140:143], v[208:211], v[78:81]
	v_mfma_f32_16x16x32_bf16 v[74:77], v[150:153], v[208:211], v[74:77]
	v_mfma_f32_16x16x32_bf16 v[126:129], v[146:149], v[162:165], v[126:129]
	v_mfma_f32_16x16x32_bf16 v[122:125], v[154:157], v[162:165], v[122:125]
	v_mfma_f32_16x16x32_bf16 v[110:113], v[146:149], v[170:173], v[110:113]
	v_mfma_f32_16x16x32_bf16 v[106:109], v[154:157], v[170:173], v[106:109]
	v_mfma_f32_16x16x32_bf16 v[94:97], v[146:149], v[204:207], v[94:97]
	v_mfma_f32_16x16x32_bf16 v[90:93], v[154:157], v[204:207], v[90:93]
	v_mfma_f32_16x16x32_bf16 v[78:81], v[146:149], v[212:215], v[78:81]
	v_mfma_f32_16x16x32_bf16 v[74:77], v[154:157], v[212:215], v[74:77]
	s_setprio 0
	s_barrier
	s_add_i32 s16, 0, 0x1c000
	s_add_i32 s10, s33, s20
	v_add_u32_e32 v228, s16, v131
	v_lshl_add_u64 v[174:175], v[174:175], 0, s[86:87]
	s_mov_b32 m0, s10
	ds_read_b128 v[216:219], v228
	ds_read_b128 v[220:223], v228 offset:1024
	ds_read_b128 v[224:227], v228 offset:2048
	ds_read_b128 v[228:231], v228 offset:3072
	global_load_lds_dwordx4 v[174:175], off
	v_lshl_add_u64 v[174:175], v[182:183], 0, s[86:87]
	s_add_i32 m0, s10, 0x2000
	s_nop 0
	global_load_lds_dwordx4 v[174:175], off
	s_setprio 1
	s_barrier
; #define PG8_STAGE(bufoff, gbase, voff) do { _Pragma("unroll") for (int _i = 0; _i < 2; ++_i) \
;     __builtin_amdgcn_global_load_lds((const unsigned*)((const char*)(gbase) + (voff)[_i]), (PG8_LAS unsigned*)(lds + (bufoff) + ldsw + _i * 8192), 16, 0, 0); } while (0)
; #define PG8_LDA(dst, b, h) do { _Pragma("unroll") for (int m = 0; m < 4; ++m) _Pragma("unroll") for (int k = 0; k < 2; ++k) dst[m][k] = *(const PG8_LAS bf16x8*)(lds + PG8_SA(b, h) + aoff + m * 2048 + k * 1024); } while (0)
; #define PG8_MMA(ai, bj, At, Bt) do { __builtin_amdgcn_s_setprio(1); _Pragma("unroll") for (int m = 0; m < 4; ++m) _Pragma("unroll") for (int n = 0; n < 2; ++n) _Pragma("unroll") for (int k = 0; k < 2; ++k) \
;     acc[ai][bj][m][n] = __builtin_amdgcn_mfma_f32_16x16x32_bf16(Bt[n][k], At[m][k], acc[ai][bj][m][n], 0, 0, 0); __builtin_amdgcn_s_setprio(0); } while (0)
; #define PG8_WAIT_V(n) asm volatile("s_waitcnt vmcnt(" #n ")" ::: "memory")
; #define PG8_WAIT_L(n) asm volatile("s_waitcnt lgkmcnt(" #n ")" ::: "memory")
; #define PG8_BAR __builtin_amdgcn_s_barrier()
; #define PG8_SCHED __builtin_amdgcn_sched_barrier(0)
; template <class Epi, class Sched>
; __device__ __forceinline__ void gemm_phase(PG8_LAS unsigned char* lds, const int lda, const int ldb, const Sched& S, const Epi& E) {
;     ...
;       PG8_BAR; PG8_WAIT_L(0); PG8_MMA(0, 1, At, B1); PG8_BAR;
;       PG8_LDA(At, 1, 1); PG8_STAGE(PG8_SA(1, 0), a3, voffA);
;       PG8_BAR; PG8_WAIT_L(0); PG8_MMA(1, 0, At, B0); PG8_BAR; PG8_SCHED;
;       PG8_STAGE(PG8_SB(1, 1), b3 + hstepB, voffB);
;       PG8_WAIT_V(6); PG8_BAR; PG8_MMA(1, 1, At, B1); PG8_BAR;
;     }
;   __device__ __forceinline__ void operator()(const f32x4 (&acc)[2][2][4][2], const Unit& u, int wr, int wc, int fr, int fq) const {
;     const int mr = (u.pm * 256 < ML) ? ((u.pm * 256) >> 11) : 32;
;     const float* gp = mod + (size_t)mr * 6144 + gate_off;
	s_waitcnt lgkmcnt(0)
	v_mfma_f32_16x16x32_bf16 v[118:121], v[216:219], v[158:161], v[118:121]
	v_mfma_f32_16x16x32_bf16 v[114:117], v[224:227], v[158:161], v[114:117]
	v_mfma_f32_16x16x32_bf16 v[102:105], v[216:219], v[166:169], v[102:105]
	v_mfma_f32_16x16x32_bf16 v[98:101], v[224:227], v[166:169], v[98:101]
	v_mfma_f32_16x16x32_bf16 v[86:89], v[216:219], v[200:203], v[86:89]
	v_mfma_f32_16x16x32_bf16 v[82:85], v[224:227], v[200:203], v[82:85]
	v_mfma_f32_16x16x32_bf16 v[70:73], v[216:219], v[208:211], v[70:73]
	v_mfma_f32_16x16x32_bf16 v[66:69], v[224:227], v[208:211], v[66:69]
	v_mfma_f32_16x16x32_bf16 v[118:121], v[220:223], v[162:165], v[118:121]
	v_mfma_f32_16x16x32_bf16 v[114:117], v[228:231], v[162:165], v[114:117]
	v_mfma_f32_16x16x32_bf16 v[102:105], v[220:223], v[170:173], v[102:105]
	v_mfma_f32_16x16x32_bf16 v[98:101], v[228:231], v[170:173], v[98:101]
	v_mfma_f32_16x16x32_bf16 v[86:89], v[220:223], v[204:207], v[86:89]
	v_mfma_f32_16x16x32_bf16 v[82:85], v[228:231], v[204:207], v[82:85]
	v_mfma_f32_16x16x32_bf16 v[70:73], v[220:223], v[212:215], v[70:73]
	v_mfma_f32_16x16x32_bf16 v[66:69], v[228:231], v[212:215], v[66:69]
	s_setprio 0
	s_mov_b32 m0, s28
	v_lshl_add_u64 v[174:175], v[184:185], 0, s[86:87]
	s_barrier
	ds_read_b128 v[158:161], v145 offset:49152
	ds_read_b128 v[162:165], v145 offset:50176
	ds_read_b128 v[166:169], v145 offset:51200
	ds_read_b128 v[170:173], v145 offset:52224
	ds_read_b128 v[200:203], v145 offset:53248
	ds_read_b128 v[204:207], v145 offset:54272
	ds_read_b128 v[208:211], v145 offset:55296
	ds_read_b128 v[212:215], v145 offset:56320
	global_load_lds_dwordx4 v[174:175], off
	v_lshl_add_u64 v[174:175], v[232:233], 0, s[86:87]
	s_mov_b32 m0, s29
	s_nop 0
	global_load_lds_dwordx4 v[174:175], off
	s_setprio 1
	s_barrier
	s_waitcnt lgkmcnt(0)
	v_mfma_f32_16x16x32_bf16 v[62:65], v[140:143], v[158:161], v[62:65]
	v_mfma_f32_16x16x32_bf16 v[58:61], v[150:153], v[158:161], v[58:61]
	v_mfma_f32_16x16x32_bf16 v[46:49], v[140:143], v[166:169], v[46:49]
	v_mfma_f32_16x16x32_bf16 v[42:45], v[150:153], v[166:169], v[42:45]
	v_mfma_f32_16x16x32_bf16 v[30:33], v[140:143], v[200:203], v[30:33]
	v_mfma_f32_16x16x32_bf16 v[26:29], v[150:153], v[200:203], v[26:29]
	v_mfma_f32_16x16x32_bf16 v[14:17], v[140:143], v[208:211], v[14:17]
	v_mfma_f32_16x16x32_bf16 v[10:13], v[150:153], v[208:211], v[10:13]
	v_mfma_f32_16x16x32_bf16 v[62:65], v[146:149], v[162:165], v[62:65]
	v_mfma_f32_16x16x32_bf16 v[58:61], v[154:157], v[162:165], v[58:61]
	v_mfma_f32_16x16x32_bf16 v[46:49], v[146:149], v[170:173], v[46:49]
	v_mfma_f32_16x16x32_bf16 v[42:45], v[154:157], v[170:173], v[42:45]
	v_mfma_f32_16x16x32_bf16 v[30:33], v[146:149], v[204:207], v[30:33]
	v_mfma_f32_16x16x32_bf16 v[26:29], v[154:157], v[204:207], v[26:29]
	v_mfma_f32_16x16x32_bf16 v[14:17], v[146:149], v[212:215], v[14:17]
	v_mfma_f32_16x16x32_bf16 v[10:13], v[154:157], v[212:215], v[10:13]
	s_setprio 0
	s_barrier
	s_add_u32 s10, s14, 0xb0080
	s_addc_u32 s11, s15, 0
	s_add_i32 s14, s16, s20
	v_lshl_add_u64 v[140:141], s[10:11], 0, v[134:135]
	s_mov_b32 m0, s14
	s_nop 0
	global_load_lds_dwordx4 v[140:141], off
	v_lshl_add_u64 v[140:141], s[10:11], 0, v[132:133]
	s_add_i32 m0, s14, 0x2000
	s_nop 0
	global_load_lds_dwordx4 v[140:141], off
	s_waitcnt vmcnt(6)
	s_setprio 1
	s_barrier
	v_mfma_f32_16x16x32_bf16 v[54:57], v[216:219], v[158:161], v[54:57]
	v_mfma_f32_16x16x32_bf16 v[50:53], v[224:227], v[158:161], v[50:53]
	v_mfma_f32_16x16x32_bf16 v[38:41], v[216:219], v[166:169], v[38:41]
	v_mfma_f32_16x16x32_bf16 v[34:37], v[224:227], v[166:169], v[34:37]
	v_mfma_f32_16x16x32_bf16 v[22:25], v[216:219], v[200:203], v[22:25]
	v_mfma_f32_16x16x32_bf16 v[18:21], v[224:227], v[200:203], v[18:21]
	v_mfma_f32_16x16x32_bf16 v[6:9], v[216:219], v[208:211], v[6:9]
	v_mfma_f32_16x16x32_bf16 v[2:5], v[224:227], v[208:211], v[2:5]
	v_mfma_f32_16x16x32_bf16 v[54:57], v[220:223], v[162:165], v[54:57]
	v_mfma_f32_16x16x32_bf16 v[50:53], v[228:231], v[162:165], v[50:53]
	v_mfma_f32_16x16x32_bf16 v[38:41], v[220:223], v[170:173], v[38:41]
	v_mfma_f32_16x16x32_bf16 v[34:37], v[228:231], v[170:173], v[34:37]
	v_mfma_f32_16x16x32_bf16 v[22:25], v[220:223], v[204:207], v[22:25]
	v_mfma_f32_16x16x32_bf16 v[18:21], v[228:231], v[204:207], v[18:21]
	v_mfma_f32_16x16x32_bf16 v[6:9], v[220:223], v[212:215], v[6:9]
	v_mfma_f32_16x16x32_bf16 v[2:5], v[228:231], v[212:215], v[2:5]
	s_setprio 0
	s_add_i32 s41, s41, 2
	s_add_u32 s39, s39, 0x100
	s_addc_u32 s40, s40, 0
	s_cmp_gt_u32 s41, 41
	s_mov_b64 s[10:11], s[12:13]
	s_barrier
	s_cbranch_scc0 .LBB0_1673
	s_cmpk_gt_i32 s37, 0xff
	s_mov_b64 s[10:11], 0x30000
	s_cbranch_scc1 .LBB0_1665
	s_ashr_i32 s10, s37, 3
	s_mul_hi_i32 s11, s10, 0x1800
	s_mulk_i32 s10, 0x1800
	s_branch .LBB0_1665
